# one static s_setprio 1 for waves 4-7 at kernel start, all per-MMA-block priority flips deleted
# baseline (speedup 1.0000x reference)
_Z6mk_fwd4Args:
	s_mov_b32 s10, s2
	s_load_dword s2, s[0:1], 0xf8
	s_load_dwordx8 s[84:91], s[0:1], 0xc0
	s_load_dwordx4 s[92:95], s[0:1], 0xe0
	s_load_dwordx2 s[80:81], s[0:1], 0xf0
	s_add_u32 s4, s0, 0xf0
	v_and_b32_e32 v174, 0x3ff, v0
	s_waitcnt lgkmcnt(0)
	v_writelane_b32 v243, s2, 0
	s_addc_u32 s5, s1, 0
	v_readfirstlane_b32 s2, v174
	v_cmp_gt_u32_e32 vcc, 2, v174
	s_nop 0
	v_writelane_b32 v243, s2, 1
	s_cmpk_lt_u32 s2, 0x100
	s_cbranch_scc1 .Lprio_done
	s_setprio 1
.Lprio_done:
	s_and_saveexec_b64 s[2:3], vcc
	v_lshl_add_u32 v1, v174, 2, 0
	v_add_u32_e32 v1, 0x23fc0, v1
	v_mov_b32_e32 v2, 0
	ds_write_b32 v1, v2
	s_or_b64 exec, exec, s[2:3]
	s_add_u32 s2, s92, 0xc0000
	s_addc_u32 s3, s93, 0
	v_writelane_b32 v243, s2, 3
	v_cmp_eq_u32_e32 vcc, 0, v174
	s_waitcnt lgkmcnt(0)
	v_writelane_b32 v243, s3, 4
	s_sub_i32 s2, s95, s94
	s_mov_b32 s3, 0
	s_cmp_lt_i32 s2, 2
	s_barrier
	v_writelane_b32 v243, s3, 5
	s_cbranch_scc1 .LBB0_7
	s_getreg_b32 s2, hwreg(HW_REG_XCC_ID, 0, 4)
	s_and_b32 s2, s2, 15
	v_writelane_b32 v243, s2, 5
	s_and_saveexec_b64 s[2:3], vcc
	s_cbranch_execz .LBB0_6
	s_mov_b64 s[6:7], exec
	v_mbcnt_lo_u32_b32 v1, s6, 0
	v_mbcnt_hi_u32_b32 v1, s7, v1
	v_cmp_eq_u32_e32 vcc, 0, v1
	s_and_b64 s[8:9], exec, vcc
	s_mov_b64 exec, s[8:9]
	s_cbranch_execz .LBB0_6
	v_readlane_b32 s8, v243, 5
	s_bcnt1_i32_b64 s6, s[6:7]
	s_lshl_b32 s8, s8, 8
	v_mov_b32_e32 v2, s6
	v_readlane_b32 s6, v243, 3
	v_mov_b32_e32 v1, s8
	v_readlane_b32 s7, v243, 4
	s_nop 4
	global_atomic_add v1, v2, s[6:7] offset:1024

.LBB0_319:
	ds_read_b128 v[64:67], v206
	ds_read_b128 v[68:71], v206 offset:1024
	ds_read_b128 v[136:139], v206 offset:2048
	ds_read_b128 v[140:143], v206 offset:3072
	ds_read_b128 v[162:165], v207
	ds_read_b128 v[166:169], v207 offset:1024
	ds_read_b128 v[176:179], v207 offset:2048
	ds_read_b128 v[200:203], v207 offset:3072
	s_add_u32 s26, s0, 0xfff80080
	s_addc_u32 s27, s1, -1
	s_cmp_eq_u32 vcc_hi, 28
	s_cselect_b32 s29, s19, s27
	s_cselect_b32 s28, s81, s26
	s_cselect_b32 s27, s17, vcc_lo
	s_cselect_b32 s26, s82, s83
	v_lshl_add_u64 v[170:171], s[0:1], 0, v[152:153]
	s_add_i32 m0, s25, 0xc000
	ds_read_b128 v[210:213], v208
	ds_read_b128 v[214:217], v208 offset:1024
	ds_read_b128 v[218:221], v208 offset:2048
	ds_read_b128 v[222:225], v208 offset:3072
	ds_read_b128 v[226:229], v208 offset:4096
	ds_read_b128 v[230:233], v208 offset:5120
	ds_read_b128 v[234:237], v208 offset:6144
	ds_read_b128 v[238:241], v208 offset:7168
	global_load_lds_dwordx4 v[170:171], off
	v_lshl_add_u64 v[170:171], s[0:1], 0, v[154:155]
	s_add_i32 m0, s25, 0xe000
	s_nop 0
	global_load_lds_dwordx4 v[170:171], off
	s_waitcnt vmcnt(8)
	s_waitcnt lgkmcnt(0)
	s_barrier
	s_waitcnt lgkmcnt(0)
	v_mfma_f32_16x16x32_bf16 v[132:135], v[64:67], v[210:213], v[132:135]
	v_mfma_f32_16x16x32_bf16 v[124:127], v[136:139], v[210:213], v[124:127]
	v_mfma_f32_16x16x32_bf16 v[116:119], v[64:67], v[218:221], v[116:119]
	v_mfma_f32_16x16x32_bf16 v[112:115], v[136:139], v[218:221], v[112:115]
	v_mfma_f32_16x16x32_bf16 v[100:103], v[64:67], v[226:229], v[100:103]
	v_mfma_f32_16x16x32_bf16 v[96:99], v[136:139], v[226:229], v[96:99]
	v_mfma_f32_16x16x32_bf16 v[84:87], v[64:67], v[234:237], v[84:87]
	v_mfma_f32_16x16x32_bf16 v[80:83], v[136:139], v[234:237], v[80:83]
	v_mfma_f32_16x16x32_bf16 v[132:135], v[68:71], v[214:217], v[132:135]
	v_mfma_f32_16x16x32_bf16 v[124:127], v[140:143], v[214:217], v[124:127]
	v_mfma_f32_16x16x32_bf16 v[116:119], v[68:71], v[222:225], v[116:119]
	v_mfma_f32_16x16x32_bf16 v[112:115], v[140:143], v[222:225], v[112:115]
	v_mfma_f32_16x16x32_bf16 v[100:103], v[68:71], v[230:233], v[100:103]
	v_mfma_f32_16x16x32_bf16 v[96:99], v[140:143], v[230:233], v[96:99]
	v_mfma_f32_16x16x32_bf16 v[84:87], v[68:71], v[238:241], v[84:87]
	v_mfma_f32_16x16x32_bf16 v[80:83], v[140:143], v[238:241], v[80:83]
	v_mfma_f32_16x16x32_bf16 v[128:131], v[162:165], v[210:213], v[128:131]
	v_mfma_f32_16x16x32_bf16 v[120:123], v[176:179], v[210:213], v[120:123]
	v_mfma_f32_16x16x32_bf16 v[108:111], v[162:165], v[218:221], v[108:111]
	v_mfma_f32_16x16x32_bf16 v[104:107], v[176:179], v[218:221], v[104:107]
	v_mfma_f32_16x16x32_bf16 v[92:95], v[162:165], v[226:229], v[92:95]
	v_mfma_f32_16x16x32_bf16 v[88:91], v[176:179], v[226:229], v[88:91]
	v_mfma_f32_16x16x32_bf16 v[76:79], v[162:165], v[234:237], v[76:79]
	v_mfma_f32_16x16x32_bf16 v[72:75], v[176:179], v[234:237], v[72:75]
	v_mfma_f32_16x16x32_bf16 v[128:131], v[166:169], v[214:217], v[128:131]
	v_mfma_f32_16x16x32_bf16 v[120:123], v[200:203], v[214:217], v[120:123]
	v_mfma_f32_16x16x32_bf16 v[108:111], v[166:169], v[222:225], v[108:111]
	v_mfma_f32_16x16x32_bf16 v[104:107], v[200:203], v[222:225], v[104:107]
	v_mfma_f32_16x16x32_bf16 v[92:95], v[166:169], v[230:233], v[92:95]
	v_mfma_f32_16x16x32_bf16 v[88:91], v[200:203], v[230:233], v[88:91]
	v_mfma_f32_16x16x32_bf16 v[76:79], v[166:169], v[238:241], v[76:79]
	v_mfma_f32_16x16x32_bf16 v[72:75], v[200:203], v[238:241], v[72:75]
	s_barrier
	s_add_i32 s33, s74, s30
	v_lshl_add_u64 v[170:171], s[26:27], 0, v[148:149]
	s_mov_b32 m0, s33
	ds_read_b128 v[210:213], v208 offset:16384
	ds_read_b128 v[214:217], v208 offset:17408
	ds_read_b128 v[218:221], v208 offset:18432
	ds_read_b128 v[222:225], v208 offset:19456
	ds_read_b128 v[226:229], v208 offset:20480
	ds_read_b128 v[230:233], v208 offset:21504
	ds_read_b128 v[234:237], v208 offset:22528
	ds_read_b128 v[238:241], v208 offset:23552
	global_load_lds_dwordx4 v[170:171], off
	s_add_i32 m0, s33, 0x2000
	s_add_u32 s56, s26, 0x80000
	v_lshl_add_u64 v[180:181], s[26:27], 0, v[144:145]
	s_addc_u32 s57, s27, 0
	s_add_i32 s33, s75, s30
	global_load_lds_dwordx4 v[180:181], off
	v_lshl_add_u64 v[186:187], s[56:57], 0, v[148:149]
	s_mov_b32 m0, s33
	v_lshl_add_u64 v[194:195], s[28:29], 0, v[146:147]
	global_load_lds_dwordx4 v[186:187], off
	v_lshl_add_u64 v[186:187], s[56:57], 0, v[144:145]
	s_add_i32 m0, s33, 0x2000
	s_nop 0
	global_load_lds_dwordx4 v[186:187], off
	v_lshl_add_u64 v[186:187], s[28:29], 0, v[150:151]
	s_mov_b32 m0, s25
	s_nop 0
	global_load_lds_dwordx4 v[186:187], off
	s_mov_b32 m0, s52
	s_nop 0
	global_load_lds_dwordx4 v[194:195], off
	s_waitcnt vmcnt(8)
	s_waitcnt lgkmcnt(0)
	s_barrier
	s_waitcnt lgkmcnt(0)
	v_mfma_f32_16x16x32_bf16 v[60:63], v[64:67], v[210:213], v[60:63]
	v_mfma_f32_16x16x32_bf16 v[56:59], v[136:139], v[210:213], v[56:59]
	v_mfma_f32_16x16x32_bf16 v[44:47], v[64:67], v[218:221], v[44:47]
	v_mfma_f32_16x16x32_bf16 v[40:43], v[136:139], v[218:221], v[40:43]
	v_mfma_f32_16x16x32_bf16 v[28:31], v[64:67], v[226:229], v[28:31]
	v_mfma_f32_16x16x32_bf16 v[24:27], v[136:139], v[226:229], v[24:27]
	v_mfma_f32_16x16x32_bf16 v[12:15], v[64:67], v[234:237], v[12:15]
	v_mfma_f32_16x16x32_bf16 v[8:11], v[136:139], v[234:237], v[8:11]
	v_mfma_f32_16x16x32_bf16 v[60:63], v[68:71], v[214:217], v[60:63]
	v_mfma_f32_16x16x32_bf16 v[56:59], v[140:143], v[214:217], v[56:59]
	v_mfma_f32_16x16x32_bf16 v[44:47], v[68:71], v[222:225], v[44:47]
	v_mfma_f32_16x16x32_bf16 v[40:43], v[140:143], v[222:225], v[40:43]
	v_mfma_f32_16x16x32_bf16 v[28:31], v[68:71], v[230:233], v[28:31]
	v_mfma_f32_16x16x32_bf16 v[24:27], v[140:143], v[230:233], v[24:27]
	v_mfma_f32_16x16x32_bf16 v[12:15], v[68:71], v[238:241], v[12:15]
	v_mfma_f32_16x16x32_bf16 v[8:11], v[140:143], v[238:241], v[8:11]
	v_mfma_f32_16x16x32_bf16 v[52:55], v[162:165], v[210:213], v[52:55]
	v_mfma_f32_16x16x32_bf16 v[48:51], v[176:179], v[210:213], v[48:51]
	v_mfma_f32_16x16x32_bf16 v[36:39], v[162:165], v[218:221], v[36:39]
	v_mfma_f32_16x16x32_bf16 v[32:35], v[176:179], v[218:221], v[32:35]
	v_mfma_f32_16x16x32_bf16 v[20:23], v[162:165], v[226:229], v[20:23]
	v_mfma_f32_16x16x32_bf16 v[16:19], v[176:179], v[226:229], v[16:19]
	v_mfma_f32_16x16x32_bf16 v[4:7], v[162:165], v[234:237], v[4:7]
	v_mfma_f32_16x16x32_bf16 v[0:3], v[176:179], v[234:237], v[0:3]
	v_mfma_f32_16x16x32_bf16 v[52:55], v[166:169], v[214:217], v[52:55]
	v_mfma_f32_16x16x32_bf16 v[48:51], v[200:203], v[214:217], v[48:51]
	v_mfma_f32_16x16x32_bf16 v[36:39], v[166:169], v[222:225], v[36:39]
	v_mfma_f32_16x16x32_bf16 v[32:35], v[200:203], v[222:225], v[32:35]
	v_mfma_f32_16x16x32_bf16 v[20:23], v[166:169], v[230:233], v[20:23]
	v_mfma_f32_16x16x32_bf16 v[16:19], v[200:203], v[230:233], v[16:19]
	v_mfma_f32_16x16x32_bf16 v[4:7], v[166:169], v[238:241], v[4:7]
	v_mfma_f32_16x16x32_bf16 v[0:3], v[200:203], v[238:241], v[0:3]
	s_barrier
	s_add_i32 s33, 0, 0x18000
	s_add_i32 s34, 0, 0x1c000
	v_add_u32_e32 v140, s33, v189
	v_add_u32_e32 v161, s34, v189
	ds_read_b128 v[64:67], v140
	ds_read_b128 v[68:71], v140 offset:1024
	ds_read_b128 v[136:139], v140 offset:2048
	ds_read_b128 v[140:143], v140 offset:3072
	ds_read_b128 v[162:165], v161
	ds_read_b128 v[166:169], v161 offset:1024
	ds_read_b128 v[176:179], v161 offset:2048
	ds_read_b128 v[200:203], v161 offset:3072
	s_add_u32 s28, s28, 0x80000
	s_addc_u32 s29, s29, 0
	s_mov_b32 m0, s53
	v_lshl_add_u64 v[204:205], s[28:29], 0, v[150:151]
	ds_read_b128 v[210:213], v208 offset:32768
	ds_read_b128 v[214:217], v208 offset:33792
	ds_read_b128 v[218:221], v208 offset:34816
	ds_read_b128 v[222:225], v208 offset:35840
	ds_read_b128 v[226:229], v208 offset:36864
	ds_read_b128 v[230:233], v208 offset:37888
	ds_read_b128 v[234:237], v208 offset:38912
	ds_read_b128 v[238:241], v208 offset:39936
	global_load_lds_dwordx4 v[204:205], off
	v_lshl_add_u64 v[204:205], s[28:29], 0, v[146:147]
	s_mov_b32 m0, s54
	s_nop 0
	global_load_lds_dwordx4 v[204:205], off
	s_waitcnt vmcnt(8)
	s_waitcnt lgkmcnt(0)
	s_barrier
	s_waitcnt lgkmcnt(0)
	v_mfma_f32_16x16x32_bf16 v[132:135], v[64:67], v[210:213], v[132:135]
	v_mfma_f32_16x16x32_bf16 v[124:127], v[136:139], v[210:213], v[124:127]
	v_mfma_f32_16x16x32_bf16 v[116:119], v[64:67], v[218:221], v[116:119]
	v_mfma_f32_16x16x32_bf16 v[112:115], v[136:139], v[218:221], v[112:115]
	v_mfma_f32_16x16x32_bf16 v[100:103], v[64:67], v[226:229], v[100:103]
	v_mfma_f32_16x16x32_bf16 v[96:99], v[136:139], v[226:229], v[96:99]
	v_mfma_f32_16x16x32_bf16 v[84:87], v[64:67], v[234:237], v[84:87]
	v_mfma_f32_16x16x32_bf16 v[80:83], v[136:139], v[234:237], v[80:83]
	v_mfma_f32_16x16x32_bf16 v[132:135], v[68:71], v[214:217], v[132:135]
	v_mfma_f32_16x16x32_bf16 v[124:127], v[140:143], v[214:217], v[124:127]
	v_mfma_f32_16x16x32_bf16 v[116:119], v[68:71], v[222:225], v[116:119]
	v_mfma_f32_16x16x32_bf16 v[112:115], v[140:143], v[222:225], v[112:115]
	v_mfma_f32_16x16x32_bf16 v[100:103], v[68:71], v[230:233], v[100:103]
	v_mfma_f32_16x16x32_bf16 v[96:99], v[140:143], v[230:233], v[96:99]
	v_mfma_f32_16x16x32_bf16 v[84:87], v[68:71], v[238:241], v[84:87]
	v_mfma_f32_16x16x32_bf16 v[80:83], v[140:143], v[238:241], v[80:83]
	v_mfma_f32_16x16x32_bf16 v[128:131], v[162:165], v[210:213], v[128:131]
	v_mfma_f32_16x16x32_bf16 v[120:123], v[176:179], v[210:213], v[120:123]
	v_mfma_f32_16x16x32_bf16 v[108:111], v[162:165], v[218:221], v[108:111]
	v_mfma_f32_16x16x32_bf16 v[104:107], v[176:179], v[218:221], v[104:107]
	v_mfma_f32_16x16x32_bf16 v[92:95], v[162:165], v[226:229], v[92:95]
	v_mfma_f32_16x16x32_bf16 v[88:91], v[176:179], v[226:229], v[88:91]
	v_mfma_f32_16x16x32_bf16 v[76:79], v[162:165], v[234:237], v[76:79]
	v_mfma_f32_16x16x32_bf16 v[72:75], v[176:179], v[234:237], v[72:75]
	v_mfma_f32_16x16x32_bf16 v[128:131], v[166:169], v[214:217], v[128:131]
	v_mfma_f32_16x16x32_bf16 v[120:123], v[200:203], v[214:217], v[120:123]
	v_mfma_f32_16x16x32_bf16 v[108:111], v[166:169], v[222:225], v[108:111]
	v_mfma_f32_16x16x32_bf16 v[104:107], v[200:203], v[222:225], v[104:107]
	v_mfma_f32_16x16x32_bf16 v[92:95], v[166:169], v[230:233], v[92:95]
	v_mfma_f32_16x16x32_bf16 v[88:91], v[200:203], v[230:233], v[88:91]
	v_mfma_f32_16x16x32_bf16 v[76:79], v[166:169], v[238:241], v[76:79]
	v_mfma_f32_16x16x32_bf16 v[72:75], v[200:203], v[238:241], v[72:75]
	s_barrier
	s_add_i32 s28, s33, s30
	v_lshl_add_u64 v[170:171], v[170:171], 0, s[8:9]
	s_mov_b32 m0, s28
	ds_read_b128 v[210:213], v208 offset:49152
	ds_read_b128 v[214:217], v208 offset:50176
	ds_read_b128 v[218:221], v208 offset:51200
	ds_read_b128 v[222:225], v208 offset:52224
	ds_read_b128 v[226:229], v208 offset:53248
	ds_read_b128 v[230:233], v208 offset:54272
	ds_read_b128 v[234:237], v208 offset:55296
	ds_read_b128 v[238:241], v208 offset:56320
	global_load_lds_dwordx4 v[170:171], off
	s_add_i32 m0, s28, 0x2000
	s_add_u32 s26, s26, 0x80080
	v_lshl_add_u64 v[170:171], v[180:181], 0, s[8:9]
	s_addc_u32 s27, s27, 0
	s_add_i32 s28, s34, s30
	global_load_lds_dwordx4 v[170:171], off
	v_lshl_add_u64 v[170:171], s[26:27], 0, v[148:149]
	s_mov_b32 m0, s28
	s_nop 0
	global_load_lds_dwordx4 v[170:171], off
	v_lshl_add_u64 v[170:171], s[26:27], 0, v[144:145]
	s_add_i32 m0, s28, 0x2000
	s_nop 0
	global_load_lds_dwordx4 v[170:171], off
	v_lshl_add_u64 v[170:171], v[186:187], 0, s[8:9]
	s_mov_b32 m0, s69
	s_nop 0
	global_load_lds_dwordx4 v[170:171], off
	v_lshl_add_u64 v[170:171], v[194:195], 0, s[8:9]
	s_mov_b32 m0, s70
	s_nop 0
	global_load_lds_dwordx4 v[170:171], off
	s_waitcnt vmcnt(8)
	s_waitcnt lgkmcnt(0)
	s_barrier
	s_waitcnt lgkmcnt(0)
	v_mfma_f32_16x16x32_bf16 v[60:63], v[64:67], v[210:213], v[60:63]
	v_mfma_f32_16x16x32_bf16 v[56:59], v[136:139], v[210:213], v[56:59]
	v_mfma_f32_16x16x32_bf16 v[44:47], v[64:67], v[218:221], v[44:47]
	v_mfma_f32_16x16x32_bf16 v[40:43], v[136:139], v[218:221], v[40:43]
	v_mfma_f32_16x16x32_bf16 v[28:31], v[64:67], v[226:229], v[28:31]
	v_mfma_f32_16x16x32_bf16 v[24:27], v[136:139], v[226:229], v[24:27]
	v_mfma_f32_16x16x32_bf16 v[12:15], v[64:67], v[234:237], v[12:15]
	v_mfma_f32_16x16x32_bf16 v[8:11], v[136:139], v[234:237], v[8:11]
	v_mfma_f32_16x16x32_bf16 v[60:63], v[68:71], v[214:217], v[60:63]
	v_mfma_f32_16x16x32_bf16 v[56:59], v[140:143], v[214:217], v[56:59]
	v_mfma_f32_16x16x32_bf16 v[44:47], v[68:71], v[222:225], v[44:47]
	v_mfma_f32_16x16x32_bf16 v[40:43], v[140:143], v[222:225], v[40:43]
	v_mfma_f32_16x16x32_bf16 v[28:31], v[68:71], v[230:233], v[28:31]
	v_mfma_f32_16x16x32_bf16 v[24:27], v[140:143], v[230:233], v[24:27]
	v_mfma_f32_16x16x32_bf16 v[12:15], v[68:71], v[238:241], v[12:15]
	v_mfma_f32_16x16x32_bf16 v[8:11], v[140:143], v[238:241], v[8:11]
	v_mfma_f32_16x16x32_bf16 v[52:55], v[162:165], v[210:213], v[52:55]
	v_mfma_f32_16x16x32_bf16 v[48:51], v[176:179], v[210:213], v[48:51]
	v_mfma_f32_16x16x32_bf16 v[36:39], v[162:165], v[218:221], v[36:39]
	v_mfma_f32_16x16x32_bf16 v[32:35], v[176:179], v[218:221], v[32:35]
	v_mfma_f32_16x16x32_bf16 v[20:23], v[162:165], v[226:229], v[20:23]
	v_mfma_f32_16x16x32_bf16 v[16:19], v[176:179], v[226:229], v[16:19]
	v_mfma_f32_16x16x32_bf16 v[4:7], v[162:165], v[234:237], v[4:7]
	v_mfma_f32_16x16x32_bf16 v[0:3], v[176:179], v[234:237], v[0:3]
	v_mfma_f32_16x16x32_bf16 v[52:55], v[166:169], v[214:217], v[52:55]
	v_mfma_f32_16x16x32_bf16 v[48:51], v[200:203], v[214:217], v[48:51]
	v_mfma_f32_16x16x32_bf16 v[36:39], v[166:169], v[222:225], v[36:39]
	v_mfma_f32_16x16x32_bf16 v[32:35], v[200:203], v[222:225], v[32:35]
	v_mfma_f32_16x16x32_bf16 v[20:23], v[166:169], v[230:233], v[20:23]
	v_mfma_f32_16x16x32_bf16 v[16:19], v[200:203], v[230:233], v[16:19]
	v_mfma_f32_16x16x32_bf16 v[4:7], v[166:169], v[238:241], v[4:7]
	v_mfma_f32_16x16x32_bf16 v[0:3], v[200:203], v[238:241], v[0:3]
	s_barrier
	s_add_i32 vcc_hi, vcc_hi, 2
	s_add_u32 s0, s0, 0x100
	s_addc_u32 s1, s1, 0
	s_add_u32 s83, s83, 0x100
	s_addc_u32 vcc_lo, vcc_lo, 0
	s_cmp_gt_u32 vcc_hi, 29
	s_cbranch_scc0 .LBB0_319
	s_and_b64 vcc, exec, s[10:11]
	s_cbranch_vccz .LBB0_322
	s_barrier

.LBB0_440:
	ds_read_b128 v[72:75], v189
	ds_read_b128 v[76:79], v189 offset:1024
	ds_read_b128 v[88:91], v189 offset:2048
	ds_read_b128 v[92:95], v189 offset:3072
	ds_read_b128 v[160:163], v190
	ds_read_b128 v[164:167], v190 offset:1024
	ds_read_b128 v[168:171], v190 offset:2048
	ds_read_b128 v[176:179], v190 offset:3072
	s_add_u32 s20, s2, 0xffea0080
	s_addc_u32 s21, s3, -1
	s_cmpk_eq_i32 s74, 0x54
	s_cselect_b32 s23, s17, s21
	s_cselect_b32 s22, s16, s20
	s_cselect_b32 s21, s19, s73
	s_cselect_b32 s20, s18, s72
	v_lshl_add_u64 v[220:221], s[2:3], 0, v[152:153]
	s_add_i32 m0, s25, 0xc000
	ds_read_b128 v[180:183], v191
	ds_read_b128 v[184:187], v191 offset:1024
	ds_read_b128 v[194:197], v191 offset:2048
	ds_read_b128 v[200:203], v191 offset:3072
	ds_read_b128 v[204:207], v191 offset:4096
	ds_read_b128 v[208:211], v191 offset:5120
	ds_read_b128 v[212:215], v191 offset:6144
	ds_read_b128 v[216:219], v191 offset:7168
	global_load_lds_dwordx4 v[220:221], off
	v_lshl_add_u64 v[220:221], s[2:3], 0, v[154:155]
	s_add_i32 m0, s25, 0xe000
	s_nop 0
	global_load_lds_dwordx4 v[220:221], off
	s_waitcnt vmcnt(8)
	s_waitcnt lgkmcnt(0)
	s_barrier
	s_waitcnt lgkmcnt(0)
	v_mfma_f32_16x16x32_bf16 v[140:143], v[72:75], v[180:183], v[140:143]
	v_mfma_f32_16x16x32_bf16 v[136:139], v[88:91], v[180:183], v[136:139]
	v_mfma_f32_16x16x32_bf16 v[124:127], v[72:75], v[194:197], v[124:127]
	v_mfma_f32_16x16x32_bf16 v[120:123], v[88:91], v[194:197], v[120:123]
	v_mfma_f32_16x16x32_bf16 v[108:111], v[72:75], v[204:207], v[108:111]
	v_mfma_f32_16x16x32_bf16 v[104:107], v[88:91], v[204:207], v[104:107]
	v_mfma_f32_16x16x32_bf16 v[84:87], v[72:75], v[212:215], v[84:87]
	v_mfma_f32_16x16x32_bf16 v[80:83], v[88:91], v[212:215], v[80:83]
	v_mfma_f32_16x16x32_bf16 v[140:143], v[76:79], v[184:187], v[140:143]
	v_mfma_f32_16x16x32_bf16 v[136:139], v[92:95], v[184:187], v[136:139]
	v_mfma_f32_16x16x32_bf16 v[124:127], v[76:79], v[200:203], v[124:127]
	v_mfma_f32_16x16x32_bf16 v[120:123], v[92:95], v[200:203], v[120:123]
	v_mfma_f32_16x16x32_bf16 v[108:111], v[76:79], v[208:211], v[108:111]
	v_mfma_f32_16x16x32_bf16 v[104:107], v[92:95], v[208:211], v[104:107]
	v_mfma_f32_16x16x32_bf16 v[84:87], v[76:79], v[216:219], v[84:87]
	v_mfma_f32_16x16x32_bf16 v[80:83], v[92:95], v[216:219], v[80:83]
	v_mfma_f32_16x16x32_bf16 v[132:135], v[160:163], v[180:183], v[132:135]
	v_mfma_f32_16x16x32_bf16 v[128:131], v[168:171], v[180:183], v[128:131]
	v_mfma_f32_16x16x32_bf16 v[116:119], v[160:163], v[194:197], v[116:119]
	v_mfma_f32_16x16x32_bf16 v[112:115], v[168:171], v[194:197], v[112:115]
	v_mfma_f32_16x16x32_bf16 v[100:103], v[160:163], v[204:207], v[100:103]
	v_mfma_f32_16x16x32_bf16 v[96:99], v[168:171], v[204:207], v[96:99]
	v_mfma_f32_16x16x32_bf16 v[68:71], v[160:163], v[212:215], v[68:71]
	v_mfma_f32_16x16x32_bf16 v[64:67], v[168:171], v[212:215], v[64:67]
	v_mfma_f32_16x16x32_bf16 v[132:135], v[164:167], v[184:187], v[132:135]
	v_mfma_f32_16x16x32_bf16 v[128:131], v[176:179], v[184:187], v[128:131]
	v_mfma_f32_16x16x32_bf16 v[116:119], v[164:167], v[200:203], v[116:119]
	v_mfma_f32_16x16x32_bf16 v[112:115], v[176:179], v[200:203], v[112:115]
	v_mfma_f32_16x16x32_bf16 v[100:103], v[164:167], v[208:211], v[100:103]
	v_mfma_f32_16x16x32_bf16 v[96:99], v[176:179], v[208:211], v[96:99]
	v_mfma_f32_16x16x32_bf16 v[68:71], v[164:167], v[216:219], v[68:71]
	v_mfma_f32_16x16x32_bf16 v[64:67], v[176:179], v[216:219], v[64:67]
	s_barrier
	s_add_i32 s33, s60, s24
	v_lshl_add_u64 v[220:221], s[20:21], 0, v[146:147]
	s_mov_b32 m0, s33
	ds_read_b128 v[180:183], v191 offset:16384
	ds_read_b128 v[184:187], v191 offset:17408
	ds_read_b128 v[194:197], v191 offset:18432
	ds_read_b128 v[200:203], v191 offset:19456
	ds_read_b128 v[204:207], v191 offset:20480
	ds_read_b128 v[208:211], v191 offset:21504
	ds_read_b128 v[212:215], v191 offset:22528
	ds_read_b128 v[216:219], v191 offset:23552
	global_load_lds_dwordx4 v[220:221], off
	s_add_i32 m0, s33, 0x2000
	s_add_u32 s56, s20, 0x160000
	v_lshl_add_u64 v[222:223], s[20:21], 0, v[150:151]
	s_addc_u32 s57, s21, 0
	s_add_i32 s33, s61, s24
	global_load_lds_dwordx4 v[222:223], off
	v_lshl_add_u64 v[224:225], s[56:57], 0, v[146:147]
	s_mov_b32 m0, s33
	v_lshl_add_u64 v[226:227], s[22:23], 0, v[148:149]
	global_load_lds_dwordx4 v[224:225], off
	v_lshl_add_u64 v[224:225], s[56:57], 0, v[150:151]
	s_add_i32 m0, s33, 0x2000
	s_nop 0
	global_load_lds_dwordx4 v[224:225], off
	v_lshl_add_u64 v[224:225], s[22:23], 0, v[144:145]
	s_mov_b32 m0, s25
	s_nop 0
	global_load_lds_dwordx4 v[224:225], off
	s_mov_b32 m0, s26
	s_nop 0
	global_load_lds_dwordx4 v[226:227], off
	s_waitcnt vmcnt(8)
	s_waitcnt lgkmcnt(0)
	s_barrier
	s_waitcnt lgkmcnt(0)
	v_mfma_f32_16x16x32_bf16 v[60:63], v[72:75], v[180:183], v[60:63]
	v_mfma_f32_16x16x32_bf16 v[56:59], v[88:91], v[180:183], v[56:59]
	v_mfma_f32_16x16x32_bf16 v[44:47], v[72:75], v[194:197], v[44:47]
	v_mfma_f32_16x16x32_bf16 v[40:43], v[88:91], v[194:197], v[40:43]
	v_mfma_f32_16x16x32_bf16 v[28:31], v[72:75], v[204:207], v[28:31]
	v_mfma_f32_16x16x32_bf16 v[24:27], v[88:91], v[204:207], v[24:27]
	v_mfma_f32_16x16x32_bf16 v[12:15], v[72:75], v[212:215], v[12:15]
	v_mfma_f32_16x16x32_bf16 v[8:11], v[88:91], v[212:215], v[8:11]
	v_mfma_f32_16x16x32_bf16 v[60:63], v[76:79], v[184:187], v[60:63]
	v_mfma_f32_16x16x32_bf16 v[56:59], v[92:95], v[184:187], v[56:59]
	v_mfma_f32_16x16x32_bf16 v[44:47], v[76:79], v[200:203], v[44:47]
	v_mfma_f32_16x16x32_bf16 v[40:43], v[92:95], v[200:203], v[40:43]
	v_mfma_f32_16x16x32_bf16 v[28:31], v[76:79], v[208:211], v[28:31]
	v_mfma_f32_16x16x32_bf16 v[24:27], v[92:95], v[208:211], v[24:27]
	v_mfma_f32_16x16x32_bf16 v[12:15], v[76:79], v[216:219], v[12:15]
	v_mfma_f32_16x16x32_bf16 v[8:11], v[92:95], v[216:219], v[8:11]
	v_mfma_f32_16x16x32_bf16 v[52:55], v[160:163], v[180:183], v[52:55]
	v_mfma_f32_16x16x32_bf16 v[48:51], v[168:171], v[180:183], v[48:51]
	v_mfma_f32_16x16x32_bf16 v[36:39], v[160:163], v[194:197], v[36:39]
	v_mfma_f32_16x16x32_bf16 v[32:35], v[168:171], v[194:197], v[32:35]
	v_mfma_f32_16x16x32_bf16 v[20:23], v[160:163], v[204:207], v[20:23]
	v_mfma_f32_16x16x32_bf16 v[16:19], v[168:171], v[204:207], v[16:19]
	v_mfma_f32_16x16x32_bf16 v[4:7], v[160:163], v[212:215], v[4:7]
	v_mfma_f32_16x16x32_bf16 v[0:3], v[168:171], v[212:215], v[0:3]
	v_mfma_f32_16x16x32_bf16 v[52:55], v[164:167], v[184:187], v[52:55]
	v_mfma_f32_16x16x32_bf16 v[48:51], v[176:179], v[184:187], v[48:51]
	v_mfma_f32_16x16x32_bf16 v[36:39], v[164:167], v[200:203], v[36:39]
	v_mfma_f32_16x16x32_bf16 v[32:35], v[176:179], v[200:203], v[32:35]
	v_mfma_f32_16x16x32_bf16 v[20:23], v[164:167], v[208:211], v[20:23]
	v_mfma_f32_16x16x32_bf16 v[16:19], v[176:179], v[208:211], v[16:19]
	v_mfma_f32_16x16x32_bf16 v[4:7], v[164:167], v[216:219], v[4:7]
	v_mfma_f32_16x16x32_bf16 v[0:3], v[176:179], v[216:219], v[0:3]
	s_barrier
	s_add_i32 s33, 0, 0x18000
	s_add_i32 s34, 0, 0x1c000
	v_add_u32_e32 v92, s33, v188
	v_add_u32_e32 v176, s34, v188
	ds_read_b128 v[72:75], v92
	ds_read_b128 v[76:79], v92 offset:1024
	ds_read_b128 v[88:91], v92 offset:2048
	ds_read_b128 v[92:95], v92 offset:3072
	ds_read_b128 v[160:163], v176
	ds_read_b128 v[164:167], v176 offset:1024
	ds_read_b128 v[168:171], v176 offset:2048
	ds_read_b128 v[176:179], v176 offset:3072
	s_add_u32 s22, s22, 0x160000
	s_addc_u32 s23, s23, 0
	s_mov_b32 m0, s27
	v_lshl_add_u64 v[228:229], s[22:23], 0, v[144:145]
	ds_read_b128 v[180:183], v191 offset:32768
	ds_read_b128 v[184:187], v191 offset:33792
	ds_read_b128 v[194:197], v191 offset:34816
	ds_read_b128 v[200:203], v191 offset:35840
	ds_read_b128 v[204:207], v191 offset:36864
	ds_read_b128 v[208:211], v191 offset:37888
	ds_read_b128 v[212:215], v191 offset:38912
	ds_read_b128 v[216:219], v191 offset:39936
	global_load_lds_dwordx4 v[228:229], off
	v_lshl_add_u64 v[228:229], s[22:23], 0, v[148:149]
	s_mov_b32 m0, s28
	s_nop 0
	global_load_lds_dwordx4 v[228:229], off
	s_waitcnt vmcnt(8)
	s_waitcnt lgkmcnt(0)
	s_barrier
	s_waitcnt lgkmcnt(0)
	v_mfma_f32_16x16x32_bf16 v[140:143], v[72:75], v[180:183], v[140:143]
	v_mfma_f32_16x16x32_bf16 v[136:139], v[88:91], v[180:183], v[136:139]
	v_mfma_f32_16x16x32_bf16 v[124:127], v[72:75], v[194:197], v[124:127]
	v_mfma_f32_16x16x32_bf16 v[120:123], v[88:91], v[194:197], v[120:123]
	v_mfma_f32_16x16x32_bf16 v[108:111], v[72:75], v[204:207], v[108:111]
	v_mfma_f32_16x16x32_bf16 v[104:107], v[88:91], v[204:207], v[104:107]
	v_mfma_f32_16x16x32_bf16 v[84:87], v[72:75], v[212:215], v[84:87]
	v_mfma_f32_16x16x32_bf16 v[80:83], v[88:91], v[212:215], v[80:83]
	v_mfma_f32_16x16x32_bf16 v[140:143], v[76:79], v[184:187], v[140:143]
	v_mfma_f32_16x16x32_bf16 v[136:139], v[92:95], v[184:187], v[136:139]
	v_mfma_f32_16x16x32_bf16 v[124:127], v[76:79], v[200:203], v[124:127]
	v_mfma_f32_16x16x32_bf16 v[120:123], v[92:95], v[200:203], v[120:123]
	v_mfma_f32_16x16x32_bf16 v[108:111], v[76:79], v[208:211], v[108:111]
	v_mfma_f32_16x16x32_bf16 v[104:107], v[92:95], v[208:211], v[104:107]
	v_mfma_f32_16x16x32_bf16 v[84:87], v[76:79], v[216:219], v[84:87]
	v_mfma_f32_16x16x32_bf16 v[80:83], v[92:95], v[216:219], v[80:83]
	v_mfma_f32_16x16x32_bf16 v[132:135], v[160:163], v[180:183], v[132:135]
	v_mfma_f32_16x16x32_bf16 v[128:131], v[168:171], v[180:183], v[128:131]
	v_mfma_f32_16x16x32_bf16 v[116:119], v[160:163], v[194:197], v[116:119]
	v_mfma_f32_16x16x32_bf16 v[112:115], v[168:171], v[194:197], v[112:115]
	v_mfma_f32_16x16x32_bf16 v[100:103], v[160:163], v[204:207], v[100:103]
	v_mfma_f32_16x16x32_bf16 v[96:99], v[168:171], v[204:207], v[96:99]
	v_mfma_f32_16x16x32_bf16 v[68:71], v[160:163], v[212:215], v[68:71]
	v_mfma_f32_16x16x32_bf16 v[64:67], v[168:171], v[212:215], v[64:67]
	v_mfma_f32_16x16x32_bf16 v[132:135], v[164:167], v[184:187], v[132:135]
	v_mfma_f32_16x16x32_bf16 v[128:131], v[176:179], v[184:187], v[128:131]
	v_mfma_f32_16x16x32_bf16 v[116:119], v[164:167], v[200:203], v[116:119]
	v_mfma_f32_16x16x32_bf16 v[112:115], v[176:179], v[200:203], v[112:115]
	v_mfma_f32_16x16x32_bf16 v[100:103], v[164:167], v[208:211], v[100:103]
	v_mfma_f32_16x16x32_bf16 v[96:99], v[176:179], v[208:211], v[96:99]
	v_mfma_f32_16x16x32_bf16 v[68:71], v[164:167], v[216:219], v[68:71]
	v_mfma_f32_16x16x32_bf16 v[64:67], v[176:179], v[216:219], v[64:67]
	s_barrier
	s_add_i32 s22, s33, s24
	v_lshl_add_u64 v[220:221], v[220:221], 0, s[6:7]
	s_mov_b32 m0, s22
	ds_read_b128 v[180:183], v191 offset:49152
	ds_read_b128 v[184:187], v191 offset:50176
	ds_read_b128 v[194:197], v191 offset:51200
	ds_read_b128 v[200:203], v191 offset:52224
	ds_read_b128 v[204:207], v191 offset:53248
	ds_read_b128 v[208:211], v191 offset:54272
	ds_read_b128 v[212:215], v191 offset:55296
	ds_read_b128 v[216:219], v191 offset:56320
	global_load_lds_dwordx4 v[220:221], off
	s_add_i32 m0, s22, 0x2000
	s_add_u32 s20, s20, 0x160080
	v_lshl_add_u64 v[220:221], v[222:223], 0, s[6:7]
	s_addc_u32 s21, s21, 0
	s_add_i32 s22, s34, s24
	global_load_lds_dwordx4 v[220:221], off
	v_lshl_add_u64 v[220:221], s[20:21], 0, v[146:147]
	s_mov_b32 m0, s22
	s_nop 0
	global_load_lds_dwordx4 v[220:221], off
	v_lshl_add_u64 v[220:221], s[20:21], 0, v[150:151]
	s_add_i32 m0, s22, 0x2000
	s_nop 0
	global_load_lds_dwordx4 v[220:221], off
	v_lshl_add_u64 v[220:221], v[224:225], 0, s[6:7]
	s_mov_b32 m0, s35
	s_nop 0
	global_load_lds_dwordx4 v[220:221], off
	v_lshl_add_u64 v[220:221], v[226:227], 0, s[6:7]
	s_mov_b32 m0, s48
	s_nop 0
	global_load_lds_dwordx4 v[220:221], off
	s_waitcnt vmcnt(8)
	s_waitcnt lgkmcnt(0)
	s_barrier
	s_waitcnt lgkmcnt(0)
	v_mfma_f32_16x16x32_bf16 v[60:63], v[72:75], v[180:183], v[60:63]
	v_mfma_f32_16x16x32_bf16 v[56:59], v[88:91], v[180:183], v[56:59]
	v_mfma_f32_16x16x32_bf16 v[44:47], v[72:75], v[194:197], v[44:47]
	v_mfma_f32_16x16x32_bf16 v[40:43], v[88:91], v[194:197], v[40:43]
	v_mfma_f32_16x16x32_bf16 v[28:31], v[72:75], v[204:207], v[28:31]
	v_mfma_f32_16x16x32_bf16 v[24:27], v[88:91], v[204:207], v[24:27]
	v_mfma_f32_16x16x32_bf16 v[12:15], v[72:75], v[212:215], v[12:15]
	v_mfma_f32_16x16x32_bf16 v[8:11], v[88:91], v[212:215], v[8:11]
	v_mfma_f32_16x16x32_bf16 v[60:63], v[76:79], v[184:187], v[60:63]
	v_mfma_f32_16x16x32_bf16 v[56:59], v[92:95], v[184:187], v[56:59]
	v_mfma_f32_16x16x32_bf16 v[44:47], v[76:79], v[200:203], v[44:47]
	v_mfma_f32_16x16x32_bf16 v[40:43], v[92:95], v[200:203], v[40:43]
	v_mfma_f32_16x16x32_bf16 v[28:31], v[76:79], v[208:211], v[28:31]
	v_mfma_f32_16x16x32_bf16 v[24:27], v[92:95], v[208:211], v[24:27]
	v_mfma_f32_16x16x32_bf16 v[12:15], v[76:79], v[216:219], v[12:15]
	v_mfma_f32_16x16x32_bf16 v[8:11], v[92:95], v[216:219], v[8:11]
	v_mfma_f32_16x16x32_bf16 v[52:55], v[160:163], v[180:183], v[52:55]
	v_mfma_f32_16x16x32_bf16 v[48:51], v[168:171], v[180:183], v[48:51]
	v_mfma_f32_16x16x32_bf16 v[36:39], v[160:163], v[194:197], v[36:39]
	v_mfma_f32_16x16x32_bf16 v[32:35], v[168:171], v[194:197], v[32:35]
	v_mfma_f32_16x16x32_bf16 v[20:23], v[160:163], v[204:207], v[20:23]
	v_mfma_f32_16x16x32_bf16 v[16:19], v[168:171], v[204:207], v[16:19]
	v_mfma_f32_16x16x32_bf16 v[4:7], v[160:163], v[212:215], v[4:7]
	v_mfma_f32_16x16x32_bf16 v[0:3], v[168:171], v[212:215], v[0:3]
	v_mfma_f32_16x16x32_bf16 v[52:55], v[164:167], v[184:187], v[52:55]
	v_mfma_f32_16x16x32_bf16 v[48:51], v[176:179], v[184:187], v[48:51]
	v_mfma_f32_16x16x32_bf16 v[36:39], v[164:167], v[200:203], v[36:39]
	v_mfma_f32_16x16x32_bf16 v[32:35], v[176:179], v[200:203], v[32:35]
	v_mfma_f32_16x16x32_bf16 v[20:23], v[164:167], v[208:211], v[20:23]
	v_mfma_f32_16x16x32_bf16 v[16:19], v[176:179], v[208:211], v[16:19]
	v_mfma_f32_16x16x32_bf16 v[4:7], v[164:167], v[216:219], v[4:7]
	v_mfma_f32_16x16x32_bf16 v[0:3], v[176:179], v[216:219], v[0:3]
	s_barrier
	s_add_i32 s74, s74, 2
	s_add_u32 s2, s2, 0x100
	s_addc_u32 s3, s3, 0
	s_add_u32 s72, s72, 0x100
	s_addc_u32 s73, s73, 0
	s_cmpk_gt_u32 s74, 0x55
	s_cbranch_scc0 .LBB0_440
	s_and_b64 vcc, exec, s[8:9]
	s_cbranch_vccz .LBB0_443
	s_barrier

.LBB0_668:
	ds_read_b128 v[24:27], v202
	ds_read_b128 v[28:31], v202 offset:1024
	ds_read_b128 v[40:43], v202 offset:2048
	ds_read_b128 v[44:47], v202 offset:3072
	ds_read_b128 v[164:167], v203
	ds_read_b128 v[168:171], v203 offset:1024
	ds_read_b128 v[176:179], v203 offset:2048
	ds_read_b128 v[180:183], v203 offset:3072
	s_add_u32 s8, s0, 0xfff80080
	s_addc_u32 s9, s1, -1
	s_cmp_eq_u32 s83, 28
	s_cselect_b32 s81, s7, s9
	s_cselect_b32 s80, s52, s8
	s_cselect_b32 s9, s53, s82
	s_cselect_b32 s8, s59, s69
	v_lshl_add_u64 v[196:197], s[0:1], 0, v[154:155]
	s_add_i32 m0, s57, 0xc000
	ds_read_b128 v[184:187], v204
	ds_read_b128 v[188:191], v204 offset:1024
	ds_read_b128 v[192:195], v204 offset:2048
	ds_read_b128 v[208:211], v204 offset:3072
	ds_read_b128 v[212:215], v204 offset:4096
	ds_read_b128 v[216:219], v204 offset:5120
	ds_read_b128 v[220:223], v204 offset:6144
	ds_read_b128 v[224:227], v204 offset:7168
	global_load_lds_dwordx4 v[196:197], off
	v_lshl_add_u64 v[196:197], s[0:1], 0, v[156:157]
	s_add_i32 m0, s57, 0xe000
	s_nop 0
	global_load_lds_dwordx4 v[196:197], off
	s_waitcnt vmcnt(8)
	s_waitcnt lgkmcnt(0)
	s_barrier
	s_waitcnt lgkmcnt(0)
	v_mfma_f32_16x16x32_bf16 v[140:143], v[24:27], v[184:187], v[140:143]
	v_mfma_f32_16x16x32_bf16 v[136:139], v[40:43], v[184:187], v[136:139]
	v_mfma_f32_16x16x32_bf16 v[124:127], v[24:27], v[192:195], v[124:127]
	v_mfma_f32_16x16x32_bf16 v[120:123], v[40:43], v[192:195], v[120:123]
	v_mfma_f32_16x16x32_bf16 v[108:111], v[24:27], v[212:215], v[108:111]
	v_mfma_f32_16x16x32_bf16 v[104:107], v[40:43], v[212:215], v[104:107]
	v_mfma_f32_16x16x32_bf16 v[92:95], v[24:27], v[220:223], v[92:95]
	v_mfma_f32_16x16x32_bf16 v[88:91], v[40:43], v[220:223], v[88:91]
	v_mfma_f32_16x16x32_bf16 v[140:143], v[28:31], v[188:191], v[140:143]
	v_mfma_f32_16x16x32_bf16 v[136:139], v[44:47], v[188:191], v[136:139]
	v_mfma_f32_16x16x32_bf16 v[124:127], v[28:31], v[208:211], v[124:127]
	v_mfma_f32_16x16x32_bf16 v[120:123], v[44:47], v[208:211], v[120:123]
	v_mfma_f32_16x16x32_bf16 v[108:111], v[28:31], v[216:219], v[108:111]
	v_mfma_f32_16x16x32_bf16 v[104:107], v[44:47], v[216:219], v[104:107]
	v_mfma_f32_16x16x32_bf16 v[92:95], v[28:31], v[224:227], v[92:95]
	v_mfma_f32_16x16x32_bf16 v[88:91], v[44:47], v[224:227], v[88:91]
	v_mfma_f32_16x16x32_bf16 v[132:135], v[164:167], v[184:187], v[132:135]
	v_mfma_f32_16x16x32_bf16 v[128:131], v[176:179], v[184:187], v[128:131]
	v_mfma_f32_16x16x32_bf16 v[116:119], v[164:167], v[192:195], v[116:119]
	v_mfma_f32_16x16x32_bf16 v[112:115], v[176:179], v[192:195], v[112:115]
	v_mfma_f32_16x16x32_bf16 v[100:103], v[164:167], v[212:215], v[100:103]
	v_mfma_f32_16x16x32_bf16 v[96:99], v[176:179], v[212:215], v[96:99]
	v_mfma_f32_16x16x32_bf16 v[84:87], v[164:167], v[220:223], v[84:87]
	v_mfma_f32_16x16x32_bf16 v[80:83], v[176:179], v[220:223], v[80:83]
	v_mfma_f32_16x16x32_bf16 v[132:135], v[168:171], v[188:191], v[132:135]
	v_mfma_f32_16x16x32_bf16 v[128:131], v[180:183], v[188:191], v[128:131]
	v_mfma_f32_16x16x32_bf16 v[116:119], v[168:171], v[208:211], v[116:119]
	v_mfma_f32_16x16x32_bf16 v[112:115], v[180:183], v[208:211], v[112:115]
	v_mfma_f32_16x16x32_bf16 v[100:103], v[168:171], v[216:219], v[100:103]
	v_mfma_f32_16x16x32_bf16 v[96:99], v[180:183], v[216:219], v[96:99]
	v_mfma_f32_16x16x32_bf16 v[84:87], v[168:171], v[224:227], v[84:87]
	v_mfma_f32_16x16x32_bf16 v[80:83], v[180:183], v[224:227], v[80:83]
	s_barrier
	s_add_i32 s33, s15, s35
	v_lshl_add_u64 v[196:197], s[8:9], 0, v[146:147]
	s_mov_b32 m0, s33
	ds_read_b128 v[184:187], v204 offset:16384
	ds_read_b128 v[188:191], v204 offset:17408
	ds_read_b128 v[192:195], v204 offset:18432
	ds_read_b128 v[208:211], v204 offset:19456
	ds_read_b128 v[212:215], v204 offset:20480
	ds_read_b128 v[216:219], v204 offset:21504
	ds_read_b128 v[220:223], v204 offset:22528
	ds_read_b128 v[224:227], v204 offset:23552
	global_load_lds_dwordx4 v[196:197], off
	s_add_i32 m0, s33, 0x2000
	s_add_u32 s62, s8, 0x80000
	v_lshl_add_u64 v[228:229], s[8:9], 0, v[150:151]
	s_addc_u32 s63, s9, 0
	s_add_i32 s33, s76, s35
	global_load_lds_dwordx4 v[228:229], off
	v_lshl_add_u64 v[230:231], s[62:63], 0, v[146:147]
	s_mov_b32 m0, s33
	v_lshl_add_u64 v[232:233], s[80:81], 0, v[148:149]
	global_load_lds_dwordx4 v[230:231], off
	v_lshl_add_u64 v[230:231], s[62:63], 0, v[150:151]
	s_add_i32 m0, s33, 0x2000
	s_nop 0
	global_load_lds_dwordx4 v[230:231], off
	v_lshl_add_u64 v[230:231], s[80:81], 0, v[144:145]
	s_mov_b32 m0, s57
	s_nop 0
	global_load_lds_dwordx4 v[230:231], off
	s_mov_b32 m0, s72
	s_nop 0
	global_load_lds_dwordx4 v[232:233], off
	s_waitcnt vmcnt(8)
	s_waitcnt lgkmcnt(0)
	s_barrier
	s_waitcnt lgkmcnt(0)
	v_mfma_f32_16x16x32_bf16 v[76:79], v[24:27], v[184:187], v[76:79]
	v_mfma_f32_16x16x32_bf16 v[72:75], v[40:43], v[184:187], v[72:75]
	v_mfma_f32_16x16x32_bf16 v[60:63], v[24:27], v[192:195], v[60:63]
	v_mfma_f32_16x16x32_bf16 v[56:59], v[40:43], v[192:195], v[56:59]
	v_mfma_f32_16x16x32_bf16 v[36:39], v[24:27], v[212:215], v[36:39]
	v_mfma_f32_16x16x32_bf16 v[32:35], v[40:43], v[212:215], v[32:35]
	v_mfma_f32_16x16x32_bf16 v[12:15], v[24:27], v[220:223], v[12:15]
	v_mfma_f32_16x16x32_bf16 v[8:11], v[40:43], v[220:223], v[8:11]
	v_mfma_f32_16x16x32_bf16 v[76:79], v[28:31], v[188:191], v[76:79]
	v_mfma_f32_16x16x32_bf16 v[72:75], v[44:47], v[188:191], v[72:75]
	v_mfma_f32_16x16x32_bf16 v[60:63], v[28:31], v[208:211], v[60:63]
	v_mfma_f32_16x16x32_bf16 v[56:59], v[44:47], v[208:211], v[56:59]
	v_mfma_f32_16x16x32_bf16 v[36:39], v[28:31], v[216:219], v[36:39]
	v_mfma_f32_16x16x32_bf16 v[32:35], v[44:47], v[216:219], v[32:35]
	v_mfma_f32_16x16x32_bf16 v[12:15], v[28:31], v[224:227], v[12:15]
	v_mfma_f32_16x16x32_bf16 v[8:11], v[44:47], v[224:227], v[8:11]
	v_mfma_f32_16x16x32_bf16 v[20:23], v[164:167], v[212:215], v[20:23]
	v_mfma_f32_16x16x32_bf16 v[16:19], v[176:179], v[212:215], v[16:19]
	v_mfma_f32_16x16x32_bf16 v[4:7], v[164:167], v[220:223], v[4:7]
	v_mfma_f32_16x16x32_bf16 v[0:3], v[176:179], v[220:223], v[0:3]
	v_mfma_f32_16x16x32_bf16 v[24:27], v[164:167], v[184:187], v[68:71]
	v_mfma_f32_16x16x32_bf16 v[28:31], v[176:179], v[184:187], v[64:67]
	v_mfma_f32_16x16x32_bf16 v[40:43], v[164:167], v[192:195], v[52:55]
	v_mfma_f32_16x16x32_bf16 v[44:47], v[176:179], v[192:195], v[48:51]
	v_mfma_f32_16x16x32_bf16 v[20:23], v[168:171], v[216:219], v[20:23]
	v_mfma_f32_16x16x32_bf16 v[16:19], v[180:183], v[216:219], v[16:19]
	v_mfma_f32_16x16x32_bf16 v[4:7], v[168:171], v[224:227], v[4:7]
	v_mfma_f32_16x16x32_bf16 v[0:3], v[180:183], v[224:227], v[0:3]
	v_mfma_f32_16x16x32_bf16 v[24:27], v[168:171], v[188:191], v[24:27]
	v_mfma_f32_16x16x32_bf16 v[28:31], v[180:183], v[188:191], v[28:31]
	v_mfma_f32_16x16x32_bf16 v[40:43], v[168:171], v[208:211], v[40:43]
	v_mfma_f32_16x16x32_bf16 v[44:47], v[180:183], v[208:211], v[44:47]
	s_barrier
	s_add_i32 s33, 0, 0x18000
	s_add_i32 s34, 0, 0x1c000
	v_add_u32_e32 v68, s33, v175
	v_add_u32_e32 v152, s34, v175
	ds_read_b128 v[48:51], v68
	ds_read_b128 v[52:55], v68 offset:1024
	ds_read_b128 v[64:67], v68 offset:2048
	ds_read_b128 v[68:71], v68 offset:3072
	ds_read_b128 v[164:167], v152
	ds_read_b128 v[168:171], v152 offset:1024
	ds_read_b128 v[176:179], v152 offset:2048
	ds_read_b128 v[180:183], v152 offset:3072
	s_add_u32 s62, s80, 0x80000
	s_addc_u32 s63, s81, 0
	s_mov_b32 m0, s73
	v_lshl_add_u64 v[234:235], s[62:63], 0, v[144:145]
	ds_read_b128 v[184:187], v204 offset:32768
	ds_read_b128 v[188:191], v204 offset:33792
	ds_read_b128 v[192:195], v204 offset:34816
	ds_read_b128 v[208:211], v204 offset:35840
	ds_read_b128 v[212:215], v204 offset:36864
	ds_read_b128 v[216:219], v204 offset:37888
	ds_read_b128 v[220:223], v204 offset:38912
	ds_read_b128 v[224:227], v204 offset:39936
	global_load_lds_dwordx4 v[234:235], off
	v_lshl_add_u64 v[234:235], s[62:63], 0, v[148:149]
	s_mov_b32 m0, s18
	s_nop 0
	global_load_lds_dwordx4 v[234:235], off
	s_waitcnt vmcnt(8)
	s_waitcnt lgkmcnt(0)
	s_barrier
	s_waitcnt lgkmcnt(0)
	v_mfma_f32_16x16x32_bf16 v[140:143], v[48:51], v[184:187], v[140:143]
	v_mfma_f32_16x16x32_bf16 v[136:139], v[64:67], v[184:187], v[136:139]
	v_mfma_f32_16x16x32_bf16 v[124:127], v[48:51], v[192:195], v[124:127]
	v_mfma_f32_16x16x32_bf16 v[120:123], v[64:67], v[192:195], v[120:123]
	v_mfma_f32_16x16x32_bf16 v[108:111], v[48:51], v[212:215], v[108:111]
	v_mfma_f32_16x16x32_bf16 v[104:107], v[64:67], v[212:215], v[104:107]
	v_mfma_f32_16x16x32_bf16 v[92:95], v[48:51], v[220:223], v[92:95]
	v_mfma_f32_16x16x32_bf16 v[88:91], v[64:67], v[220:223], v[88:91]
	v_mfma_f32_16x16x32_bf16 v[140:143], v[52:55], v[188:191], v[140:143]
	v_mfma_f32_16x16x32_bf16 v[136:139], v[68:71], v[188:191], v[136:139]
	v_mfma_f32_16x16x32_bf16 v[124:127], v[52:55], v[208:211], v[124:127]
	v_mfma_f32_16x16x32_bf16 v[120:123], v[68:71], v[208:211], v[120:123]
	v_mfma_f32_16x16x32_bf16 v[108:111], v[52:55], v[216:219], v[108:111]
	v_mfma_f32_16x16x32_bf16 v[104:107], v[68:71], v[216:219], v[104:107]
	v_mfma_f32_16x16x32_bf16 v[92:95], v[52:55], v[224:227], v[92:95]
	v_mfma_f32_16x16x32_bf16 v[88:91], v[68:71], v[224:227], v[88:91]
	v_mfma_f32_16x16x32_bf16 v[132:135], v[164:167], v[184:187], v[132:135]
	v_mfma_f32_16x16x32_bf16 v[128:131], v[176:179], v[184:187], v[128:131]
	v_mfma_f32_16x16x32_bf16 v[116:119], v[164:167], v[192:195], v[116:119]
	v_mfma_f32_16x16x32_bf16 v[112:115], v[176:179], v[192:195], v[112:115]
	v_mfma_f32_16x16x32_bf16 v[100:103], v[164:167], v[212:215], v[100:103]
	v_mfma_f32_16x16x32_bf16 v[96:99], v[176:179], v[212:215], v[96:99]
	v_mfma_f32_16x16x32_bf16 v[84:87], v[164:167], v[220:223], v[84:87]
	v_mfma_f32_16x16x32_bf16 v[80:83], v[176:179], v[220:223], v[80:83]
	v_mfma_f32_16x16x32_bf16 v[132:135], v[168:171], v[188:191], v[132:135]
	v_mfma_f32_16x16x32_bf16 v[128:131], v[180:183], v[188:191], v[128:131]
	v_mfma_f32_16x16x32_bf16 v[116:119], v[168:171], v[208:211], v[116:119]
	v_mfma_f32_16x16x32_bf16 v[112:115], v[180:183], v[208:211], v[112:115]
	v_mfma_f32_16x16x32_bf16 v[100:103], v[168:171], v[216:219], v[100:103]
	v_mfma_f32_16x16x32_bf16 v[96:99], v[180:183], v[216:219], v[96:99]
	v_mfma_f32_16x16x32_bf16 v[84:87], v[168:171], v[224:227], v[84:87]
	v_mfma_f32_16x16x32_bf16 v[80:83], v[180:183], v[224:227], v[80:83]
	s_barrier
	s_add_i32 s33, s33, s35
	v_lshl_add_u64 v[196:197], v[196:197], 0, s[28:29]
	s_mov_b32 m0, s33
	ds_read_b128 v[184:187], v204 offset:49152
	ds_read_b128 v[188:191], v204 offset:50176
	ds_read_b128 v[192:195], v204 offset:51200
	ds_read_b128 v[208:211], v204 offset:52224
	ds_read_b128 v[212:215], v204 offset:53248
	ds_read_b128 v[216:219], v204 offset:54272
	ds_read_b128 v[220:223], v204 offset:55296
	ds_read_b128 v[224:227], v204 offset:56320
	global_load_lds_dwordx4 v[196:197], off
	s_add_i32 m0, s33, 0x2000
	s_add_u32 s8, s8, 0x80080
	v_lshl_add_u64 v[196:197], v[228:229], 0, s[28:29]
	s_addc_u32 s9, s9, 0
	s_add_i32 s33, s34, s35
	global_load_lds_dwordx4 v[196:197], off
	v_lshl_add_u64 v[196:197], s[8:9], 0, v[146:147]
	s_mov_b32 m0, s33
	s_nop 0
	global_load_lds_dwordx4 v[196:197], off
	v_lshl_add_u64 v[196:197], s[8:9], 0, v[150:151]
	s_add_i32 m0, s33, 0x2000
	s_nop 0
	global_load_lds_dwordx4 v[196:197], off
	v_lshl_add_u64 v[196:197], v[230:231], 0, s[28:29]
	s_mov_b32 m0, s79
	s_nop 0
	global_load_lds_dwordx4 v[196:197], off
	v_lshl_add_u64 v[196:197], v[232:233], 0, s[28:29]
	s_mov_b32 m0, s20
	s_nop 0
	global_load_lds_dwordx4 v[196:197], off
	s_waitcnt vmcnt(8)
	s_waitcnt lgkmcnt(0)
	s_barrier
	s_waitcnt lgkmcnt(0)
	v_mfma_f32_16x16x32_bf16 v[76:79], v[48:51], v[184:187], v[76:79]
	v_mfma_f32_16x16x32_bf16 v[72:75], v[64:67], v[184:187], v[72:75]
	v_mfma_f32_16x16x32_bf16 v[60:63], v[48:51], v[192:195], v[60:63]
	v_mfma_f32_16x16x32_bf16 v[56:59], v[64:67], v[192:195], v[56:59]
	v_mfma_f32_16x16x32_bf16 v[36:39], v[48:51], v[212:215], v[36:39]
	v_mfma_f32_16x16x32_bf16 v[32:35], v[64:67], v[212:215], v[32:35]
	v_mfma_f32_16x16x32_bf16 v[12:15], v[48:51], v[220:223], v[12:15]
	v_mfma_f32_16x16x32_bf16 v[8:11], v[64:67], v[220:223], v[8:11]
	v_mfma_f32_16x16x32_bf16 v[76:79], v[52:55], v[188:191], v[76:79]
	v_mfma_f32_16x16x32_bf16 v[72:75], v[68:71], v[188:191], v[72:75]
	v_mfma_f32_16x16x32_bf16 v[60:63], v[52:55], v[208:211], v[60:63]
	v_mfma_f32_16x16x32_bf16 v[56:59], v[68:71], v[208:211], v[56:59]
	v_mfma_f32_16x16x32_bf16 v[36:39], v[52:55], v[216:219], v[36:39]
	v_mfma_f32_16x16x32_bf16 v[32:35], v[68:71], v[216:219], v[32:35]
	v_mfma_f32_16x16x32_bf16 v[12:15], v[52:55], v[224:227], v[12:15]
	v_mfma_f32_16x16x32_bf16 v[8:11], v[68:71], v[224:227], v[8:11]
	v_mfma_f32_16x16x32_bf16 v[24:27], v[164:167], v[184:187], v[24:27]
	v_mfma_f32_16x16x32_bf16 v[68:71], v[168:171], v[188:191], v[24:27]
	v_mfma_f32_16x16x32_bf16 v[24:27], v[176:179], v[184:187], v[28:31]
	v_mfma_f32_16x16x32_bf16 v[64:67], v[180:183], v[188:191], v[24:27]
	v_mfma_f32_16x16x32_bf16 v[24:27], v[164:167], v[192:195], v[40:43]
	v_mfma_f32_16x16x32_bf16 v[52:55], v[168:171], v[208:211], v[24:27]
	v_mfma_f32_16x16x32_bf16 v[24:27], v[176:179], v[192:195], v[44:47]
	v_mfma_f32_16x16x32_bf16 v[20:23], v[164:167], v[212:215], v[20:23]
	v_mfma_f32_16x16x32_bf16 v[16:19], v[176:179], v[212:215], v[16:19]
	v_mfma_f32_16x16x32_bf16 v[4:7], v[164:167], v[220:223], v[4:7]
	v_mfma_f32_16x16x32_bf16 v[0:3], v[176:179], v[220:223], v[0:3]
	v_mfma_f32_16x16x32_bf16 v[48:51], v[180:183], v[208:211], v[24:27]
	v_mfma_f32_16x16x32_bf16 v[20:23], v[168:171], v[216:219], v[20:23]
	v_mfma_f32_16x16x32_bf16 v[16:19], v[180:183], v[216:219], v[16:19]
	v_mfma_f32_16x16x32_bf16 v[4:7], v[168:171], v[224:227], v[4:7]
	v_mfma_f32_16x16x32_bf16 v[0:3], v[180:183], v[224:227], v[0:3]
	s_barrier
	s_add_i32 s83, s83, 2
	s_add_u32 s0, s0, 0x100
	s_addc_u32 s1, s1, 0
	s_add_u32 s69, s69, 0x100
	s_addc_u32 s82, s82, 0
	s_cmp_gt_u32 s83, 29
	s_cbranch_scc0 .LBB0_668
	s_and_b64 vcc, exec, s[30:31]
	s_cbranch_vccz .LBB0_671
	s_barrier

.LBB0_1623:
	ds_read_b128 v[146:149], v153
	ds_read_b128 v[156:159], v153 offset:1024
	ds_read_b128 v[160:163], v153 offset:2048
	ds_read_b128 v[164:167], v153 offset:3072
	ds_read_b128 v[168:171], v154
	ds_read_b128 v[176:179], v154 offset:1024
	ds_read_b128 v[180:183], v154 offset:2048
	ds_read_b128 v[184:187], v154 offset:3072
	s_add_u32 s33, s30, 0xfffc0080
	s_addc_u32 s34, s31, -1
	s_cmp_eq_u32 s68, 12
	s_cselect_b32 s43, s23, s34
	s_cselect_b32 s42, s63, s33
	s_cselect_b32 s37, s21, s67
	s_cselect_b32 s36, s65, s66
	v_lshl_add_u64 v[150:151], s[30:31], 0, v[138:139]
	s_add_i32 m0, s29, 0xc000
	ds_read_b128 v[188:191], v155
	ds_read_b128 v[192:195], v155 offset:1024
	ds_read_b128 v[196:199], v155 offset:2048
	ds_read_b128 v[200:203], v155 offset:3072
	ds_read_b128 v[204:207], v155 offset:4096
	ds_read_b128 v[208:211], v155 offset:5120
	ds_read_b128 v[212:215], v155 offset:6144
	ds_read_b128 v[216:219], v155 offset:7168
	global_load_lds_dwordx4 v[150:151], off
	v_lshl_add_u64 v[150:151], s[30:31], 0, v[140:141]
	s_add_i32 m0, s29, 0xe000
	s_nop 0
	global_load_lds_dwordx4 v[150:151], off
	s_waitcnt vmcnt(8)
	s_waitcnt lgkmcnt(0)
	s_barrier
	s_waitcnt lgkmcnt(0)
	v_mfma_f32_16x16x32_bf16 v[124:127], v[146:149], v[188:191], v[124:127]
	v_mfma_f32_16x16x32_bf16 v[120:123], v[160:163], v[188:191], v[120:123]
	v_mfma_f32_16x16x32_bf16 v[108:111], v[146:149], v[196:199], v[108:111]
	v_mfma_f32_16x16x32_bf16 v[104:107], v[160:163], v[196:199], v[104:107]
	v_mfma_f32_16x16x32_bf16 v[92:95], v[146:149], v[204:207], v[92:95]
	v_mfma_f32_16x16x32_bf16 v[88:91], v[160:163], v[204:207], v[88:91]
	v_mfma_f32_16x16x32_bf16 v[76:79], v[146:149], v[212:215], v[76:79]
	v_mfma_f32_16x16x32_bf16 v[72:75], v[160:163], v[212:215], v[72:75]
	v_mfma_f32_16x16x32_bf16 v[124:127], v[156:159], v[192:195], v[124:127]
	v_mfma_f32_16x16x32_bf16 v[120:123], v[164:167], v[192:195], v[120:123]
	v_mfma_f32_16x16x32_bf16 v[108:111], v[156:159], v[200:203], v[108:111]
	v_mfma_f32_16x16x32_bf16 v[104:107], v[164:167], v[200:203], v[104:107]
	v_mfma_f32_16x16x32_bf16 v[92:95], v[156:159], v[208:211], v[92:95]
	v_mfma_f32_16x16x32_bf16 v[88:91], v[164:167], v[208:211], v[88:91]
	v_mfma_f32_16x16x32_bf16 v[76:79], v[156:159], v[216:219], v[76:79]
	v_mfma_f32_16x16x32_bf16 v[72:75], v[164:167], v[216:219], v[72:75]
	v_mfma_f32_16x16x32_bf16 v[116:119], v[168:171], v[188:191], v[116:119]
	v_mfma_f32_16x16x32_bf16 v[112:115], v[180:183], v[188:191], v[112:115]
	v_mfma_f32_16x16x32_bf16 v[100:103], v[168:171], v[196:199], v[100:103]
	v_mfma_f32_16x16x32_bf16 v[96:99], v[180:183], v[196:199], v[96:99]
	v_mfma_f32_16x16x32_bf16 v[84:87], v[168:171], v[204:207], v[84:87]
	v_mfma_f32_16x16x32_bf16 v[80:83], v[180:183], v[204:207], v[80:83]
	v_mfma_f32_16x16x32_bf16 v[68:71], v[168:171], v[212:215], v[68:71]
	v_mfma_f32_16x16x32_bf16 v[64:67], v[180:183], v[212:215], v[64:67]
	v_mfma_f32_16x16x32_bf16 v[116:119], v[176:179], v[192:195], v[116:119]
	v_mfma_f32_16x16x32_bf16 v[112:115], v[184:187], v[192:195], v[112:115]
	v_mfma_f32_16x16x32_bf16 v[100:103], v[176:179], v[200:203], v[100:103]
	v_mfma_f32_16x16x32_bf16 v[96:99], v[184:187], v[200:203], v[96:99]
	v_mfma_f32_16x16x32_bf16 v[84:87], v[176:179], v[208:211], v[84:87]
	v_mfma_f32_16x16x32_bf16 v[80:83], v[184:187], v[208:211], v[80:83]
	v_mfma_f32_16x16x32_bf16 v[68:71], v[176:179], v[216:219], v[68:71]
	v_mfma_f32_16x16x32_bf16 v[64:67], v[184:187], v[216:219], v[64:67]
	s_barrier
	s_add_i32 s33, s60, s44
	v_lshl_add_u64 v[150:151], s[36:37], 0, v[132:133]
	s_mov_b32 m0, s33
	ds_read_b128 v[188:191], v155 offset:16384
	ds_read_b128 v[192:195], v155 offset:17408
	ds_read_b128 v[196:199], v155 offset:18432
	ds_read_b128 v[200:203], v155 offset:19456
	ds_read_b128 v[204:207], v155 offset:20480
	ds_read_b128 v[208:211], v155 offset:21504
	ds_read_b128 v[212:215], v155 offset:22528
	ds_read_b128 v[216:219], v155 offset:23552
	global_load_lds_dwordx4 v[150:151], off
	s_add_i32 m0, s33, 0x2000
	s_add_u32 s56, s36, 0x40000
	v_lshl_add_u64 v[220:221], s[36:37], 0, v[128:129]
	s_addc_u32 s57, s37, 0
	s_add_i32 s33, s61, s44
	global_load_lds_dwordx4 v[220:221], off
	v_lshl_add_u64 v[222:223], s[56:57], 0, v[132:133]
	s_mov_b32 m0, s33
	v_lshl_add_u64 v[224:225], s[42:43], 0, v[130:131]
	global_load_lds_dwordx4 v[222:223], off
	v_lshl_add_u64 v[222:223], s[56:57], 0, v[128:129]
	s_add_i32 m0, s33, 0x2000
	s_nop 0
	global_load_lds_dwordx4 v[222:223], off
	v_lshl_add_u64 v[222:223], s[42:43], 0, v[134:135]
	s_mov_b32 m0, s29
	s_nop 0
	global_load_lds_dwordx4 v[222:223], off
	s_mov_b32 m0, s46
	s_nop 0
	global_load_lds_dwordx4 v[224:225], off
	s_waitcnt vmcnt(8)
	s_waitcnt lgkmcnt(0)
	s_barrier
	s_waitcnt lgkmcnt(0)
	v_mfma_f32_16x16x32_bf16 v[60:63], v[146:149], v[188:191], v[60:63]
	v_mfma_f32_16x16x32_bf16 v[56:59], v[160:163], v[188:191], v[56:59]
	v_mfma_f32_16x16x32_bf16 v[44:47], v[146:149], v[196:199], v[44:47]
	v_mfma_f32_16x16x32_bf16 v[40:43], v[160:163], v[196:199], v[40:43]
	v_mfma_f32_16x16x32_bf16 v[28:31], v[146:149], v[204:207], v[28:31]
	v_mfma_f32_16x16x32_bf16 v[24:27], v[160:163], v[204:207], v[24:27]
	v_mfma_f32_16x16x32_bf16 v[12:15], v[146:149], v[212:215], v[12:15]
	v_mfma_f32_16x16x32_bf16 v[8:11], v[160:163], v[212:215], v[8:11]
	v_mfma_f32_16x16x32_bf16 v[60:63], v[156:159], v[192:195], v[60:63]
	v_mfma_f32_16x16x32_bf16 v[56:59], v[164:167], v[192:195], v[56:59]
	v_mfma_f32_16x16x32_bf16 v[44:47], v[156:159], v[200:203], v[44:47]
	v_mfma_f32_16x16x32_bf16 v[40:43], v[164:167], v[200:203], v[40:43]
	v_mfma_f32_16x16x32_bf16 v[28:31], v[156:159], v[208:211], v[28:31]
	v_mfma_f32_16x16x32_bf16 v[24:27], v[164:167], v[208:211], v[24:27]
	v_mfma_f32_16x16x32_bf16 v[12:15], v[156:159], v[216:219], v[12:15]
	v_mfma_f32_16x16x32_bf16 v[8:11], v[164:167], v[216:219], v[8:11]
	v_mfma_f32_16x16x32_bf16 v[52:55], v[168:171], v[188:191], v[52:55]
	v_mfma_f32_16x16x32_bf16 v[48:51], v[180:183], v[188:191], v[48:51]
	v_mfma_f32_16x16x32_bf16 v[36:39], v[168:171], v[196:199], v[36:39]
	v_mfma_f32_16x16x32_bf16 v[32:35], v[180:183], v[196:199], v[32:35]
	v_mfma_f32_16x16x32_bf16 v[20:23], v[168:171], v[204:207], v[20:23]
	v_mfma_f32_16x16x32_bf16 v[16:19], v[180:183], v[204:207], v[16:19]
	v_mfma_f32_16x16x32_bf16 v[4:7], v[168:171], v[212:215], v[4:7]
	v_mfma_f32_16x16x32_bf16 v[0:3], v[180:183], v[212:215], v[0:3]
	v_mfma_f32_16x16x32_bf16 v[52:55], v[176:179], v[192:195], v[52:55]
	v_mfma_f32_16x16x32_bf16 v[48:51], v[184:187], v[192:195], v[48:51]
	v_mfma_f32_16x16x32_bf16 v[36:39], v[176:179], v[200:203], v[36:39]
	v_mfma_f32_16x16x32_bf16 v[32:35], v[184:187], v[200:203], v[32:35]
	v_mfma_f32_16x16x32_bf16 v[20:23], v[176:179], v[208:211], v[20:23]
	v_mfma_f32_16x16x32_bf16 v[16:19], v[184:187], v[208:211], v[16:19]
	v_mfma_f32_16x16x32_bf16 v[4:7], v[176:179], v[216:219], v[4:7]
	v_mfma_f32_16x16x32_bf16 v[0:3], v[184:187], v[216:219], v[0:3]
	s_barrier
	s_add_i32 s33, 0, 0x18000
	s_add_i32 s34, 0, 0x1c000
	v_add_u32_e32 v164, s33, v152
	v_add_u32_e32 v173, s34, v152
	ds_read_b128 v[146:149], v164
	ds_read_b128 v[156:159], v164 offset:1024
	ds_read_b128 v[160:163], v164 offset:2048
	ds_read_b128 v[164:167], v164 offset:3072
	ds_read_b128 v[168:171], v173
	ds_read_b128 v[176:179], v173 offset:1024
	ds_read_b128 v[180:183], v173 offset:2048
	ds_read_b128 v[184:187], v173 offset:3072
	s_add_u32 s42, s42, 0x40000
	s_addc_u32 s43, s43, 0
	s_mov_b32 m0, s47
	v_lshl_add_u64 v[226:227], s[42:43], 0, v[134:135]
	ds_read_b128 v[188:191], v155 offset:32768
	ds_read_b128 v[192:195], v155 offset:33792
	ds_read_b128 v[196:199], v155 offset:34816
	ds_read_b128 v[200:203], v155 offset:35840
	ds_read_b128 v[204:207], v155 offset:36864
	ds_read_b128 v[208:211], v155 offset:37888
	ds_read_b128 v[212:215], v155 offset:38912
	ds_read_b128 v[216:219], v155 offset:39936
	global_load_lds_dwordx4 v[226:227], off
	v_lshl_add_u64 v[226:227], s[42:43], 0, v[130:131]
	s_mov_b32 m0, s52
	s_nop 0
	global_load_lds_dwordx4 v[226:227], off
	s_waitcnt vmcnt(8)
	s_waitcnt lgkmcnt(0)
	s_barrier
	s_waitcnt lgkmcnt(0)
	v_mfma_f32_16x16x32_bf16 v[124:127], v[146:149], v[188:191], v[124:127]
	v_mfma_f32_16x16x32_bf16 v[120:123], v[160:163], v[188:191], v[120:123]
	v_mfma_f32_16x16x32_bf16 v[108:111], v[146:149], v[196:199], v[108:111]
	v_mfma_f32_16x16x32_bf16 v[104:107], v[160:163], v[196:199], v[104:107]
	v_mfma_f32_16x16x32_bf16 v[92:95], v[146:149], v[204:207], v[92:95]
	v_mfma_f32_16x16x32_bf16 v[88:91], v[160:163], v[204:207], v[88:91]
	v_mfma_f32_16x16x32_bf16 v[76:79], v[146:149], v[212:215], v[76:79]
	v_mfma_f32_16x16x32_bf16 v[72:75], v[160:163], v[212:215], v[72:75]
	v_mfma_f32_16x16x32_bf16 v[124:127], v[156:159], v[192:195], v[124:127]
	v_mfma_f32_16x16x32_bf16 v[120:123], v[164:167], v[192:195], v[120:123]
	v_mfma_f32_16x16x32_bf16 v[108:111], v[156:159], v[200:203], v[108:111]
	v_mfma_f32_16x16x32_bf16 v[104:107], v[164:167], v[200:203], v[104:107]
	v_mfma_f32_16x16x32_bf16 v[92:95], v[156:159], v[208:211], v[92:95]
	v_mfma_f32_16x16x32_bf16 v[88:91], v[164:167], v[208:211], v[88:91]
	v_mfma_f32_16x16x32_bf16 v[76:79], v[156:159], v[216:219], v[76:79]
	v_mfma_f32_16x16x32_bf16 v[72:75], v[164:167], v[216:219], v[72:75]
	v_mfma_f32_16x16x32_bf16 v[116:119], v[168:171], v[188:191], v[116:119]
	v_mfma_f32_16x16x32_bf16 v[112:115], v[180:183], v[188:191], v[112:115]
	v_mfma_f32_16x16x32_bf16 v[100:103], v[168:171], v[196:199], v[100:103]
	v_mfma_f32_16x16x32_bf16 v[96:99], v[180:183], v[196:199], v[96:99]
	v_mfma_f32_16x16x32_bf16 v[84:87], v[168:171], v[204:207], v[84:87]
	v_mfma_f32_16x16x32_bf16 v[80:83], v[180:183], v[204:207], v[80:83]
	v_mfma_f32_16x16x32_bf16 v[68:71], v[168:171], v[212:215], v[68:71]
	v_mfma_f32_16x16x32_bf16 v[64:67], v[180:183], v[212:215], v[64:67]
	v_mfma_f32_16x16x32_bf16 v[116:119], v[176:179], v[192:195], v[116:119]
	v_mfma_f32_16x16x32_bf16 v[112:115], v[184:187], v[192:195], v[112:115]
	v_mfma_f32_16x16x32_bf16 v[100:103], v[176:179], v[200:203], v[100:103]
	v_mfma_f32_16x16x32_bf16 v[96:99], v[184:187], v[200:203], v[96:99]
	v_mfma_f32_16x16x32_bf16 v[84:87], v[176:179], v[208:211], v[84:87]
	v_mfma_f32_16x16x32_bf16 v[80:83], v[184:187], v[208:211], v[80:83]
	v_mfma_f32_16x16x32_bf16 v[68:71], v[176:179], v[216:219], v[68:71]
	v_mfma_f32_16x16x32_bf16 v[64:67], v[184:187], v[216:219], v[64:67]
	s_barrier
	s_add_i32 s33, s33, s44
	v_lshl_add_u64 v[150:151], v[150:151], 0, s[4:5]
	s_mov_b32 m0, s33
	ds_read_b128 v[188:191], v155 offset:49152
	ds_read_b128 v[192:195], v155 offset:50176
	ds_read_b128 v[196:199], v155 offset:51200
	ds_read_b128 v[200:203], v155 offset:52224
	ds_read_b128 v[204:207], v155 offset:53248
	ds_read_b128 v[208:211], v155 offset:54272
	ds_read_b128 v[212:215], v155 offset:55296
	ds_read_b128 v[216:219], v155 offset:56320
	global_load_lds_dwordx4 v[150:151], off
	s_add_i32 m0, s33, 0x2000
	s_add_u32 s36, s36, 0x40080
	v_lshl_add_u64 v[150:151], v[220:221], 0, s[4:5]
	s_addc_u32 s37, s37, 0
	s_add_i32 s33, s34, s44
	global_load_lds_dwordx4 v[150:151], off
	v_lshl_add_u64 v[150:151], s[36:37], 0, v[132:133]
	s_mov_b32 m0, s33
	s_nop 0
	global_load_lds_dwordx4 v[150:151], off
	v_lshl_add_u64 v[150:151], s[36:37], 0, v[128:129]
	s_add_i32 m0, s33, 0x2000
	s_nop 0
	global_load_lds_dwordx4 v[150:151], off
	v_lshl_add_u64 v[150:151], v[222:223], 0, s[4:5]
	s_mov_b32 m0, s54
	s_nop 0
	global_load_lds_dwordx4 v[150:151], off
	v_lshl_add_u64 v[150:151], v[224:225], 0, s[4:5]
	s_mov_b32 m0, s55
	s_nop 0
	global_load_lds_dwordx4 v[150:151], off
	s_waitcnt vmcnt(8)
	s_waitcnt lgkmcnt(0)
	s_barrier
	s_waitcnt lgkmcnt(0)
	v_mfma_f32_16x16x32_bf16 v[60:63], v[146:149], v[188:191], v[60:63]
	v_mfma_f32_16x16x32_bf16 v[56:59], v[160:163], v[188:191], v[56:59]
	v_mfma_f32_16x16x32_bf16 v[44:47], v[146:149], v[196:199], v[44:47]
	v_mfma_f32_16x16x32_bf16 v[40:43], v[160:163], v[196:199], v[40:43]
	v_mfma_f32_16x16x32_bf16 v[28:31], v[146:149], v[204:207], v[28:31]
	v_mfma_f32_16x16x32_bf16 v[24:27], v[160:163], v[204:207], v[24:27]
	v_mfma_f32_16x16x32_bf16 v[12:15], v[146:149], v[212:215], v[12:15]
	v_mfma_f32_16x16x32_bf16 v[8:11], v[160:163], v[212:215], v[8:11]
	v_mfma_f32_16x16x32_bf16 v[60:63], v[156:159], v[192:195], v[60:63]
	v_mfma_f32_16x16x32_bf16 v[56:59], v[164:167], v[192:195], v[56:59]
	v_mfma_f32_16x16x32_bf16 v[44:47], v[156:159], v[200:203], v[44:47]
	v_mfma_f32_16x16x32_bf16 v[40:43], v[164:167], v[200:203], v[40:43]
	v_mfma_f32_16x16x32_bf16 v[28:31], v[156:159], v[208:211], v[28:31]
	v_mfma_f32_16x16x32_bf16 v[24:27], v[164:167], v[208:211], v[24:27]
	v_mfma_f32_16x16x32_bf16 v[12:15], v[156:159], v[216:219], v[12:15]
	v_mfma_f32_16x16x32_bf16 v[8:11], v[164:167], v[216:219], v[8:11]
	v_mfma_f32_16x16x32_bf16 v[52:55], v[168:171], v[188:191], v[52:55]
	v_mfma_f32_16x16x32_bf16 v[48:51], v[180:183], v[188:191], v[48:51]
	v_mfma_f32_16x16x32_bf16 v[36:39], v[168:171], v[196:199], v[36:39]
	v_mfma_f32_16x16x32_bf16 v[32:35], v[180:183], v[196:199], v[32:35]
	v_mfma_f32_16x16x32_bf16 v[20:23], v[168:171], v[204:207], v[20:23]
	v_mfma_f32_16x16x32_bf16 v[16:19], v[180:183], v[204:207], v[16:19]
	v_mfma_f32_16x16x32_bf16 v[4:7], v[168:171], v[212:215], v[4:7]
	v_mfma_f32_16x16x32_bf16 v[0:3], v[180:183], v[212:215], v[0:3]
	v_mfma_f32_16x16x32_bf16 v[52:55], v[176:179], v[192:195], v[52:55]
	v_mfma_f32_16x16x32_bf16 v[48:51], v[184:187], v[192:195], v[48:51]
	v_mfma_f32_16x16x32_bf16 v[36:39], v[176:179], v[200:203], v[36:39]
	v_mfma_f32_16x16x32_bf16 v[32:35], v[184:187], v[200:203], v[32:35]
	v_mfma_f32_16x16x32_bf16 v[20:23], v[176:179], v[208:211], v[20:23]
	v_mfma_f32_16x16x32_bf16 v[16:19], v[184:187], v[208:211], v[16:19]
	v_mfma_f32_16x16x32_bf16 v[4:7], v[176:179], v[216:219], v[4:7]
	v_mfma_f32_16x16x32_bf16 v[0:3], v[184:187], v[216:219], v[0:3]
	s_barrier
	s_add_i32 s68, s68, 2
	s_add_u32 s30, s30, 0x100
	s_addc_u32 s31, s31, 0
	s_add_u32 s66, s66, 0x100
	s_addc_u32 s67, s67, 0
	s_cmp_gt_u32 s68, 13
	s_cbranch_scc0 .LBB0_1623
	s_and_b64 vcc, exec, s[6:7]
	s_cbranch_vccz .LBB0_1626
	s_barrier

.LBB0_1944:
	ds_read_b128 v[146:149], v161
	ds_read_b128 v[164:167], v161 offset:1024
	ds_read_b128 v[168:171], v161 offset:2048
	ds_read_b128 v[176:179], v161 offset:3072
	ds_read_b128 v[180:183], v162
	ds_read_b128 v[184:187], v162 offset:1024
	ds_read_b128 v[188:191], v162 offset:2048
	ds_read_b128 v[192:195], v162 offset:3072
	s_add_u32 s33, s42, 0xfffc0080
	s_addc_u32 s34, s43, -1
	s_cmp_eq_u32 s72, 12
	s_cselect_b32 s47, s27, s34
	s_cselect_b32 s46, s68, s33
	s_cselect_b32 s45, s25, s71
	s_cselect_b32 s44, s69, s70
	v_lshl_add_u64 v[150:151], s[42:43], 0, v[138:139]
	s_add_i32 m0, s37, 0xc000
	ds_read_b128 v[196:199], v163
	ds_read_b128 v[200:203], v163 offset:1024
	ds_read_b128 v[204:207], v163 offset:2048
	ds_read_b128 v[208:211], v163 offset:3072
	ds_read_b128 v[212:215], v163 offset:4096
	ds_read_b128 v[216:219], v163 offset:5120
	ds_read_b128 v[220:223], v163 offset:6144
	ds_read_b128 v[224:227], v163 offset:7168
	global_load_lds_dwordx4 v[150:151], off
	v_lshl_add_u64 v[150:151], s[42:43], 0, v[140:141]
	s_add_i32 m0, s37, 0xe000
	s_nop 0
	global_load_lds_dwordx4 v[150:151], off
	s_waitcnt vmcnt(8)
	s_waitcnt lgkmcnt(0)
	s_barrier
	s_waitcnt lgkmcnt(0)
	v_mfma_f32_16x16x32_bf16 v[124:127], v[146:149], v[196:199], v[124:127]
	v_mfma_f32_16x16x32_bf16 v[120:123], v[168:171], v[196:199], v[120:123]
	v_mfma_f32_16x16x32_bf16 v[108:111], v[146:149], v[204:207], v[108:111]
	v_mfma_f32_16x16x32_bf16 v[104:107], v[168:171], v[204:207], v[104:107]
	v_mfma_f32_16x16x32_bf16 v[92:95], v[146:149], v[212:215], v[92:95]
	v_mfma_f32_16x16x32_bf16 v[88:91], v[168:171], v[212:215], v[88:91]
	v_mfma_f32_16x16x32_bf16 v[76:79], v[146:149], v[220:223], v[76:79]
	v_mfma_f32_16x16x32_bf16 v[72:75], v[168:171], v[220:223], v[72:75]
	v_mfma_f32_16x16x32_bf16 v[124:127], v[164:167], v[200:203], v[124:127]
	v_mfma_f32_16x16x32_bf16 v[120:123], v[176:179], v[200:203], v[120:123]
	v_mfma_f32_16x16x32_bf16 v[108:111], v[164:167], v[208:211], v[108:111]
	v_mfma_f32_16x16x32_bf16 v[104:107], v[176:179], v[208:211], v[104:107]
	v_mfma_f32_16x16x32_bf16 v[92:95], v[164:167], v[216:219], v[92:95]
	v_mfma_f32_16x16x32_bf16 v[88:91], v[176:179], v[216:219], v[88:91]
	v_mfma_f32_16x16x32_bf16 v[76:79], v[164:167], v[224:227], v[76:79]
	v_mfma_f32_16x16x32_bf16 v[72:75], v[176:179], v[224:227], v[72:75]
	v_mfma_f32_16x16x32_bf16 v[116:119], v[180:183], v[196:199], v[116:119]
	v_mfma_f32_16x16x32_bf16 v[112:115], v[188:191], v[196:199], v[112:115]
	v_mfma_f32_16x16x32_bf16 v[100:103], v[180:183], v[204:207], v[100:103]
	v_mfma_f32_16x16x32_bf16 v[96:99], v[188:191], v[204:207], v[96:99]
	v_mfma_f32_16x16x32_bf16 v[84:87], v[180:183], v[212:215], v[84:87]
	v_mfma_f32_16x16x32_bf16 v[80:83], v[188:191], v[212:215], v[80:83]
	v_mfma_f32_16x16x32_bf16 v[68:71], v[180:183], v[220:223], v[68:71]
	v_mfma_f32_16x16x32_bf16 v[64:67], v[188:191], v[220:223], v[64:67]
	v_mfma_f32_16x16x32_bf16 v[116:119], v[184:187], v[200:203], v[116:119]
	v_mfma_f32_16x16x32_bf16 v[112:115], v[192:195], v[200:203], v[112:115]
	v_mfma_f32_16x16x32_bf16 v[100:103], v[184:187], v[208:211], v[100:103]
	v_mfma_f32_16x16x32_bf16 v[96:99], v[192:195], v[208:211], v[96:99]
	v_mfma_f32_16x16x32_bf16 v[84:87], v[184:187], v[216:219], v[84:87]
	v_mfma_f32_16x16x32_bf16 v[80:83], v[192:195], v[216:219], v[80:83]
	v_mfma_f32_16x16x32_bf16 v[68:71], v[184:187], v[224:227], v[68:71]
	v_mfma_f32_16x16x32_bf16 v[64:67], v[192:195], v[224:227], v[64:67]
	s_barrier
	s_add_i32 s33, s65, s52
	v_lshl_add_u64 v[150:151], s[44:45], 0, v[130:131]
	s_mov_b32 m0, s33
	ds_read_b128 v[196:199], v163 offset:16384
	ds_read_b128 v[200:203], v163 offset:17408
	ds_read_b128 v[204:207], v163 offset:18432
	ds_read_b128 v[208:211], v163 offset:19456
	ds_read_b128 v[212:215], v163 offset:20480
	ds_read_b128 v[216:219], v163 offset:21504
	ds_read_b128 v[220:223], v163 offset:22528
	ds_read_b128 v[224:227], v163 offset:23552
	global_load_lds_dwordx4 v[150:151], off
	s_add_i32 m0, s33, 0x2000
	s_add_u32 s56, s44, 0x40000
	v_lshl_add_u64 v[228:229], s[44:45], 0, v[134:135]
	s_addc_u32 s57, s45, 0
	s_add_i32 s33, s66, s52
	global_load_lds_dwordx4 v[228:229], off
	v_lshl_add_u64 v[230:231], s[56:57], 0, v[130:131]
	s_mov_b32 m0, s33
	v_lshl_add_u64 v[232:233], s[46:47], 0, v[132:133]
	global_load_lds_dwordx4 v[230:231], off
	v_lshl_add_u64 v[230:231], s[56:57], 0, v[134:135]
	s_add_i32 m0, s33, 0x2000
	s_nop 0
	global_load_lds_dwordx4 v[230:231], off
	v_lshl_add_u64 v[230:231], s[46:47], 0, v[128:129]
	s_mov_b32 m0, s37
	s_nop 0
	global_load_lds_dwordx4 v[230:231], off
	s_mov_b32 m0, s54
	s_nop 0
	global_load_lds_dwordx4 v[232:233], off
	s_waitcnt vmcnt(8)
	s_waitcnt lgkmcnt(0)
	s_barrier
	s_waitcnt lgkmcnt(0)
	v_mfma_f32_16x16x32_bf16 v[60:63], v[146:149], v[196:199], v[60:63]
	v_mfma_f32_16x16x32_bf16 v[56:59], v[168:171], v[196:199], v[56:59]
	v_mfma_f32_16x16x32_bf16 v[44:47], v[146:149], v[204:207], v[44:47]
	v_mfma_f32_16x16x32_bf16 v[40:43], v[168:171], v[204:207], v[40:43]
	v_mfma_f32_16x16x32_bf16 v[28:31], v[146:149], v[212:215], v[28:31]
	v_mfma_f32_16x16x32_bf16 v[24:27], v[168:171], v[212:215], v[24:27]
	v_mfma_f32_16x16x32_bf16 v[12:15], v[146:149], v[220:223], v[12:15]
	v_mfma_f32_16x16x32_bf16 v[8:11], v[168:171], v[220:223], v[8:11]
	v_mfma_f32_16x16x32_bf16 v[60:63], v[164:167], v[200:203], v[60:63]
	v_mfma_f32_16x16x32_bf16 v[56:59], v[176:179], v[200:203], v[56:59]
	v_mfma_f32_16x16x32_bf16 v[44:47], v[164:167], v[208:211], v[44:47]
	v_mfma_f32_16x16x32_bf16 v[40:43], v[176:179], v[208:211], v[40:43]
	v_mfma_f32_16x16x32_bf16 v[28:31], v[164:167], v[216:219], v[28:31]
	v_mfma_f32_16x16x32_bf16 v[24:27], v[176:179], v[216:219], v[24:27]
	v_mfma_f32_16x16x32_bf16 v[12:15], v[164:167], v[224:227], v[12:15]
	v_mfma_f32_16x16x32_bf16 v[8:11], v[176:179], v[224:227], v[8:11]
	v_mfma_f32_16x16x32_bf16 v[52:55], v[180:183], v[196:199], v[52:55]
	v_mfma_f32_16x16x32_bf16 v[48:51], v[188:191], v[196:199], v[48:51]
	v_mfma_f32_16x16x32_bf16 v[36:39], v[180:183], v[204:207], v[36:39]
	v_mfma_f32_16x16x32_bf16 v[32:35], v[188:191], v[204:207], v[32:35]
	v_mfma_f32_16x16x32_bf16 v[20:23], v[180:183], v[212:215], v[20:23]
	v_mfma_f32_16x16x32_bf16 v[16:19], v[188:191], v[212:215], v[16:19]
	v_mfma_f32_16x16x32_bf16 v[4:7], v[180:183], v[220:223], v[4:7]
	v_mfma_f32_16x16x32_bf16 v[0:3], v[188:191], v[220:223], v[0:3]
	v_mfma_f32_16x16x32_bf16 v[52:55], v[184:187], v[200:203], v[52:55]
	v_mfma_f32_16x16x32_bf16 v[48:51], v[192:195], v[200:203], v[48:51]
	v_mfma_f32_16x16x32_bf16 v[36:39], v[184:187], v[208:211], v[36:39]
	v_mfma_f32_16x16x32_bf16 v[32:35], v[192:195], v[208:211], v[32:35]
	v_mfma_f32_16x16x32_bf16 v[20:23], v[184:187], v[216:219], v[20:23]
	v_mfma_f32_16x16x32_bf16 v[16:19], v[192:195], v[216:219], v[16:19]
	v_mfma_f32_16x16x32_bf16 v[4:7], v[184:187], v[224:227], v[4:7]
	v_mfma_f32_16x16x32_bf16 v[0:3], v[192:195], v[224:227], v[0:3]
	s_barrier
	s_add_i32 s33, 0, 0x18000
	v_add_u32_e32 v173, s33, v160
	s_add_i32 s34, 0, 0x1c000
	ds_read_b128 v[146:149], v173
	ds_read_b128 v[164:167], v173 offset:1024
	ds_read_b128 v[168:171], v173 offset:2048
	ds_read_b128 v[176:179], v173 offset:3072
	v_add_u32_e32 v173, s34, v160
	ds_read_b128 v[180:183], v173
	ds_read_b128 v[184:187], v173 offset:1024
	ds_read_b128 v[188:191], v173 offset:2048
	ds_read_b128 v[192:195], v173 offset:3072
	s_add_u32 s46, s46, 0x40000
	s_addc_u32 s47, s47, 0
	s_mov_b32 m0, s55
	v_lshl_add_u64 v[234:235], s[46:47], 0, v[128:129]
	ds_read_b128 v[196:199], v163 offset:32768
	ds_read_b128 v[200:203], v163 offset:33792
	ds_read_b128 v[204:207], v163 offset:34816
	ds_read_b128 v[208:211], v163 offset:35840
	ds_read_b128 v[212:215], v163 offset:36864
	ds_read_b128 v[216:219], v163 offset:37888
	ds_read_b128 v[220:223], v163 offset:38912
	ds_read_b128 v[224:227], v163 offset:39936
	global_load_lds_dwordx4 v[234:235], off
	v_lshl_add_u64 v[234:235], s[46:47], 0, v[132:133]
	s_mov_b32 m0, s58
	s_nop 0
	global_load_lds_dwordx4 v[234:235], off
	s_waitcnt vmcnt(8)
	s_waitcnt lgkmcnt(0)
	s_barrier
	s_waitcnt lgkmcnt(0)
	v_mfma_f32_16x16x32_bf16 v[124:127], v[146:149], v[196:199], v[124:127]
	v_mfma_f32_16x16x32_bf16 v[120:123], v[168:171], v[196:199], v[120:123]
	v_mfma_f32_16x16x32_bf16 v[108:111], v[146:149], v[204:207], v[108:111]
	v_mfma_f32_16x16x32_bf16 v[104:107], v[168:171], v[204:207], v[104:107]
	v_mfma_f32_16x16x32_bf16 v[92:95], v[146:149], v[212:215], v[92:95]
	v_mfma_f32_16x16x32_bf16 v[88:91], v[168:171], v[212:215], v[88:91]
	v_mfma_f32_16x16x32_bf16 v[76:79], v[146:149], v[220:223], v[76:79]
	v_mfma_f32_16x16x32_bf16 v[72:75], v[168:171], v[220:223], v[72:75]
	v_mfma_f32_16x16x32_bf16 v[124:127], v[164:167], v[200:203], v[124:127]
	v_mfma_f32_16x16x32_bf16 v[120:123], v[176:179], v[200:203], v[120:123]
	v_mfma_f32_16x16x32_bf16 v[108:111], v[164:167], v[208:211], v[108:111]
	v_mfma_f32_16x16x32_bf16 v[104:107], v[176:179], v[208:211], v[104:107]
	v_mfma_f32_16x16x32_bf16 v[92:95], v[164:167], v[216:219], v[92:95]
	v_mfma_f32_16x16x32_bf16 v[88:91], v[176:179], v[216:219], v[88:91]
	v_mfma_f32_16x16x32_bf16 v[76:79], v[164:167], v[224:227], v[76:79]
	v_mfma_f32_16x16x32_bf16 v[72:75], v[176:179], v[224:227], v[72:75]
	v_mfma_f32_16x16x32_bf16 v[116:119], v[180:183], v[196:199], v[116:119]
	v_mfma_f32_16x16x32_bf16 v[112:115], v[188:191], v[196:199], v[112:115]
	v_mfma_f32_16x16x32_bf16 v[100:103], v[180:183], v[204:207], v[100:103]
	v_mfma_f32_16x16x32_bf16 v[96:99], v[188:191], v[204:207], v[96:99]
	v_mfma_f32_16x16x32_bf16 v[84:87], v[180:183], v[212:215], v[84:87]
	v_mfma_f32_16x16x32_bf16 v[80:83], v[188:191], v[212:215], v[80:83]
	v_mfma_f32_16x16x32_bf16 v[68:71], v[180:183], v[220:223], v[68:71]
	v_mfma_f32_16x16x32_bf16 v[64:67], v[188:191], v[220:223], v[64:67]
	v_mfma_f32_16x16x32_bf16 v[116:119], v[184:187], v[200:203], v[116:119]
	v_mfma_f32_16x16x32_bf16 v[112:115], v[192:195], v[200:203], v[112:115]
	v_mfma_f32_16x16x32_bf16 v[100:103], v[184:187], v[208:211], v[100:103]
	v_mfma_f32_16x16x32_bf16 v[96:99], v[192:195], v[208:211], v[96:99]
	v_mfma_f32_16x16x32_bf16 v[84:87], v[184:187], v[216:219], v[84:87]
	v_mfma_f32_16x16x32_bf16 v[80:83], v[192:195], v[216:219], v[80:83]
	v_mfma_f32_16x16x32_bf16 v[68:71], v[184:187], v[224:227], v[68:71]
	v_mfma_f32_16x16x32_bf16 v[64:67], v[192:195], v[224:227], v[64:67]
	s_barrier
	s_add_i32 s33, s33, s52
	v_lshl_add_u64 v[150:151], v[150:151], 0, s[8:9]
	s_mov_b32 m0, s33
	ds_read_b128 v[196:199], v163 offset:49152
	ds_read_b128 v[200:203], v163 offset:50176
	ds_read_b128 v[204:207], v163 offset:51200
	ds_read_b128 v[208:211], v163 offset:52224
	ds_read_b128 v[212:215], v163 offset:53248
	ds_read_b128 v[216:219], v163 offset:54272
	ds_read_b128 v[220:223], v163 offset:55296
	ds_read_b128 v[224:227], v163 offset:56320
	global_load_lds_dwordx4 v[150:151], off
	s_add_i32 m0, s33, 0x2000
	s_add_u32 s44, s44, 0x40080
	v_lshl_add_u64 v[150:151], v[228:229], 0, s[8:9]
	s_addc_u32 s45, s45, 0
	s_add_i32 s33, s34, s52
	global_load_lds_dwordx4 v[150:151], off
	v_lshl_add_u64 v[150:151], s[44:45], 0, v[130:131]
	s_mov_b32 m0, s33
	s_nop 0
	global_load_lds_dwordx4 v[150:151], off
	v_lshl_add_u64 v[150:151], s[44:45], 0, v[134:135]
	s_add_i32 m0, s33, 0x2000
	s_nop 0
	global_load_lds_dwordx4 v[150:151], off
	v_lshl_add_u64 v[150:151], v[230:231], 0, s[8:9]
	s_mov_b32 m0, s60
	s_nop 0
	global_load_lds_dwordx4 v[150:151], off
	v_lshl_add_u64 v[150:151], v[232:233], 0, s[8:9]
	s_mov_b32 m0, s61
	s_nop 0
	global_load_lds_dwordx4 v[150:151], off
	s_waitcnt vmcnt(8)
	s_waitcnt lgkmcnt(0)
	s_barrier
	s_waitcnt lgkmcnt(0)
	v_mfma_f32_16x16x32_bf16 v[60:63], v[146:149], v[196:199], v[60:63]
	v_mfma_f32_16x16x32_bf16 v[56:59], v[168:171], v[196:199], v[56:59]
	v_mfma_f32_16x16x32_bf16 v[44:47], v[146:149], v[204:207], v[44:47]
	v_mfma_f32_16x16x32_bf16 v[40:43], v[168:171], v[204:207], v[40:43]
	v_mfma_f32_16x16x32_bf16 v[28:31], v[146:149], v[212:215], v[28:31]
	v_mfma_f32_16x16x32_bf16 v[24:27], v[168:171], v[212:215], v[24:27]
	v_mfma_f32_16x16x32_bf16 v[12:15], v[146:149], v[220:223], v[12:15]
	v_mfma_f32_16x16x32_bf16 v[8:11], v[168:171], v[220:223], v[8:11]
	v_mfma_f32_16x16x32_bf16 v[60:63], v[164:167], v[200:203], v[60:63]
	v_mfma_f32_16x16x32_bf16 v[56:59], v[176:179], v[200:203], v[56:59]
	v_mfma_f32_16x16x32_bf16 v[44:47], v[164:167], v[208:211], v[44:47]
	v_mfma_f32_16x16x32_bf16 v[40:43], v[176:179], v[208:211], v[40:43]
	v_mfma_f32_16x16x32_bf16 v[28:31], v[164:167], v[216:219], v[28:31]
	v_mfma_f32_16x16x32_bf16 v[24:27], v[176:179], v[216:219], v[24:27]
	v_mfma_f32_16x16x32_bf16 v[12:15], v[164:167], v[224:227], v[12:15]
	v_mfma_f32_16x16x32_bf16 v[8:11], v[176:179], v[224:227], v[8:11]
	v_mfma_f32_16x16x32_bf16 v[52:55], v[180:183], v[196:199], v[52:55]
	v_mfma_f32_16x16x32_bf16 v[48:51], v[188:191], v[196:199], v[48:51]
	v_mfma_f32_16x16x32_bf16 v[36:39], v[180:183], v[204:207], v[36:39]
	v_mfma_f32_16x16x32_bf16 v[32:35], v[188:191], v[204:207], v[32:35]
	v_mfma_f32_16x16x32_bf16 v[20:23], v[180:183], v[212:215], v[20:23]
	v_mfma_f32_16x16x32_bf16 v[16:19], v[188:191], v[212:215], v[16:19]
	v_mfma_f32_16x16x32_bf16 v[4:7], v[180:183], v[220:223], v[4:7]
	v_mfma_f32_16x16x32_bf16 v[0:3], v[188:191], v[220:223], v[0:3]
	v_mfma_f32_16x16x32_bf16 v[52:55], v[184:187], v[200:203], v[52:55]
	v_mfma_f32_16x16x32_bf16 v[48:51], v[192:195], v[200:203], v[48:51]
	v_mfma_f32_16x16x32_bf16 v[36:39], v[184:187], v[208:211], v[36:39]
	v_mfma_f32_16x16x32_bf16 v[32:35], v[192:195], v[208:211], v[32:35]
	v_mfma_f32_16x16x32_bf16 v[20:23], v[184:187], v[216:219], v[20:23]
	v_mfma_f32_16x16x32_bf16 v[16:19], v[192:195], v[216:219], v[16:19]
	v_mfma_f32_16x16x32_bf16 v[4:7], v[184:187], v[224:227], v[4:7]
	v_mfma_f32_16x16x32_bf16 v[0:3], v[192:195], v[224:227], v[0:3]
	s_barrier
	s_add_i32 s72, s72, 2
	s_add_u32 s42, s42, 0x100
	s_addc_u32 s43, s43, 0
	s_add_u32 s70, s70, 0x100
	s_addc_u32 s71, s71, 0
	s_cmp_gt_u32 s72, 13
	s_cbranch_scc0 .LBB0_1944
	s_and_b64 vcc, exec, s[10:11]
	s_cbranch_vccz .LBB0_1947
	s_barrier

.LBB0_1960:
	ds_read_b128 v[146:149], v137
	ds_read_b128 v[158:161], v137 offset:1024
	ds_read_b128 v[162:165], v137 offset:2048
	ds_read_b128 v[166:169], v137 offset:3072
	ds_read_b128 v[176:179], v152
	ds_read_b128 v[180:183], v152 offset:1024
	ds_read_b128 v[184:187], v152 offset:2048
	ds_read_b128 v[188:191], v152 offset:3072
	s_add_u32 s33, s46, 0xfffc0080
	s_addc_u32 s34, s47, -1
	s_cmp_eq_u32 s73, 12
	s_cselect_b32 s57, s31, s34
	s_cselect_b32 s56, s69, s33
	s_cselect_b32 s51, s29, s72
	s_cselect_b32 s50, s70, s71
	v_lshl_add_u64 v[150:151], s[46:47], 0, v[138:139]
	s_add_i32 m0, s45, 0xc000
	ds_read_b128 v[192:195], v153
	ds_read_b128 v[196:199], v153 offset:1024
	ds_read_b128 v[200:203], v153 offset:2048
	ds_read_b128 v[204:207], v153 offset:3072
	ds_read_b128 v[208:211], v153 offset:4096
	ds_read_b128 v[212:215], v153 offset:5120
	ds_read_b128 v[216:219], v153 offset:6144
	ds_read_b128 v[220:223], v153 offset:7168
	global_load_lds_dwordx4 v[150:151], off
	v_lshl_add_u64 v[150:151], s[46:47], 0, v[140:141]
	s_add_i32 m0, s45, 0xe000
	s_nop 0
	global_load_lds_dwordx4 v[150:151], off
	s_waitcnt vmcnt(8)
	s_waitcnt lgkmcnt(0)
	s_barrier
	s_waitcnt lgkmcnt(0)
	v_mfma_f32_16x16x32_bf16 v[124:127], v[146:149], v[192:195], v[124:127]
	v_mfma_f32_16x16x32_bf16 v[120:123], v[162:165], v[192:195], v[120:123]
	v_mfma_f32_16x16x32_bf16 v[108:111], v[146:149], v[200:203], v[108:111]
	v_mfma_f32_16x16x32_bf16 v[104:107], v[162:165], v[200:203], v[104:107]
	v_mfma_f32_16x16x32_bf16 v[92:95], v[146:149], v[208:211], v[92:95]
	v_mfma_f32_16x16x32_bf16 v[88:91], v[162:165], v[208:211], v[88:91]
	v_mfma_f32_16x16x32_bf16 v[76:79], v[146:149], v[216:219], v[76:79]
	v_mfma_f32_16x16x32_bf16 v[72:75], v[162:165], v[216:219], v[72:75]
	v_mfma_f32_16x16x32_bf16 v[124:127], v[158:161], v[196:199], v[124:127]
	v_mfma_f32_16x16x32_bf16 v[120:123], v[166:169], v[196:199], v[120:123]
	v_mfma_f32_16x16x32_bf16 v[108:111], v[158:161], v[204:207], v[108:111]
	v_mfma_f32_16x16x32_bf16 v[104:107], v[166:169], v[204:207], v[104:107]
	v_mfma_f32_16x16x32_bf16 v[92:95], v[158:161], v[212:215], v[92:95]
	v_mfma_f32_16x16x32_bf16 v[88:91], v[166:169], v[212:215], v[88:91]
	v_mfma_f32_16x16x32_bf16 v[76:79], v[158:161], v[220:223], v[76:79]
	v_mfma_f32_16x16x32_bf16 v[72:75], v[166:169], v[220:223], v[72:75]
	v_mfma_f32_16x16x32_bf16 v[116:119], v[176:179], v[192:195], v[116:119]
	v_mfma_f32_16x16x32_bf16 v[112:115], v[184:187], v[192:195], v[112:115]
	v_mfma_f32_16x16x32_bf16 v[100:103], v[176:179], v[200:203], v[100:103]
	v_mfma_f32_16x16x32_bf16 v[96:99], v[184:187], v[200:203], v[96:99]
	v_mfma_f32_16x16x32_bf16 v[84:87], v[176:179], v[208:211], v[84:87]
	v_mfma_f32_16x16x32_bf16 v[80:83], v[184:187], v[208:211], v[80:83]
	v_mfma_f32_16x16x32_bf16 v[68:71], v[176:179], v[216:219], v[68:71]
	v_mfma_f32_16x16x32_bf16 v[64:67], v[184:187], v[216:219], v[64:67]
	v_mfma_f32_16x16x32_bf16 v[116:119], v[180:183], v[196:199], v[116:119]
	v_mfma_f32_16x16x32_bf16 v[112:115], v[188:191], v[196:199], v[112:115]
	v_mfma_f32_16x16x32_bf16 v[100:103], v[180:183], v[204:207], v[100:103]
	v_mfma_f32_16x16x32_bf16 v[96:99], v[188:191], v[204:207], v[96:99]
	v_mfma_f32_16x16x32_bf16 v[84:87], v[180:183], v[212:215], v[84:87]
	v_mfma_f32_16x16x32_bf16 v[80:83], v[188:191], v[212:215], v[80:83]
	v_mfma_f32_16x16x32_bf16 v[68:71], v[180:183], v[220:223], v[68:71]
	v_mfma_f32_16x16x32_bf16 v[64:67], v[188:191], v[220:223], v[64:67]
	s_barrier
	s_add_i32 s33, s66, s52
	v_lshl_add_u64 v[150:151], s[50:51], 0, v[130:131]
	s_mov_b32 m0, s33
	ds_read_b128 v[192:195], v153 offset:16384
	ds_read_b128 v[196:199], v153 offset:17408
	ds_read_b128 v[200:203], v153 offset:18432
	ds_read_b128 v[204:207], v153 offset:19456
	ds_read_b128 v[208:211], v153 offset:20480
	ds_read_b128 v[212:215], v153 offset:21504
	ds_read_b128 v[216:219], v153 offset:22528
	ds_read_b128 v[220:223], v153 offset:23552
	global_load_lds_dwordx4 v[150:151], off
	s_add_i32 m0, s33, 0x2000
	s_add_u32 s74, s50, 0x40000
	v_lshl_add_u64 v[170:171], s[50:51], 0, v[134:135]
	s_addc_u32 s75, s51, 0
	s_add_i32 s33, s67, s52
	global_load_lds_dwordx4 v[170:171], off
	v_lshl_add_u64 v[224:225], s[74:75], 0, v[130:131]
	s_mov_b32 m0, s33
	v_lshl_add_u64 v[226:227], s[56:57], 0, v[132:133]
	global_load_lds_dwordx4 v[224:225], off
	v_lshl_add_u64 v[224:225], s[74:75], 0, v[134:135]
	s_add_i32 m0, s33, 0x2000
	s_nop 0
	global_load_lds_dwordx4 v[224:225], off
	v_lshl_add_u64 v[224:225], s[56:57], 0, v[128:129]
	s_mov_b32 m0, s45
	s_nop 0
	global_load_lds_dwordx4 v[224:225], off
	s_mov_b32 m0, s55
	s_nop 0
	global_load_lds_dwordx4 v[226:227], off
	s_waitcnt vmcnt(8)
	s_waitcnt lgkmcnt(0)
	s_barrier
	s_waitcnt lgkmcnt(0)
	v_mfma_f32_16x16x32_bf16 v[60:63], v[146:149], v[192:195], v[60:63]
	v_mfma_f32_16x16x32_bf16 v[56:59], v[162:165], v[192:195], v[56:59]
	v_mfma_f32_16x16x32_bf16 v[44:47], v[146:149], v[200:203], v[44:47]
	v_mfma_f32_16x16x32_bf16 v[40:43], v[162:165], v[200:203], v[40:43]
	v_mfma_f32_16x16x32_bf16 v[28:31], v[146:149], v[208:211], v[28:31]
	v_mfma_f32_16x16x32_bf16 v[24:27], v[162:165], v[208:211], v[24:27]
	v_mfma_f32_16x16x32_bf16 v[12:15], v[146:149], v[216:219], v[12:15]
	v_mfma_f32_16x16x32_bf16 v[8:11], v[162:165], v[216:219], v[8:11]
	v_mfma_f32_16x16x32_bf16 v[60:63], v[158:161], v[196:199], v[60:63]
	v_mfma_f32_16x16x32_bf16 v[56:59], v[166:169], v[196:199], v[56:59]
	v_mfma_f32_16x16x32_bf16 v[44:47], v[158:161], v[204:207], v[44:47]
	v_mfma_f32_16x16x32_bf16 v[40:43], v[166:169], v[204:207], v[40:43]
	v_mfma_f32_16x16x32_bf16 v[28:31], v[158:161], v[212:215], v[28:31]
	v_mfma_f32_16x16x32_bf16 v[24:27], v[166:169], v[212:215], v[24:27]
	v_mfma_f32_16x16x32_bf16 v[12:15], v[158:161], v[220:223], v[12:15]
	v_mfma_f32_16x16x32_bf16 v[8:11], v[166:169], v[220:223], v[8:11]
	v_mfma_f32_16x16x32_bf16 v[52:55], v[176:179], v[192:195], v[52:55]
	v_mfma_f32_16x16x32_bf16 v[48:51], v[184:187], v[192:195], v[48:51]
	v_mfma_f32_16x16x32_bf16 v[36:39], v[176:179], v[200:203], v[36:39]
	v_mfma_f32_16x16x32_bf16 v[32:35], v[184:187], v[200:203], v[32:35]
	v_mfma_f32_16x16x32_bf16 v[20:23], v[176:179], v[208:211], v[20:23]
	v_mfma_f32_16x16x32_bf16 v[16:19], v[184:187], v[208:211], v[16:19]
	v_mfma_f32_16x16x32_bf16 v[4:7], v[176:179], v[216:219], v[4:7]
	v_mfma_f32_16x16x32_bf16 v[0:3], v[184:187], v[216:219], v[0:3]
	v_mfma_f32_16x16x32_bf16 v[52:55], v[180:183], v[196:199], v[52:55]
	v_mfma_f32_16x16x32_bf16 v[48:51], v[188:191], v[196:199], v[48:51]
	v_mfma_f32_16x16x32_bf16 v[36:39], v[180:183], v[204:207], v[36:39]
	v_mfma_f32_16x16x32_bf16 v[32:35], v[188:191], v[204:207], v[32:35]
	v_mfma_f32_16x16x32_bf16 v[20:23], v[180:183], v[212:215], v[20:23]
	v_mfma_f32_16x16x32_bf16 v[16:19], v[188:191], v[212:215], v[16:19]
	v_mfma_f32_16x16x32_bf16 v[4:7], v[180:183], v[220:223], v[4:7]
	v_mfma_f32_16x16x32_bf16 v[0:3], v[188:191], v[220:223], v[0:3]
	s_barrier
	s_add_i32 s33, 0, 0x18000
	v_add_u32_e32 v155, s33, v156
	s_add_i32 s34, 0, 0x1c000
	ds_read_b128 v[146:149], v155
	ds_read_b128 v[158:161], v155 offset:1024
	ds_read_b128 v[162:165], v155 offset:2048
	ds_read_b128 v[166:169], v155 offset:3072
	v_add_u32_e32 v155, s34, v156
	ds_read_b128 v[176:179], v155
	ds_read_b128 v[180:183], v155 offset:1024
	ds_read_b128 v[184:187], v155 offset:2048
	ds_read_b128 v[188:191], v155 offset:3072
	s_add_u32 s56, s56, 0x40000
	s_addc_u32 s57, s57, 0
	s_mov_b32 m0, s58
	v_lshl_add_u64 v[228:229], s[56:57], 0, v[128:129]
	ds_read_b128 v[192:195], v153 offset:32768
	ds_read_b128 v[196:199], v153 offset:33792
	ds_read_b128 v[200:203], v153 offset:34816
	ds_read_b128 v[204:207], v153 offset:35840
	ds_read_b128 v[208:211], v153 offset:36864
	ds_read_b128 v[212:215], v153 offset:37888
	ds_read_b128 v[216:219], v153 offset:38912
	ds_read_b128 v[220:223], v153 offset:39936
	global_load_lds_dwordx4 v[228:229], off
	v_lshl_add_u64 v[228:229], s[56:57], 0, v[132:133]
	s_mov_b32 m0, s59
	s_nop 0
	global_load_lds_dwordx4 v[228:229], off
	s_waitcnt vmcnt(8)
	s_waitcnt lgkmcnt(0)
	s_barrier
	s_waitcnt lgkmcnt(0)
	v_mfma_f32_16x16x32_bf16 v[124:127], v[146:149], v[192:195], v[124:127]
	v_mfma_f32_16x16x32_bf16 v[120:123], v[162:165], v[192:195], v[120:123]
	v_mfma_f32_16x16x32_bf16 v[108:111], v[146:149], v[200:203], v[108:111]
	v_mfma_f32_16x16x32_bf16 v[104:107], v[162:165], v[200:203], v[104:107]
	v_mfma_f32_16x16x32_bf16 v[92:95], v[146:149], v[208:211], v[92:95]
	v_mfma_f32_16x16x32_bf16 v[88:91], v[162:165], v[208:211], v[88:91]
	v_mfma_f32_16x16x32_bf16 v[76:79], v[146:149], v[216:219], v[76:79]
	v_mfma_f32_16x16x32_bf16 v[72:75], v[162:165], v[216:219], v[72:75]
	v_mfma_f32_16x16x32_bf16 v[124:127], v[158:161], v[196:199], v[124:127]
	v_mfma_f32_16x16x32_bf16 v[120:123], v[166:169], v[196:199], v[120:123]
	v_mfma_f32_16x16x32_bf16 v[108:111], v[158:161], v[204:207], v[108:111]
	v_mfma_f32_16x16x32_bf16 v[104:107], v[166:169], v[204:207], v[104:107]
	v_mfma_f32_16x16x32_bf16 v[92:95], v[158:161], v[212:215], v[92:95]
	v_mfma_f32_16x16x32_bf16 v[88:91], v[166:169], v[212:215], v[88:91]
	v_mfma_f32_16x16x32_bf16 v[76:79], v[158:161], v[220:223], v[76:79]
	v_mfma_f32_16x16x32_bf16 v[72:75], v[166:169], v[220:223], v[72:75]
	v_mfma_f32_16x16x32_bf16 v[116:119], v[176:179], v[192:195], v[116:119]
	v_mfma_f32_16x16x32_bf16 v[112:115], v[184:187], v[192:195], v[112:115]
	v_mfma_f32_16x16x32_bf16 v[100:103], v[176:179], v[200:203], v[100:103]
	v_mfma_f32_16x16x32_bf16 v[96:99], v[184:187], v[200:203], v[96:99]
	v_mfma_f32_16x16x32_bf16 v[84:87], v[176:179], v[208:211], v[84:87]
	v_mfma_f32_16x16x32_bf16 v[80:83], v[184:187], v[208:211], v[80:83]
	v_mfma_f32_16x16x32_bf16 v[68:71], v[176:179], v[216:219], v[68:71]
	v_mfma_f32_16x16x32_bf16 v[64:67], v[184:187], v[216:219], v[64:67]
	v_mfma_f32_16x16x32_bf16 v[116:119], v[180:183], v[196:199], v[116:119]
	v_mfma_f32_16x16x32_bf16 v[112:115], v[188:191], v[196:199], v[112:115]
	v_mfma_f32_16x16x32_bf16 v[100:103], v[180:183], v[204:207], v[100:103]
	v_mfma_f32_16x16x32_bf16 v[96:99], v[188:191], v[204:207], v[96:99]
	v_mfma_f32_16x16x32_bf16 v[84:87], v[180:183], v[212:215], v[84:87]
	v_mfma_f32_16x16x32_bf16 v[80:83], v[188:191], v[212:215], v[80:83]
	v_mfma_f32_16x16x32_bf16 v[68:71], v[180:183], v[220:223], v[68:71]
	v_mfma_f32_16x16x32_bf16 v[64:67], v[188:191], v[220:223], v[64:67]
	s_barrier
	s_add_i32 s33, s33, s52
	v_lshl_add_u64 v[150:151], v[150:151], 0, s[6:7]
	s_mov_b32 m0, s33
	ds_read_b128 v[192:195], v153 offset:49152
	ds_read_b128 v[196:199], v153 offset:50176
	ds_read_b128 v[200:203], v153 offset:51200
	ds_read_b128 v[204:207], v153 offset:52224
	ds_read_b128 v[208:211], v153 offset:53248
	ds_read_b128 v[212:215], v153 offset:54272
	ds_read_b128 v[216:219], v153 offset:55296
	ds_read_b128 v[220:223], v153 offset:56320
	global_load_lds_dwordx4 v[150:151], off
	s_add_i32 m0, s33, 0x2000
	s_add_u32 s50, s50, 0x40080
	v_lshl_add_u64 v[150:151], v[170:171], 0, s[6:7]
	s_addc_u32 s51, s51, 0
	s_add_i32 s33, s34, s52
	global_load_lds_dwordx4 v[150:151], off
	v_lshl_add_u64 v[150:151], s[50:51], 0, v[130:131]
	s_mov_b32 m0, s33
	s_nop 0
	global_load_lds_dwordx4 v[150:151], off
	v_lshl_add_u64 v[150:151], s[50:51], 0, v[134:135]
	s_add_i32 m0, s33, 0x2000
	s_nop 0
	global_load_lds_dwordx4 v[150:151], off
	v_lshl_add_u64 v[150:151], v[224:225], 0, s[6:7]
	s_mov_b32 m0, s61
	s_nop 0
	global_load_lds_dwordx4 v[150:151], off
	v_lshl_add_u64 v[150:151], v[226:227], 0, s[6:7]
	s_mov_b32 m0, s62
	s_nop 0
	global_load_lds_dwordx4 v[150:151], off
	s_waitcnt vmcnt(8)
	s_waitcnt lgkmcnt(0)
	s_barrier
	s_waitcnt lgkmcnt(0)
	v_mfma_f32_16x16x32_bf16 v[60:63], v[146:149], v[192:195], v[60:63]
	v_mfma_f32_16x16x32_bf16 v[56:59], v[162:165], v[192:195], v[56:59]
	v_mfma_f32_16x16x32_bf16 v[44:47], v[146:149], v[200:203], v[44:47]
	v_mfma_f32_16x16x32_bf16 v[40:43], v[162:165], v[200:203], v[40:43]
	v_mfma_f32_16x16x32_bf16 v[28:31], v[146:149], v[208:211], v[28:31]
	v_mfma_f32_16x16x32_bf16 v[24:27], v[162:165], v[208:211], v[24:27]
	v_mfma_f32_16x16x32_bf16 v[12:15], v[146:149], v[216:219], v[12:15]
	v_mfma_f32_16x16x32_bf16 v[8:11], v[162:165], v[216:219], v[8:11]
	v_mfma_f32_16x16x32_bf16 v[60:63], v[158:161], v[196:199], v[60:63]
	v_mfma_f32_16x16x32_bf16 v[56:59], v[166:169], v[196:199], v[56:59]
	v_mfma_f32_16x16x32_bf16 v[44:47], v[158:161], v[204:207], v[44:47]
	v_mfma_f32_16x16x32_bf16 v[40:43], v[166:169], v[204:207], v[40:43]
	v_mfma_f32_16x16x32_bf16 v[28:31], v[158:161], v[212:215], v[28:31]
	v_mfma_f32_16x16x32_bf16 v[24:27], v[166:169], v[212:215], v[24:27]
	v_mfma_f32_16x16x32_bf16 v[12:15], v[158:161], v[220:223], v[12:15]
	v_mfma_f32_16x16x32_bf16 v[8:11], v[166:169], v[220:223], v[8:11]
	v_mfma_f32_16x16x32_bf16 v[52:55], v[176:179], v[192:195], v[52:55]
	v_mfma_f32_16x16x32_bf16 v[48:51], v[184:187], v[192:195], v[48:51]
	v_mfma_f32_16x16x32_bf16 v[36:39], v[176:179], v[200:203], v[36:39]
	v_mfma_f32_16x16x32_bf16 v[32:35], v[184:187], v[200:203], v[32:35]
	v_mfma_f32_16x16x32_bf16 v[20:23], v[176:179], v[208:211], v[20:23]
	v_mfma_f32_16x16x32_bf16 v[16:19], v[184:187], v[208:211], v[16:19]
	v_mfma_f32_16x16x32_bf16 v[4:7], v[176:179], v[216:219], v[4:7]
	v_mfma_f32_16x16x32_bf16 v[0:3], v[184:187], v[216:219], v[0:3]
	v_mfma_f32_16x16x32_bf16 v[52:55], v[180:183], v[196:199], v[52:55]
	v_mfma_f32_16x16x32_bf16 v[48:51], v[188:191], v[196:199], v[48:51]
	v_mfma_f32_16x16x32_bf16 v[36:39], v[180:183], v[204:207], v[36:39]
	v_mfma_f32_16x16x32_bf16 v[32:35], v[188:191], v[204:207], v[32:35]
	v_mfma_f32_16x16x32_bf16 v[20:23], v[180:183], v[212:215], v[20:23]
	v_mfma_f32_16x16x32_bf16 v[16:19], v[188:191], v[212:215], v[16:19]
	v_mfma_f32_16x16x32_bf16 v[4:7], v[180:183], v[220:223], v[4:7]
	v_mfma_f32_16x16x32_bf16 v[0:3], v[188:191], v[220:223], v[0:3]
	s_barrier
	s_add_i32 s73, s73, 2
	s_add_u32 s46, s46, 0x100
	s_addc_u32 s47, s47, 0
	s_add_u32 s71, s71, 0x100
	s_addc_u32 s72, s72, 0
	s_cmp_gt_u32 s73, 13
	s_cbranch_scc0 .LBB0_1960
	s_and_b64 vcc, exec, s[8:9]
	s_cbranch_vccz .LBB0_1963
	s_barrier

.LBB0_2029:
	ds_read_b128 v[72:75], v185
	ds_read_b128 v[76:79], v185 offset:1024
	ds_read_b128 v[84:87], v185 offset:2048
	ds_read_b128 v[92:95], v185 offset:3072
	ds_read_b128 v[96:99], v186
	ds_read_b128 v[100:103], v186 offset:1024
	ds_read_b128 v[104:107], v186 offset:2048
	ds_read_b128 v[108:111], v186 offset:3072
	s_add_u32 s28, s26, 0xfff80080
	s_addc_u32 s29, s27, -1
	s_cmp_eq_u32 s61, 28
	s_cselect_b32 s31, s3, s29
	s_cselect_b32 s30, s19, s28
	s_cselect_b32 s29, s17, s60
	s_cselect_b32 s28, s58, s59
	v_lshl_add_u64 v[218:219], s[26:27], 0, v[168:169]
	s_add_i32 m0, s25, 0xc000
	ds_read_b128 v[180:183], v187
	ds_read_b128 v[190:193], v187 offset:1024
	ds_read_b128 v[194:197], v187 offset:2048
	ds_read_b128 v[198:201], v187 offset:3072
	ds_read_b128 v[202:205], v187 offset:4096
	ds_read_b128 v[206:209], v187 offset:5120
	ds_read_b128 v[210:213], v187 offset:6144
	ds_read_b128 v[214:217], v187 offset:7168
	global_load_lds_dwordx4 v[218:219], off
	v_lshl_add_u64 v[218:219], s[26:27], 0, v[170:171]
	s_add_i32 m0, s25, 0xe000
	s_nop 0
	global_load_lds_dwordx4 v[218:219], off
	s_waitcnt vmcnt(8)
	s_waitcnt lgkmcnt(0)
	s_barrier
	s_waitcnt lgkmcnt(0)
	v_mfma_f32_16x16x32_bf16 v[156:159], v[72:75], v[180:183], v[156:159]
	v_mfma_f32_16x16x32_bf16 v[152:155], v[84:87], v[180:183], v[152:155]
	v_mfma_f32_16x16x32_bf16 v[140:143], v[72:75], v[194:197], v[140:143]
	v_mfma_f32_16x16x32_bf16 v[136:139], v[84:87], v[194:197], v[136:139]
	v_mfma_f32_16x16x32_bf16 v[124:127], v[72:75], v[202:205], v[124:127]
	v_mfma_f32_16x16x32_bf16 v[120:123], v[84:87], v[202:205], v[120:123]
	v_mfma_f32_16x16x32_bf16 v[88:91], v[72:75], v[210:213], v[88:91]
	v_mfma_f32_16x16x32_bf16 v[80:83], v[84:87], v[210:213], v[80:83]
	v_mfma_f32_16x16x32_bf16 v[156:159], v[76:79], v[190:193], v[156:159]
	v_mfma_f32_16x16x32_bf16 v[152:155], v[92:95], v[190:193], v[152:155]
	v_mfma_f32_16x16x32_bf16 v[140:143], v[76:79], v[198:201], v[140:143]
	v_mfma_f32_16x16x32_bf16 v[136:139], v[92:95], v[198:201], v[136:139]
	v_mfma_f32_16x16x32_bf16 v[124:127], v[76:79], v[206:209], v[124:127]
	v_mfma_f32_16x16x32_bf16 v[120:123], v[92:95], v[206:209], v[120:123]
	v_mfma_f32_16x16x32_bf16 v[88:91], v[76:79], v[214:217], v[88:91]
	v_mfma_f32_16x16x32_bf16 v[80:83], v[92:95], v[214:217], v[80:83]
	v_mfma_f32_16x16x32_bf16 v[148:151], v[96:99], v[180:183], v[148:151]
	v_mfma_f32_16x16x32_bf16 v[144:147], v[104:107], v[180:183], v[144:147]
	v_mfma_f32_16x16x32_bf16 v[132:135], v[96:99], v[194:197], v[132:135]
	v_mfma_f32_16x16x32_bf16 v[128:131], v[104:107], v[194:197], v[128:131]
	v_mfma_f32_16x16x32_bf16 v[116:119], v[96:99], v[202:205], v[116:119]
	v_mfma_f32_16x16x32_bf16 v[112:115], v[104:107], v[202:205], v[112:115]
	v_mfma_f32_16x16x32_bf16 v[68:71], v[96:99], v[210:213], v[68:71]
	v_mfma_f32_16x16x32_bf16 v[64:67], v[104:107], v[210:213], v[64:67]
	v_mfma_f32_16x16x32_bf16 v[148:151], v[100:103], v[190:193], v[148:151]
	v_mfma_f32_16x16x32_bf16 v[144:147], v[108:111], v[190:193], v[144:147]
	v_mfma_f32_16x16x32_bf16 v[132:135], v[100:103], v[198:201], v[132:135]
	v_mfma_f32_16x16x32_bf16 v[128:131], v[108:111], v[198:201], v[128:131]
	v_mfma_f32_16x16x32_bf16 v[116:119], v[100:103], v[206:209], v[116:119]
	v_mfma_f32_16x16x32_bf16 v[112:115], v[108:111], v[206:209], v[112:115]
	v_mfma_f32_16x16x32_bf16 v[68:71], v[100:103], v[214:217], v[68:71]
	v_mfma_f32_16x16x32_bf16 v[64:67], v[108:111], v[214:217], v[64:67]
	s_barrier
	s_add_i32 s33, s56, s36
	v_lshl_add_u64 v[218:219], s[28:29], 0, v[162:163]
	s_mov_b32 m0, s33
	ds_read_b128 v[180:183], v187 offset:16384
	ds_read_b128 v[190:193], v187 offset:17408
	ds_read_b128 v[194:197], v187 offset:18432
	ds_read_b128 v[198:201], v187 offset:19456
	ds_read_b128 v[202:205], v187 offset:20480
	ds_read_b128 v[206:209], v187 offset:21504
	ds_read_b128 v[210:213], v187 offset:22528
	ds_read_b128 v[214:217], v187 offset:23552
	global_load_lds_dwordx4 v[218:219], off
	s_add_i32 m0, s33, 0x2000
	s_add_u32 s62, s28, 0x80000
	v_lshl_add_u64 v[220:221], s[28:29], 0, v[166:167]
	s_addc_u32 s63, s29, 0
	s_add_i32 s33, s57, s36
	global_load_lds_dwordx4 v[220:221], off
	v_lshl_add_u64 v[222:223], s[62:63], 0, v[162:163]
	s_mov_b32 m0, s33
	v_lshl_add_u64 v[224:225], s[30:31], 0, v[164:165]
	global_load_lds_dwordx4 v[222:223], off
	v_lshl_add_u64 v[222:223], s[62:63], 0, v[166:167]
	s_add_i32 m0, s33, 0x2000
	s_nop 0
	global_load_lds_dwordx4 v[222:223], off
	v_lshl_add_u64 v[222:223], s[30:31], 0, v[160:161]
	s_mov_b32 m0, s25
	s_nop 0
	global_load_lds_dwordx4 v[222:223], off
	s_mov_b32 m0, s37
	s_nop 0
	global_load_lds_dwordx4 v[224:225], off
	s_waitcnt vmcnt(8)
	s_waitcnt lgkmcnt(0)
	s_barrier
	s_waitcnt lgkmcnt(0)
	v_mfma_f32_16x16x32_bf16 v[60:63], v[72:75], v[180:183], v[60:63]
	v_mfma_f32_16x16x32_bf16 v[56:59], v[84:87], v[180:183], v[56:59]
	v_mfma_f32_16x16x32_bf16 v[44:47], v[72:75], v[194:197], v[44:47]
	v_mfma_f32_16x16x32_bf16 v[40:43], v[84:87], v[194:197], v[40:43]
	v_mfma_f32_16x16x32_bf16 v[28:31], v[72:75], v[202:205], v[28:31]
	v_mfma_f32_16x16x32_bf16 v[24:27], v[84:87], v[202:205], v[24:27]
	v_mfma_f32_16x16x32_bf16 v[12:15], v[72:75], v[210:213], v[12:15]
	v_mfma_f32_16x16x32_bf16 v[8:11], v[84:87], v[210:213], v[8:11]
	v_mfma_f32_16x16x32_bf16 v[60:63], v[76:79], v[190:193], v[60:63]
	v_mfma_f32_16x16x32_bf16 v[56:59], v[92:95], v[190:193], v[56:59]
	v_mfma_f32_16x16x32_bf16 v[44:47], v[76:79], v[198:201], v[44:47]
	v_mfma_f32_16x16x32_bf16 v[40:43], v[92:95], v[198:201], v[40:43]
	v_mfma_f32_16x16x32_bf16 v[28:31], v[76:79], v[206:209], v[28:31]
	v_mfma_f32_16x16x32_bf16 v[24:27], v[92:95], v[206:209], v[24:27]
	v_mfma_f32_16x16x32_bf16 v[12:15], v[76:79], v[214:217], v[12:15]
	v_mfma_f32_16x16x32_bf16 v[8:11], v[92:95], v[214:217], v[8:11]
	v_mfma_f32_16x16x32_bf16 v[52:55], v[96:99], v[180:183], v[52:55]
	v_mfma_f32_16x16x32_bf16 v[48:51], v[104:107], v[180:183], v[48:51]
	v_mfma_f32_16x16x32_bf16 v[36:39], v[96:99], v[194:197], v[36:39]
	v_mfma_f32_16x16x32_bf16 v[32:35], v[104:107], v[194:197], v[32:35]
	v_mfma_f32_16x16x32_bf16 v[20:23], v[96:99], v[202:205], v[20:23]
	v_mfma_f32_16x16x32_bf16 v[16:19], v[104:107], v[202:205], v[16:19]
	v_mfma_f32_16x16x32_bf16 v[4:7], v[96:99], v[210:213], v[4:7]
	v_mfma_f32_16x16x32_bf16 v[0:3], v[104:107], v[210:213], v[0:3]
	v_mfma_f32_16x16x32_bf16 v[52:55], v[100:103], v[190:193], v[52:55]
	v_mfma_f32_16x16x32_bf16 v[48:51], v[108:111], v[190:193], v[48:51]
	v_mfma_f32_16x16x32_bf16 v[36:39], v[100:103], v[198:201], v[36:39]
	v_mfma_f32_16x16x32_bf16 v[32:35], v[108:111], v[198:201], v[32:35]
	v_mfma_f32_16x16x32_bf16 v[20:23], v[100:103], v[206:209], v[20:23]
	v_mfma_f32_16x16x32_bf16 v[16:19], v[108:111], v[206:209], v[16:19]
	v_mfma_f32_16x16x32_bf16 v[4:7], v[100:103], v[214:217], v[4:7]
	v_mfma_f32_16x16x32_bf16 v[0:3], v[108:111], v[214:217], v[0:3]
	s_barrier
	s_add_i32 s33, 0, 0x18000
	s_add_i32 s34, 0, 0x1c000
	v_add_u32_e32 v92, s33, v184
	v_add_u32_e32 v108, s34, v184
	ds_read_b128 v[72:75], v92
	ds_read_b128 v[76:79], v92 offset:1024
	ds_read_b128 v[84:87], v92 offset:2048
	ds_read_b128 v[92:95], v92 offset:3072
	ds_read_b128 v[96:99], v108
	ds_read_b128 v[100:103], v108 offset:1024
	ds_read_b128 v[104:107], v108 offset:2048
	ds_read_b128 v[108:111], v108 offset:3072
	s_add_u32 s30, s30, 0x80000
	s_addc_u32 s31, s31, 0
	s_mov_b32 m0, s42
	v_lshl_add_u64 v[226:227], s[30:31], 0, v[160:161]
	ds_read_b128 v[180:183], v187 offset:32768
	ds_read_b128 v[190:193], v187 offset:33792
	ds_read_b128 v[194:197], v187 offset:34816
	ds_read_b128 v[198:201], v187 offset:35840
	ds_read_b128 v[202:205], v187 offset:36864
	ds_read_b128 v[206:209], v187 offset:37888
	ds_read_b128 v[210:213], v187 offset:38912
	ds_read_b128 v[214:217], v187 offset:39936
	global_load_lds_dwordx4 v[226:227], off
	v_lshl_add_u64 v[226:227], s[30:31], 0, v[164:165]
	s_mov_b32 m0, s43
	s_nop 0
	global_load_lds_dwordx4 v[226:227], off
	s_waitcnt vmcnt(8)
	s_waitcnt lgkmcnt(0)
	s_barrier
	s_waitcnt lgkmcnt(0)
	v_mfma_f32_16x16x32_bf16 v[156:159], v[72:75], v[180:183], v[156:159]
	v_mfma_f32_16x16x32_bf16 v[152:155], v[84:87], v[180:183], v[152:155]
	v_mfma_f32_16x16x32_bf16 v[140:143], v[72:75], v[194:197], v[140:143]
	v_mfma_f32_16x16x32_bf16 v[136:139], v[84:87], v[194:197], v[136:139]
	v_mfma_f32_16x16x32_bf16 v[124:127], v[72:75], v[202:205], v[124:127]
	v_mfma_f32_16x16x32_bf16 v[120:123], v[84:87], v[202:205], v[120:123]
	v_mfma_f32_16x16x32_bf16 v[88:91], v[72:75], v[210:213], v[88:91]
	v_mfma_f32_16x16x32_bf16 v[80:83], v[84:87], v[210:213], v[80:83]
	v_mfma_f32_16x16x32_bf16 v[156:159], v[76:79], v[190:193], v[156:159]
	v_mfma_f32_16x16x32_bf16 v[152:155], v[92:95], v[190:193], v[152:155]
	v_mfma_f32_16x16x32_bf16 v[140:143], v[76:79], v[198:201], v[140:143]
	v_mfma_f32_16x16x32_bf16 v[136:139], v[92:95], v[198:201], v[136:139]
	v_mfma_f32_16x16x32_bf16 v[124:127], v[76:79], v[206:209], v[124:127]
	v_mfma_f32_16x16x32_bf16 v[120:123], v[92:95], v[206:209], v[120:123]
	v_mfma_f32_16x16x32_bf16 v[88:91], v[76:79], v[214:217], v[88:91]
	v_mfma_f32_16x16x32_bf16 v[80:83], v[92:95], v[214:217], v[80:83]
	v_mfma_f32_16x16x32_bf16 v[148:151], v[96:99], v[180:183], v[148:151]
	v_mfma_f32_16x16x32_bf16 v[144:147], v[104:107], v[180:183], v[144:147]
	v_mfma_f32_16x16x32_bf16 v[132:135], v[96:99], v[194:197], v[132:135]
	v_mfma_f32_16x16x32_bf16 v[128:131], v[104:107], v[194:197], v[128:131]
	v_mfma_f32_16x16x32_bf16 v[116:119], v[96:99], v[202:205], v[116:119]
	v_mfma_f32_16x16x32_bf16 v[112:115], v[104:107], v[202:205], v[112:115]
	v_mfma_f32_16x16x32_bf16 v[68:71], v[96:99], v[210:213], v[68:71]
	v_mfma_f32_16x16x32_bf16 v[64:67], v[104:107], v[210:213], v[64:67]
	v_mfma_f32_16x16x32_bf16 v[148:151], v[100:103], v[190:193], v[148:151]
	v_mfma_f32_16x16x32_bf16 v[144:147], v[108:111], v[190:193], v[144:147]
	v_mfma_f32_16x16x32_bf16 v[132:135], v[100:103], v[198:201], v[132:135]
	v_mfma_f32_16x16x32_bf16 v[128:131], v[108:111], v[198:201], v[128:131]
	v_mfma_f32_16x16x32_bf16 v[116:119], v[100:103], v[206:209], v[116:119]
	v_mfma_f32_16x16x32_bf16 v[112:115], v[108:111], v[206:209], v[112:115]
	v_mfma_f32_16x16x32_bf16 v[68:71], v[100:103], v[214:217], v[68:71]
	v_mfma_f32_16x16x32_bf16 v[64:67], v[108:111], v[214:217], v[64:67]
	s_barrier
	s_add_i32 s30, s33, s36
	v_lshl_add_u64 v[218:219], v[218:219], 0, s[8:9]
	s_mov_b32 m0, s30
	ds_read_b128 v[180:183], v187 offset:49152
	ds_read_b128 v[190:193], v187 offset:50176
	ds_read_b128 v[194:197], v187 offset:51200
	ds_read_b128 v[198:201], v187 offset:52224
	ds_read_b128 v[202:205], v187 offset:53248
	ds_read_b128 v[206:209], v187 offset:54272
	ds_read_b128 v[210:213], v187 offset:55296
	ds_read_b128 v[214:217], v187 offset:56320
	global_load_lds_dwordx4 v[218:219], off
	s_add_i32 m0, s30, 0x2000
	s_add_u32 s28, s28, 0x80080
	v_lshl_add_u64 v[218:219], v[220:221], 0, s[8:9]
	s_addc_u32 s29, s29, 0
	s_add_i32 s30, s34, s36
	global_load_lds_dwordx4 v[218:219], off
	v_lshl_add_u64 v[218:219], s[28:29], 0, v[162:163]
	s_mov_b32 m0, s30
	s_nop 0
	global_load_lds_dwordx4 v[218:219], off
	v_lshl_add_u64 v[218:219], s[28:29], 0, v[166:167]
	s_add_i32 m0, s30, 0x2000
	s_nop 0
	global_load_lds_dwordx4 v[218:219], off
	v_lshl_add_u64 v[218:219], v[222:223], 0, s[8:9]
	s_mov_b32 m0, s47
	s_nop 0
	global_load_lds_dwordx4 v[218:219], off
	v_lshl_add_u64 v[218:219], v[224:225], 0, s[8:9]
	s_mov_b32 m0, s48
	s_nop 0
	global_load_lds_dwordx4 v[218:219], off
	s_waitcnt vmcnt(8)
	s_waitcnt lgkmcnt(0)
	s_barrier
	s_waitcnt lgkmcnt(0)
	v_mfma_f32_16x16x32_bf16 v[60:63], v[72:75], v[180:183], v[60:63]
	v_mfma_f32_16x16x32_bf16 v[56:59], v[84:87], v[180:183], v[56:59]
	v_mfma_f32_16x16x32_bf16 v[44:47], v[72:75], v[194:197], v[44:47]
	v_mfma_f32_16x16x32_bf16 v[40:43], v[84:87], v[194:197], v[40:43]
	v_mfma_f32_16x16x32_bf16 v[28:31], v[72:75], v[202:205], v[28:31]
	v_mfma_f32_16x16x32_bf16 v[24:27], v[84:87], v[202:205], v[24:27]
	v_mfma_f32_16x16x32_bf16 v[12:15], v[72:75], v[210:213], v[12:15]
	v_mfma_f32_16x16x32_bf16 v[8:11], v[84:87], v[210:213], v[8:11]
	v_mfma_f32_16x16x32_bf16 v[60:63], v[76:79], v[190:193], v[60:63]
	v_mfma_f32_16x16x32_bf16 v[56:59], v[92:95], v[190:193], v[56:59]
	v_mfma_f32_16x16x32_bf16 v[44:47], v[76:79], v[198:201], v[44:47]
	v_mfma_f32_16x16x32_bf16 v[40:43], v[92:95], v[198:201], v[40:43]
	v_mfma_f32_16x16x32_bf16 v[28:31], v[76:79], v[206:209], v[28:31]
	v_mfma_f32_16x16x32_bf16 v[24:27], v[92:95], v[206:209], v[24:27]
	v_mfma_f32_16x16x32_bf16 v[12:15], v[76:79], v[214:217], v[12:15]
	v_mfma_f32_16x16x32_bf16 v[8:11], v[92:95], v[214:217], v[8:11]
	v_mfma_f32_16x16x32_bf16 v[52:55], v[96:99], v[180:183], v[52:55]
	v_mfma_f32_16x16x32_bf16 v[48:51], v[104:107], v[180:183], v[48:51]
	v_mfma_f32_16x16x32_bf16 v[36:39], v[96:99], v[194:197], v[36:39]
	v_mfma_f32_16x16x32_bf16 v[32:35], v[104:107], v[194:197], v[32:35]
	v_mfma_f32_16x16x32_bf16 v[20:23], v[96:99], v[202:205], v[20:23]
	v_mfma_f32_16x16x32_bf16 v[16:19], v[104:107], v[202:205], v[16:19]
	v_mfma_f32_16x16x32_bf16 v[4:7], v[96:99], v[210:213], v[4:7]
	v_mfma_f32_16x16x32_bf16 v[0:3], v[104:107], v[210:213], v[0:3]
	v_mfma_f32_16x16x32_bf16 v[52:55], v[100:103], v[190:193], v[52:55]
	v_mfma_f32_16x16x32_bf16 v[48:51], v[108:111], v[190:193], v[48:51]
	v_mfma_f32_16x16x32_bf16 v[36:39], v[100:103], v[198:201], v[36:39]
	v_mfma_f32_16x16x32_bf16 v[32:35], v[108:111], v[198:201], v[32:35]
	v_mfma_f32_16x16x32_bf16 v[20:23], v[100:103], v[206:209], v[20:23]
	v_mfma_f32_16x16x32_bf16 v[16:19], v[108:111], v[206:209], v[16:19]
	v_mfma_f32_16x16x32_bf16 v[4:7], v[100:103], v[214:217], v[4:7]
	v_mfma_f32_16x16x32_bf16 v[0:3], v[108:111], v[214:217], v[0:3]
	s_barrier
	s_add_i32 s61, s61, 2
	s_add_u32 s26, s26, 0x100
	s_addc_u32 s27, s27, 0
	s_add_u32 s59, s59, 0x100
	s_addc_u32 s60, s60, 0
	s_cmp_gt_u32 s61, 29
	s_cbranch_scc0 .LBB0_2029
	s_and_b64 vcc, exec, s[10:11]
	s_cbranch_vccz .LBB0_2032
	s_barrier

.LBB0_2112:
	ds_read_b128 v[128:131], v201
	ds_read_b128 v[132:135], v201 offset:1024
	ds_read_b128 v[136:139], v201 offset:2048
	ds_read_b128 v[140:143], v201 offset:3072
	ds_read_b128 v[162:165], v206
	ds_read_b128 v[166:169], v206 offset:1024
	ds_read_b128 v[180:183], v206 offset:2048
	ds_read_b128 v[196:199], v206 offset:3072
	s_add_u32 s26, s0, 0xfff80080
	s_addc_u32 s27, s1, -1
	s_cmp_eq_u32 s61, 28
	s_cselect_b32 s29, s19, s27
	s_cselect_b32 s28, s57, s26
	s_cselect_b32 s27, s17, s60
	s_cselect_b32 s26, s58, s59
	v_lshl_add_u64 v[170:171], s[0:1], 0, v[152:153]
	s_add_i32 m0, s25, 0xc000
	ds_read_b128 v[202:205], v207
	ds_read_b128 v[210:213], v207 offset:1024
	ds_read_b128 v[214:217], v207 offset:2048
	ds_read_b128 v[218:221], v207 offset:3072
	ds_read_b128 v[222:225], v207 offset:4096
	ds_read_b128 v[226:229], v207 offset:5120
	ds_read_b128 v[230:233], v207 offset:6144
	ds_read_b128 v[234:237], v207 offset:7168
	global_load_lds_dwordx4 v[170:171], off
	v_lshl_add_u64 v[170:171], s[0:1], 0, v[154:155]
	s_add_i32 m0, s25, 0xe000
	s_nop 0
	global_load_lds_dwordx4 v[170:171], off
	s_waitcnt vmcnt(8)
	s_waitcnt lgkmcnt(0)
	s_barrier
	s_waitcnt lgkmcnt(0)
	v_mfma_f32_16x16x32_bf16 v[124:127], v[128:131], v[202:205], v[124:127]
	v_mfma_f32_16x16x32_bf16 v[120:123], v[136:139], v[202:205], v[120:123]
	v_mfma_f32_16x16x32_bf16 v[108:111], v[128:131], v[214:217], v[108:111]
	v_mfma_f32_16x16x32_bf16 v[104:107], v[136:139], v[214:217], v[104:107]
	v_mfma_f32_16x16x32_bf16 v[92:95], v[128:131], v[222:225], v[92:95]
	v_mfma_f32_16x16x32_bf16 v[88:91], v[136:139], v[222:225], v[88:91]
	v_mfma_f32_16x16x32_bf16 v[76:79], v[128:131], v[230:233], v[76:79]
	v_mfma_f32_16x16x32_bf16 v[72:75], v[136:139], v[230:233], v[72:75]
	v_mfma_f32_16x16x32_bf16 v[124:127], v[132:135], v[210:213], v[124:127]
	v_mfma_f32_16x16x32_bf16 v[120:123], v[140:143], v[210:213], v[120:123]
	v_mfma_f32_16x16x32_bf16 v[108:111], v[132:135], v[218:221], v[108:111]
	v_mfma_f32_16x16x32_bf16 v[104:107], v[140:143], v[218:221], v[104:107]
	v_mfma_f32_16x16x32_bf16 v[92:95], v[132:135], v[226:229], v[92:95]
	v_mfma_f32_16x16x32_bf16 v[88:91], v[140:143], v[226:229], v[88:91]
	v_mfma_f32_16x16x32_bf16 v[76:79], v[132:135], v[234:237], v[76:79]
	v_mfma_f32_16x16x32_bf16 v[72:75], v[140:143], v[234:237], v[72:75]
	v_mfma_f32_16x16x32_bf16 v[116:119], v[162:165], v[202:205], v[116:119]
	v_mfma_f32_16x16x32_bf16 v[112:115], v[180:183], v[202:205], v[112:115]
	v_mfma_f32_16x16x32_bf16 v[100:103], v[162:165], v[214:217], v[100:103]
	v_mfma_f32_16x16x32_bf16 v[96:99], v[180:183], v[214:217], v[96:99]
	v_mfma_f32_16x16x32_bf16 v[84:87], v[162:165], v[222:225], v[84:87]
	v_mfma_f32_16x16x32_bf16 v[80:83], v[180:183], v[222:225], v[80:83]
	v_mfma_f32_16x16x32_bf16 v[68:71], v[162:165], v[230:233], v[68:71]
	v_mfma_f32_16x16x32_bf16 v[64:67], v[180:183], v[230:233], v[64:67]
	v_mfma_f32_16x16x32_bf16 v[116:119], v[166:169], v[210:213], v[116:119]
	v_mfma_f32_16x16x32_bf16 v[112:115], v[196:199], v[210:213], v[112:115]
	v_mfma_f32_16x16x32_bf16 v[100:103], v[166:169], v[218:221], v[100:103]
	v_mfma_f32_16x16x32_bf16 v[96:99], v[196:199], v[218:221], v[96:99]
	v_mfma_f32_16x16x32_bf16 v[84:87], v[166:169], v[226:229], v[84:87]
	v_mfma_f32_16x16x32_bf16 v[80:83], v[196:199], v[226:229], v[80:83]
	v_mfma_f32_16x16x32_bf16 v[68:71], v[166:169], v[234:237], v[68:71]
	v_mfma_f32_16x16x32_bf16 v[64:67], v[196:199], v[234:237], v[64:67]
	s_barrier
	s_add_i32 s33, s50, s15
	v_lshl_add_u64 v[170:171], s[26:27], 0, v[148:149]
	s_mov_b32 m0, s33
	ds_read_b128 v[202:205], v207 offset:16384
	ds_read_b128 v[210:213], v207 offset:17408
	ds_read_b128 v[214:217], v207 offset:18432
	ds_read_b128 v[218:221], v207 offset:19456
	ds_read_b128 v[222:225], v207 offset:20480
	ds_read_b128 v[226:229], v207 offset:21504
	ds_read_b128 v[230:233], v207 offset:22528
	ds_read_b128 v[234:237], v207 offset:23552
	global_load_lds_dwordx4 v[170:171], off
	s_add_i32 m0, s33, 0x2000
	s_add_u32 s62, s26, 0x80000
	v_lshl_add_u64 v[176:177], s[26:27], 0, v[144:145]
	s_addc_u32 s63, s27, 0
	s_add_i32 s33, s51, s15
	global_load_lds_dwordx4 v[176:177], off
	v_lshl_add_u64 v[188:189], s[62:63], 0, v[148:149]
	s_mov_b32 m0, s33
	v_lshl_add_u64 v[238:239], s[28:29], 0, v[146:147]
	global_load_lds_dwordx4 v[188:189], off
	v_lshl_add_u64 v[188:189], s[62:63], 0, v[144:145]
	s_add_i32 m0, s33, 0x2000
	s_nop 0
	global_load_lds_dwordx4 v[188:189], off
	v_lshl_add_u64 v[188:189], s[28:29], 0, v[150:151]
	s_mov_b32 m0, s25
	s_nop 0
	global_load_lds_dwordx4 v[188:189], off
	s_mov_b32 m0, s36
	s_nop 0
	global_load_lds_dwordx4 v[238:239], off
	s_waitcnt vmcnt(8)
	s_waitcnt lgkmcnt(0)
	s_barrier
	s_waitcnt lgkmcnt(0)
	v_mfma_f32_16x16x32_bf16 v[60:63], v[128:131], v[202:205], v[60:63]
	v_mfma_f32_16x16x32_bf16 v[56:59], v[136:139], v[202:205], v[56:59]
	v_mfma_f32_16x16x32_bf16 v[44:47], v[128:131], v[214:217], v[44:47]
	v_mfma_f32_16x16x32_bf16 v[40:43], v[136:139], v[214:217], v[40:43]
	v_mfma_f32_16x16x32_bf16 v[28:31], v[128:131], v[222:225], v[28:31]
	v_mfma_f32_16x16x32_bf16 v[24:27], v[136:139], v[222:225], v[24:27]
	v_mfma_f32_16x16x32_bf16 v[12:15], v[128:131], v[230:233], v[12:15]
	v_mfma_f32_16x16x32_bf16 v[8:11], v[136:139], v[230:233], v[8:11]
	v_mfma_f32_16x16x32_bf16 v[60:63], v[132:135], v[210:213], v[60:63]
	v_mfma_f32_16x16x32_bf16 v[56:59], v[140:143], v[210:213], v[56:59]
	v_mfma_f32_16x16x32_bf16 v[44:47], v[132:135], v[218:221], v[44:47]
	v_mfma_f32_16x16x32_bf16 v[40:43], v[140:143], v[218:221], v[40:43]
	v_mfma_f32_16x16x32_bf16 v[28:31], v[132:135], v[226:229], v[28:31]
	v_mfma_f32_16x16x32_bf16 v[24:27], v[140:143], v[226:229], v[24:27]
	v_mfma_f32_16x16x32_bf16 v[12:15], v[132:135], v[234:237], v[12:15]
	v_mfma_f32_16x16x32_bf16 v[8:11], v[140:143], v[234:237], v[8:11]
	v_mfma_f32_16x16x32_bf16 v[52:55], v[162:165], v[202:205], v[52:55]
	v_mfma_f32_16x16x32_bf16 v[48:51], v[180:183], v[202:205], v[48:51]
	v_mfma_f32_16x16x32_bf16 v[36:39], v[162:165], v[214:217], v[36:39]
	v_mfma_f32_16x16x32_bf16 v[32:35], v[180:183], v[214:217], v[32:35]
	v_mfma_f32_16x16x32_bf16 v[20:23], v[162:165], v[222:225], v[20:23]
	v_mfma_f32_16x16x32_bf16 v[16:19], v[180:183], v[222:225], v[16:19]
	v_mfma_f32_16x16x32_bf16 v[4:7], v[162:165], v[230:233], v[4:7]
	v_mfma_f32_16x16x32_bf16 v[0:3], v[180:183], v[230:233], v[0:3]
	v_mfma_f32_16x16x32_bf16 v[52:55], v[166:169], v[210:213], v[52:55]
	v_mfma_f32_16x16x32_bf16 v[48:51], v[196:199], v[210:213], v[48:51]
	v_mfma_f32_16x16x32_bf16 v[36:39], v[166:169], v[218:221], v[36:39]
	v_mfma_f32_16x16x32_bf16 v[32:35], v[196:199], v[218:221], v[32:35]
	v_mfma_f32_16x16x32_bf16 v[20:23], v[166:169], v[226:229], v[20:23]
	v_mfma_f32_16x16x32_bf16 v[16:19], v[196:199], v[226:229], v[16:19]
	v_mfma_f32_16x16x32_bf16 v[4:7], v[166:169], v[234:237], v[4:7]
	v_mfma_f32_16x16x32_bf16 v[0:3], v[196:199], v[234:237], v[0:3]
	s_barrier
	s_add_i32 s33, 0, 0x18000
	s_add_i32 s34, 0, 0x1c000
	v_add_u32_e32 v140, s33, v187
	v_add_u32_e32 v161, s34, v187
	ds_read_b128 v[128:131], v140
	ds_read_b128 v[132:135], v140 offset:1024
	ds_read_b128 v[136:139], v140 offset:2048
	ds_read_b128 v[140:143], v140 offset:3072
	ds_read_b128 v[162:165], v161
	ds_read_b128 v[166:169], v161 offset:1024
	ds_read_b128 v[180:183], v161 offset:2048
	ds_read_b128 v[196:199], v161 offset:3072
	s_add_u32 s28, s28, 0x80000
	s_addc_u32 s29, s29, 0
	s_mov_b32 m0, s37
	v_lshl_add_u64 v[240:241], s[28:29], 0, v[150:151]
	ds_read_b128 v[202:205], v207 offset:32768
	ds_read_b128 v[210:213], v207 offset:33792
	ds_read_b128 v[214:217], v207 offset:34816
	ds_read_b128 v[218:221], v207 offset:35840
	ds_read_b128 v[222:225], v207 offset:36864
	ds_read_b128 v[226:229], v207 offset:37888
	ds_read_b128 v[230:233], v207 offset:38912
	ds_read_b128 v[234:237], v207 offset:39936
	global_load_lds_dwordx4 v[240:241], off
	v_lshl_add_u64 v[240:241], s[28:29], 0, v[146:147]
	s_mov_b32 m0, s42
	s_nop 0
	global_load_lds_dwordx4 v[240:241], off
	s_waitcnt vmcnt(8)
	s_waitcnt lgkmcnt(0)
	s_barrier
	s_waitcnt lgkmcnt(0)
	v_mfma_f32_16x16x32_bf16 v[124:127], v[128:131], v[202:205], v[124:127]
	v_mfma_f32_16x16x32_bf16 v[120:123], v[136:139], v[202:205], v[120:123]
	v_mfma_f32_16x16x32_bf16 v[108:111], v[128:131], v[214:217], v[108:111]
	v_mfma_f32_16x16x32_bf16 v[104:107], v[136:139], v[214:217], v[104:107]
	v_mfma_f32_16x16x32_bf16 v[92:95], v[128:131], v[222:225], v[92:95]
	v_mfma_f32_16x16x32_bf16 v[88:91], v[136:139], v[222:225], v[88:91]
	v_mfma_f32_16x16x32_bf16 v[76:79], v[128:131], v[230:233], v[76:79]
	v_mfma_f32_16x16x32_bf16 v[72:75], v[136:139], v[230:233], v[72:75]
	v_mfma_f32_16x16x32_bf16 v[124:127], v[132:135], v[210:213], v[124:127]
	v_mfma_f32_16x16x32_bf16 v[120:123], v[140:143], v[210:213], v[120:123]
	v_mfma_f32_16x16x32_bf16 v[108:111], v[132:135], v[218:221], v[108:111]
	v_mfma_f32_16x16x32_bf16 v[104:107], v[140:143], v[218:221], v[104:107]
	v_mfma_f32_16x16x32_bf16 v[92:95], v[132:135], v[226:229], v[92:95]
	v_mfma_f32_16x16x32_bf16 v[88:91], v[140:143], v[226:229], v[88:91]
	v_mfma_f32_16x16x32_bf16 v[76:79], v[132:135], v[234:237], v[76:79]
	v_mfma_f32_16x16x32_bf16 v[72:75], v[140:143], v[234:237], v[72:75]
	v_mfma_f32_16x16x32_bf16 v[116:119], v[162:165], v[202:205], v[116:119]
	v_mfma_f32_16x16x32_bf16 v[112:115], v[180:183], v[202:205], v[112:115]
	v_mfma_f32_16x16x32_bf16 v[100:103], v[162:165], v[214:217], v[100:103]
	v_mfma_f32_16x16x32_bf16 v[96:99], v[180:183], v[214:217], v[96:99]
	v_mfma_f32_16x16x32_bf16 v[84:87], v[162:165], v[222:225], v[84:87]
	v_mfma_f32_16x16x32_bf16 v[80:83], v[180:183], v[222:225], v[80:83]
	v_mfma_f32_16x16x32_bf16 v[68:71], v[162:165], v[230:233], v[68:71]
	v_mfma_f32_16x16x32_bf16 v[64:67], v[180:183], v[230:233], v[64:67]
	v_mfma_f32_16x16x32_bf16 v[116:119], v[166:169], v[210:213], v[116:119]
	v_mfma_f32_16x16x32_bf16 v[112:115], v[196:199], v[210:213], v[112:115]
	v_mfma_f32_16x16x32_bf16 v[100:103], v[166:169], v[218:221], v[100:103]
	v_mfma_f32_16x16x32_bf16 v[96:99], v[196:199], v[218:221], v[96:99]
	v_mfma_f32_16x16x32_bf16 v[84:87], v[166:169], v[226:229], v[84:87]
	v_mfma_f32_16x16x32_bf16 v[80:83], v[196:199], v[226:229], v[80:83]
	v_mfma_f32_16x16x32_bf16 v[68:71], v[166:169], v[234:237], v[68:71]
	v_mfma_f32_16x16x32_bf16 v[64:67], v[196:199], v[234:237], v[64:67]
	s_barrier
	s_add_i32 s28, s33, s15
	v_lshl_add_u64 v[170:171], v[170:171], 0, s[10:11]
	s_mov_b32 m0, s28
	ds_read_b128 v[202:205], v207 offset:49152
	ds_read_b128 v[210:213], v207 offset:50176
	ds_read_b128 v[214:217], v207 offset:51200
	ds_read_b128 v[218:221], v207 offset:52224
	ds_read_b128 v[222:225], v207 offset:53248
	ds_read_b128 v[226:229], v207 offset:54272
	ds_read_b128 v[230:233], v207 offset:55296
	ds_read_b128 v[234:237], v207 offset:56320
	global_load_lds_dwordx4 v[170:171], off
	s_add_i32 m0, s28, 0x2000
	s_add_u32 s26, s26, 0x80080
	v_lshl_add_u64 v[170:171], v[176:177], 0, s[10:11]
	s_addc_u32 s27, s27, 0
	s_add_i32 s28, s34, s15
	global_load_lds_dwordx4 v[170:171], off
	v_lshl_add_u64 v[170:171], s[26:27], 0, v[148:149]
	s_mov_b32 m0, s28
	s_nop 0
	global_load_lds_dwordx4 v[170:171], off
	v_lshl_add_u64 v[170:171], s[26:27], 0, v[144:145]
	s_add_i32 m0, s28, 0x2000
	s_nop 0
	global_load_lds_dwordx4 v[170:171], off
	v_lshl_add_u64 v[170:171], v[188:189], 0, s[10:11]
	s_mov_b32 m0, s45
	s_nop 0
	global_load_lds_dwordx4 v[170:171], off
	v_lshl_add_u64 v[170:171], v[238:239], 0, s[10:11]
	s_mov_b32 m0, s46
	s_nop 0
	global_load_lds_dwordx4 v[170:171], off
	s_waitcnt vmcnt(8)
	s_waitcnt lgkmcnt(0)
	s_barrier
	s_waitcnt lgkmcnt(0)
	v_mfma_f32_16x16x32_bf16 v[60:63], v[128:131], v[202:205], v[60:63]
	v_mfma_f32_16x16x32_bf16 v[56:59], v[136:139], v[202:205], v[56:59]
	v_mfma_f32_16x16x32_bf16 v[44:47], v[128:131], v[214:217], v[44:47]
	v_mfma_f32_16x16x32_bf16 v[40:43], v[136:139], v[214:217], v[40:43]
	v_mfma_f32_16x16x32_bf16 v[28:31], v[128:131], v[222:225], v[28:31]
	v_mfma_f32_16x16x32_bf16 v[24:27], v[136:139], v[222:225], v[24:27]
	v_mfma_f32_16x16x32_bf16 v[12:15], v[128:131], v[230:233], v[12:15]
	v_mfma_f32_16x16x32_bf16 v[8:11], v[136:139], v[230:233], v[8:11]
	v_mfma_f32_16x16x32_bf16 v[60:63], v[132:135], v[210:213], v[60:63]
	v_mfma_f32_16x16x32_bf16 v[56:59], v[140:143], v[210:213], v[56:59]
	v_mfma_f32_16x16x32_bf16 v[44:47], v[132:135], v[218:221], v[44:47]
	v_mfma_f32_16x16x32_bf16 v[40:43], v[140:143], v[218:221], v[40:43]
	v_mfma_f32_16x16x32_bf16 v[28:31], v[132:135], v[226:229], v[28:31]
	v_mfma_f32_16x16x32_bf16 v[24:27], v[140:143], v[226:229], v[24:27]
	v_mfma_f32_16x16x32_bf16 v[12:15], v[132:135], v[234:237], v[12:15]
	v_mfma_f32_16x16x32_bf16 v[8:11], v[140:143], v[234:237], v[8:11]
	v_mfma_f32_16x16x32_bf16 v[52:55], v[162:165], v[202:205], v[52:55]
	v_mfma_f32_16x16x32_bf16 v[48:51], v[180:183], v[202:205], v[48:51]
	v_mfma_f32_16x16x32_bf16 v[36:39], v[162:165], v[214:217], v[36:39]
	v_mfma_f32_16x16x32_bf16 v[32:35], v[180:183], v[214:217], v[32:35]
	v_mfma_f32_16x16x32_bf16 v[20:23], v[162:165], v[222:225], v[20:23]
	v_mfma_f32_16x16x32_bf16 v[16:19], v[180:183], v[222:225], v[16:19]
	v_mfma_f32_16x16x32_bf16 v[4:7], v[162:165], v[230:233], v[4:7]
	v_mfma_f32_16x16x32_bf16 v[0:3], v[180:183], v[230:233], v[0:3]
	v_mfma_f32_16x16x32_bf16 v[52:55], v[166:169], v[210:213], v[52:55]
	v_mfma_f32_16x16x32_bf16 v[48:51], v[196:199], v[210:213], v[48:51]
	v_mfma_f32_16x16x32_bf16 v[36:39], v[166:169], v[218:221], v[36:39]
	v_mfma_f32_16x16x32_bf16 v[32:35], v[196:199], v[218:221], v[32:35]
	v_mfma_f32_16x16x32_bf16 v[20:23], v[166:169], v[226:229], v[20:23]
	v_mfma_f32_16x16x32_bf16 v[16:19], v[196:199], v[226:229], v[16:19]
	v_mfma_f32_16x16x32_bf16 v[4:7], v[166:169], v[234:237], v[4:7]
	v_mfma_f32_16x16x32_bf16 v[0:3], v[196:199], v[234:237], v[0:3]
	s_barrier
	s_add_i32 s61, s61, 2
	s_add_u32 s0, s0, 0x100
	s_addc_u32 s1, s1, 0
	s_add_u32 s59, s59, 0x100
	s_addc_u32 s60, s60, 0
	s_cmp_gt_u32 s61, 29
	s_cbranch_scc0 .LBB0_2112
	s_and_b64 vcc, exec, s[12:13]
	s_cbranch_vccz .LBB0_2115
	s_barrier

.LBB0_2188:
	ds_read_b128 v[140:143], v185
	ds_read_b128 v[144:147], v185 offset:1024
	ds_read_b128 v[148:151], v185 offset:2048
	ds_read_b128 v[152:155], v185 offset:3072
	ds_read_b128 v[156:159], v186
	ds_read_b128 v[160:163], v186 offset:1024
	ds_read_b128 v[164:167], v186 offset:2048
	ds_read_b128 v[168:171], v186 offset:3072
	s_add_u32 s28, s26, 0xffea0080
	s_addc_u32 s29, s27, -1
	s_cmpk_eq_i32 s64, 0x54
	s_cselect_b32 s31, s21, s29
	s_cselect_b32 s30, s20, s28
	s_cselect_b32 s29, s23, s63
	s_cselect_b32 s28, s22, s62
	s_mov_b32 m0, s53
	v_lshl_add_u64 v[214:215], s[26:27], 0, v[136:137]
	ds_read_b128 v[176:179], v187
	ds_read_b128 v[180:183], v187 offset:1024
	ds_read_b128 v[190:193], v187 offset:2048
	ds_read_b128 v[194:197], v187 offset:3072
	ds_read_b128 v[198:201], v187 offset:4096
	ds_read_b128 v[202:205], v187 offset:5120
	ds_read_b128 v[206:209], v187 offset:6144
	ds_read_b128 v[210:213], v187 offset:7168
	global_load_lds_dwordx4 v[214:215], off
	v_lshl_add_u64 v[214:215], s[26:27], 0, v[138:139]
	s_mov_b32 m0, s54
	s_nop 0
	global_load_lds_dwordx4 v[214:215], off
	s_waitcnt vmcnt(8)
	s_waitcnt lgkmcnt(0)
	s_barrier
	s_waitcnt lgkmcnt(0)
	v_mfma_f32_16x16x32_bf16 v[124:127], v[140:143], v[176:179], v[124:127]
	v_mfma_f32_16x16x32_bf16 v[120:123], v[148:151], v[176:179], v[120:123]
	v_mfma_f32_16x16x32_bf16 v[108:111], v[140:143], v[190:193], v[108:111]
	v_mfma_f32_16x16x32_bf16 v[104:107], v[148:151], v[190:193], v[104:107]
	v_mfma_f32_16x16x32_bf16 v[92:95], v[140:143], v[198:201], v[92:95]
	v_mfma_f32_16x16x32_bf16 v[88:91], v[148:151], v[198:201], v[88:91]
	v_mfma_f32_16x16x32_bf16 v[76:79], v[140:143], v[206:209], v[76:79]
	v_mfma_f32_16x16x32_bf16 v[72:75], v[148:151], v[206:209], v[72:75]
	v_mfma_f32_16x16x32_bf16 v[124:127], v[144:147], v[180:183], v[124:127]
	v_mfma_f32_16x16x32_bf16 v[120:123], v[152:155], v[180:183], v[120:123]
	v_mfma_f32_16x16x32_bf16 v[108:111], v[144:147], v[194:197], v[108:111]
	v_mfma_f32_16x16x32_bf16 v[104:107], v[152:155], v[194:197], v[104:107]
	v_mfma_f32_16x16x32_bf16 v[92:95], v[144:147], v[202:205], v[92:95]
	v_mfma_f32_16x16x32_bf16 v[88:91], v[152:155], v[202:205], v[88:91]
	v_mfma_f32_16x16x32_bf16 v[76:79], v[144:147], v[210:213], v[76:79]
	v_mfma_f32_16x16x32_bf16 v[72:75], v[152:155], v[210:213], v[72:75]
	v_mfma_f32_16x16x32_bf16 v[116:119], v[156:159], v[176:179], v[116:119]
	v_mfma_f32_16x16x32_bf16 v[112:115], v[164:167], v[176:179], v[112:115]
	v_mfma_f32_16x16x32_bf16 v[100:103], v[156:159], v[190:193], v[100:103]
	v_mfma_f32_16x16x32_bf16 v[96:99], v[164:167], v[190:193], v[96:99]
	v_mfma_f32_16x16x32_bf16 v[84:87], v[156:159], v[198:201], v[84:87]
	v_mfma_f32_16x16x32_bf16 v[80:83], v[164:167], v[198:201], v[80:83]
	v_mfma_f32_16x16x32_bf16 v[68:71], v[156:159], v[206:209], v[68:71]
	v_mfma_f32_16x16x32_bf16 v[64:67], v[164:167], v[206:209], v[64:67]
	v_mfma_f32_16x16x32_bf16 v[116:119], v[160:163], v[180:183], v[116:119]
	v_mfma_f32_16x16x32_bf16 v[112:115], v[168:171], v[180:183], v[112:115]
	v_mfma_f32_16x16x32_bf16 v[100:103], v[160:163], v[194:197], v[100:103]
	v_mfma_f32_16x16x32_bf16 v[96:99], v[168:171], v[194:197], v[96:99]
	v_mfma_f32_16x16x32_bf16 v[84:87], v[160:163], v[202:205], v[84:87]
	v_mfma_f32_16x16x32_bf16 v[80:83], v[168:171], v[202:205], v[80:83]
	v_mfma_f32_16x16x32_bf16 v[68:71], v[160:163], v[210:213], v[68:71]
	v_mfma_f32_16x16x32_bf16 v[64:67], v[168:171], v[210:213], v[64:67]
	s_barrier
	s_mov_b32 m0, s55
	v_lshl_add_u64 v[214:215], s[28:29], 0, v[130:131]
	s_add_u32 s66, s28, 0x160000
	ds_read_b128 v[176:179], v187 offset:16384
	ds_read_b128 v[180:183], v187 offset:17408
	ds_read_b128 v[190:193], v187 offset:18432
	ds_read_b128 v[194:197], v187 offset:19456
	ds_read_b128 v[198:201], v187 offset:20480
	ds_read_b128 v[202:205], v187 offset:21504
	ds_read_b128 v[206:209], v187 offset:22528
	ds_read_b128 v[210:213], v187 offset:23552
	global_load_lds_dwordx4 v[214:215], off
	v_lshl_add_u64 v[216:217], s[28:29], 0, v[134:135]
	s_mov_b32 m0, s56
	s_addc_u32 s67, s29, 0
	global_load_lds_dwordx4 v[216:217], off
	v_lshl_add_u64 v[218:219], s[66:67], 0, v[130:131]
	s_mov_b32 m0, s57
	v_lshl_add_u64 v[220:221], s[30:31], 0, v[132:133]
	global_load_lds_dwordx4 v[218:219], off
	v_lshl_add_u64 v[218:219], s[66:67], 0, v[134:135]
	s_mov_b32 m0, s58
	s_nop 0
	global_load_lds_dwordx4 v[218:219], off
	v_lshl_add_u64 v[218:219], s[30:31], 0, v[128:129]
	s_mov_b32 m0, s37
	s_nop 0
	global_load_lds_dwordx4 v[218:219], off
	s_mov_b32 m0, s38
	s_nop 0
	global_load_lds_dwordx4 v[220:221], off
	s_waitcnt vmcnt(8)
	s_waitcnt lgkmcnt(0)
	s_barrier
	s_waitcnt lgkmcnt(0)
	v_mfma_f32_16x16x32_bf16 v[60:63], v[140:143], v[176:179], v[60:63]
	v_mfma_f32_16x16x32_bf16 v[56:59], v[148:151], v[176:179], v[56:59]
	v_mfma_f32_16x16x32_bf16 v[44:47], v[140:143], v[190:193], v[44:47]
	v_mfma_f32_16x16x32_bf16 v[40:43], v[148:151], v[190:193], v[40:43]
	v_mfma_f32_16x16x32_bf16 v[28:31], v[140:143], v[198:201], v[28:31]
	v_mfma_f32_16x16x32_bf16 v[24:27], v[148:151], v[198:201], v[24:27]
	v_mfma_f32_16x16x32_bf16 v[12:15], v[140:143], v[206:209], v[12:15]
	v_mfma_f32_16x16x32_bf16 v[8:11], v[148:151], v[206:209], v[8:11]
	v_mfma_f32_16x16x32_bf16 v[60:63], v[144:147], v[180:183], v[60:63]
	v_mfma_f32_16x16x32_bf16 v[56:59], v[152:155], v[180:183], v[56:59]
	v_mfma_f32_16x16x32_bf16 v[44:47], v[144:147], v[194:197], v[44:47]
	v_mfma_f32_16x16x32_bf16 v[40:43], v[152:155], v[194:197], v[40:43]
	v_mfma_f32_16x16x32_bf16 v[28:31], v[144:147], v[202:205], v[28:31]
	v_mfma_f32_16x16x32_bf16 v[24:27], v[152:155], v[202:205], v[24:27]
	v_mfma_f32_16x16x32_bf16 v[12:15], v[144:147], v[210:213], v[12:15]
	v_mfma_f32_16x16x32_bf16 v[8:11], v[152:155], v[210:213], v[8:11]
	v_mfma_f32_16x16x32_bf16 v[52:55], v[156:159], v[176:179], v[52:55]
	v_mfma_f32_16x16x32_bf16 v[48:51], v[164:167], v[176:179], v[48:51]
	v_mfma_f32_16x16x32_bf16 v[36:39], v[156:159], v[190:193], v[36:39]
	v_mfma_f32_16x16x32_bf16 v[32:35], v[164:167], v[190:193], v[32:35]
	v_mfma_f32_16x16x32_bf16 v[20:23], v[156:159], v[198:201], v[20:23]
	v_mfma_f32_16x16x32_bf16 v[16:19], v[164:167], v[198:201], v[16:19]
	v_mfma_f32_16x16x32_bf16 v[4:7], v[156:159], v[206:209], v[4:7]
	v_mfma_f32_16x16x32_bf16 v[0:3], v[164:167], v[206:209], v[0:3]
	v_mfma_f32_16x16x32_bf16 v[52:55], v[160:163], v[180:183], v[52:55]
	v_mfma_f32_16x16x32_bf16 v[48:51], v[168:171], v[180:183], v[48:51]
	v_mfma_f32_16x16x32_bf16 v[36:39], v[160:163], v[194:197], v[36:39]
	v_mfma_f32_16x16x32_bf16 v[32:35], v[168:171], v[194:197], v[32:35]
	v_mfma_f32_16x16x32_bf16 v[20:23], v[160:163], v[202:205], v[20:23]
	v_mfma_f32_16x16x32_bf16 v[16:19], v[168:171], v[202:205], v[16:19]
	v_mfma_f32_16x16x32_bf16 v[4:7], v[160:163], v[210:213], v[4:7]
	v_mfma_f32_16x16x32_bf16 v[0:3], v[168:171], v[210:213], v[0:3]
	s_barrier
	s_add_i32 s33, 0, 0x18000
	s_add_i32 s34, 0, 0x1c000
	v_add_u32_e32 v152, s33, v184
	v_add_u32_e32 v168, s34, v184
	ds_read_b128 v[140:143], v152
	ds_read_b128 v[144:147], v152 offset:1024
	ds_read_b128 v[148:151], v152 offset:2048
	ds_read_b128 v[152:155], v152 offset:3072
	ds_read_b128 v[156:159], v168
	ds_read_b128 v[160:163], v168 offset:1024
	ds_read_b128 v[164:167], v168 offset:2048
	ds_read_b128 v[168:171], v168 offset:3072
	s_add_u32 s30, s30, 0x160000
	s_addc_u32 s31, s31, 0
	s_mov_b32 m0, s39
	v_lshl_add_u64 v[222:223], s[30:31], 0, v[128:129]
	ds_read_b128 v[176:179], v187 offset:32768
	ds_read_b128 v[180:183], v187 offset:33792
	ds_read_b128 v[190:193], v187 offset:34816
	ds_read_b128 v[194:197], v187 offset:35840
	ds_read_b128 v[198:201], v187 offset:36864
	ds_read_b128 v[202:205], v187 offset:37888
	ds_read_b128 v[206:209], v187 offset:38912
	ds_read_b128 v[210:213], v187 offset:39936
	global_load_lds_dwordx4 v[222:223], off
	v_lshl_add_u64 v[222:223], s[30:31], 0, v[132:133]
	s_mov_b32 m0, s42
	s_nop 0
	global_load_lds_dwordx4 v[222:223], off
	s_waitcnt vmcnt(8)
	s_waitcnt lgkmcnt(0)
	s_barrier
	s_waitcnt lgkmcnt(0)
	v_mfma_f32_16x16x32_bf16 v[124:127], v[140:143], v[176:179], v[124:127]
	v_mfma_f32_16x16x32_bf16 v[120:123], v[148:151], v[176:179], v[120:123]
	v_mfma_f32_16x16x32_bf16 v[108:111], v[140:143], v[190:193], v[108:111]
	v_mfma_f32_16x16x32_bf16 v[104:107], v[148:151], v[190:193], v[104:107]
	v_mfma_f32_16x16x32_bf16 v[92:95], v[140:143], v[198:201], v[92:95]
	v_mfma_f32_16x16x32_bf16 v[88:91], v[148:151], v[198:201], v[88:91]
	v_mfma_f32_16x16x32_bf16 v[76:79], v[140:143], v[206:209], v[76:79]
	v_mfma_f32_16x16x32_bf16 v[72:75], v[148:151], v[206:209], v[72:75]
	v_mfma_f32_16x16x32_bf16 v[124:127], v[144:147], v[180:183], v[124:127]
	v_mfma_f32_16x16x32_bf16 v[120:123], v[152:155], v[180:183], v[120:123]
	v_mfma_f32_16x16x32_bf16 v[108:111], v[144:147], v[194:197], v[108:111]
	v_mfma_f32_16x16x32_bf16 v[104:107], v[152:155], v[194:197], v[104:107]
	v_mfma_f32_16x16x32_bf16 v[92:95], v[144:147], v[202:205], v[92:95]
	v_mfma_f32_16x16x32_bf16 v[88:91], v[152:155], v[202:205], v[88:91]
	v_mfma_f32_16x16x32_bf16 v[76:79], v[144:147], v[210:213], v[76:79]
	v_mfma_f32_16x16x32_bf16 v[72:75], v[152:155], v[210:213], v[72:75]
	v_mfma_f32_16x16x32_bf16 v[116:119], v[156:159], v[176:179], v[116:119]
	v_mfma_f32_16x16x32_bf16 v[112:115], v[164:167], v[176:179], v[112:115]
	v_mfma_f32_16x16x32_bf16 v[100:103], v[156:159], v[190:193], v[100:103]
	v_mfma_f32_16x16x32_bf16 v[96:99], v[164:167], v[190:193], v[96:99]
	v_mfma_f32_16x16x32_bf16 v[84:87], v[156:159], v[198:201], v[84:87]
	v_mfma_f32_16x16x32_bf16 v[80:83], v[164:167], v[198:201], v[80:83]
	v_mfma_f32_16x16x32_bf16 v[68:71], v[156:159], v[206:209], v[68:71]
	v_mfma_f32_16x16x32_bf16 v[64:67], v[164:167], v[206:209], v[64:67]
	v_mfma_f32_16x16x32_bf16 v[116:119], v[160:163], v[180:183], v[116:119]
	v_mfma_f32_16x16x32_bf16 v[112:115], v[168:171], v[180:183], v[112:115]
	v_mfma_f32_16x16x32_bf16 v[100:103], v[160:163], v[194:197], v[100:103]
	v_mfma_f32_16x16x32_bf16 v[96:99], v[168:171], v[194:197], v[96:99]
	v_mfma_f32_16x16x32_bf16 v[84:87], v[160:163], v[202:205], v[84:87]
	v_mfma_f32_16x16x32_bf16 v[80:83], v[168:171], v[202:205], v[80:83]
	v_mfma_f32_16x16x32_bf16 v[68:71], v[160:163], v[210:213], v[68:71]
	v_mfma_f32_16x16x32_bf16 v[64:67], v[168:171], v[210:213], v[64:67]
	s_barrier
	s_add_i32 s30, s33, s36
	v_lshl_add_u64 v[214:215], v[214:215], 0, s[10:11]
	s_mov_b32 m0, s30
	ds_read_b128 v[176:179], v187 offset:49152
	ds_read_b128 v[180:183], v187 offset:50176
	ds_read_b128 v[190:193], v187 offset:51200
	ds_read_b128 v[194:197], v187 offset:52224
	ds_read_b128 v[198:201], v187 offset:53248
	ds_read_b128 v[202:205], v187 offset:54272
	ds_read_b128 v[206:209], v187 offset:55296
	ds_read_b128 v[210:213], v187 offset:56320
	global_load_lds_dwordx4 v[214:215], off
	s_add_i32 m0, s30, 0x2000
	s_add_u32 s28, s28, 0x160080
	v_lshl_add_u64 v[214:215], v[216:217], 0, s[10:11]
	s_addc_u32 s29, s29, 0
	s_add_i32 s30, s34, s36
	global_load_lds_dwordx4 v[214:215], off
	v_lshl_add_u64 v[214:215], s[28:29], 0, v[130:131]
	s_mov_b32 m0, s30
	s_nop 0
	global_load_lds_dwordx4 v[214:215], off
	v_lshl_add_u64 v[214:215], s[28:29], 0, v[134:135]
	s_add_i32 m0, s30, 0x2000
	s_nop 0
	global_load_lds_dwordx4 v[214:215], off
	v_lshl_add_u64 v[214:215], v[218:219], 0, s[10:11]
	s_mov_b32 m0, s49
	s_nop 0
	global_load_lds_dwordx4 v[214:215], off
	v_lshl_add_u64 v[214:215], v[220:221], 0, s[10:11]
	s_mov_b32 m0, s50
	s_nop 0
	global_load_lds_dwordx4 v[214:215], off
	s_waitcnt vmcnt(8)
	s_waitcnt lgkmcnt(0)
	s_barrier
	s_waitcnt lgkmcnt(0)
	v_mfma_f32_16x16x32_bf16 v[60:63], v[140:143], v[176:179], v[60:63]
	v_mfma_f32_16x16x32_bf16 v[56:59], v[148:151], v[176:179], v[56:59]
	v_mfma_f32_16x16x32_bf16 v[44:47], v[140:143], v[190:193], v[44:47]
	v_mfma_f32_16x16x32_bf16 v[40:43], v[148:151], v[190:193], v[40:43]
	v_mfma_f32_16x16x32_bf16 v[28:31], v[140:143], v[198:201], v[28:31]
	v_mfma_f32_16x16x32_bf16 v[24:27], v[148:151], v[198:201], v[24:27]
	v_mfma_f32_16x16x32_bf16 v[12:15], v[140:143], v[206:209], v[12:15]
	v_mfma_f32_16x16x32_bf16 v[8:11], v[148:151], v[206:209], v[8:11]
	v_mfma_f32_16x16x32_bf16 v[60:63], v[144:147], v[180:183], v[60:63]
	v_mfma_f32_16x16x32_bf16 v[56:59], v[152:155], v[180:183], v[56:59]
	v_mfma_f32_16x16x32_bf16 v[44:47], v[144:147], v[194:197], v[44:47]
	v_mfma_f32_16x16x32_bf16 v[40:43], v[152:155], v[194:197], v[40:43]
	v_mfma_f32_16x16x32_bf16 v[28:31], v[144:147], v[202:205], v[28:31]
	v_mfma_f32_16x16x32_bf16 v[24:27], v[152:155], v[202:205], v[24:27]
	v_mfma_f32_16x16x32_bf16 v[12:15], v[144:147], v[210:213], v[12:15]
	v_mfma_f32_16x16x32_bf16 v[8:11], v[152:155], v[210:213], v[8:11]
	v_mfma_f32_16x16x32_bf16 v[52:55], v[156:159], v[176:179], v[52:55]
	v_mfma_f32_16x16x32_bf16 v[48:51], v[164:167], v[176:179], v[48:51]
	v_mfma_f32_16x16x32_bf16 v[36:39], v[156:159], v[190:193], v[36:39]
	v_mfma_f32_16x16x32_bf16 v[32:35], v[164:167], v[190:193], v[32:35]
	v_mfma_f32_16x16x32_bf16 v[20:23], v[156:159], v[198:201], v[20:23]
	v_mfma_f32_16x16x32_bf16 v[16:19], v[164:167], v[198:201], v[16:19]
	v_mfma_f32_16x16x32_bf16 v[4:7], v[156:159], v[206:209], v[4:7]
	v_mfma_f32_16x16x32_bf16 v[0:3], v[164:167], v[206:209], v[0:3]
	v_mfma_f32_16x16x32_bf16 v[52:55], v[160:163], v[180:183], v[52:55]
	v_mfma_f32_16x16x32_bf16 v[48:51], v[168:171], v[180:183], v[48:51]
	v_mfma_f32_16x16x32_bf16 v[36:39], v[160:163], v[194:197], v[36:39]
	v_mfma_f32_16x16x32_bf16 v[32:35], v[168:171], v[194:197], v[32:35]
	v_mfma_f32_16x16x32_bf16 v[20:23], v[160:163], v[202:205], v[20:23]
	v_mfma_f32_16x16x32_bf16 v[16:19], v[168:171], v[202:205], v[16:19]
	v_mfma_f32_16x16x32_bf16 v[4:7], v[160:163], v[210:213], v[4:7]
	v_mfma_f32_16x16x32_bf16 v[0:3], v[168:171], v[210:213], v[0:3]
	s_barrier
	s_add_i32 s64, s64, 2
	s_add_u32 s26, s26, 0x100
	s_addc_u32 s27, s27, 0
	s_add_u32 s62, s62, 0x100
	s_addc_u32 s63, s63, 0
	s_cmpk_gt_u32 s64, 0x55
	s_cbranch_scc0 .LBB0_2188
	s_and_b64 vcc, exec, s[12:13]
	s_cbranch_vccz .LBB0_2191
	s_barrier

.LBB0_2240:
	ds_read_b128 v[144:147], v167
	ds_read_b128 v[148:151], v167 offset:1024
	ds_read_b128 v[152:155], v167 offset:2048
	ds_read_b128 v[156:159], v167 offset:3072
	ds_read_b128 v[160:163], v168
	ds_read_b128 v[176:179], v168 offset:1024
	ds_read_b128 v[180:183], v168 offset:2048
	ds_read_b128 v[184:187], v168 offset:3072
	s_add_u32 s22, s20, 0xffea0080
	s_addc_u32 s23, s21, -1
	s_cmpk_eq_i32 s54, 0x54
	s_cselect_b32 s25, s3, s23
	s_cselect_b32 s24, s2, s22
	s_cselect_b32 s23, s19, s53
	s_cselect_b32 s22, s18, s52
	v_lshl_add_u64 v[220:221], s[20:21], 0, v[136:137]
	s_add_i32 m0, s27, 0xc000
	ds_read_b128 v[188:191], v169
	ds_read_b128 v[192:195], v169 offset:1024
	ds_read_b128 v[196:199], v169 offset:2048
	ds_read_b128 v[200:203], v169 offset:3072
	ds_read_b128 v[204:207], v169 offset:4096
	ds_read_b128 v[208:211], v169 offset:5120
	ds_read_b128 v[212:215], v169 offset:6144
	ds_read_b128 v[216:219], v169 offset:7168
	global_load_lds_dwordx4 v[220:221], off
	v_lshl_add_u64 v[220:221], s[20:21], 0, v[138:139]
	s_add_i32 m0, s27, 0xe000
	s_nop 0
	global_load_lds_dwordx4 v[220:221], off
	s_waitcnt vmcnt(8)
	s_waitcnt lgkmcnt(0)
	s_barrier
	s_waitcnt lgkmcnt(0)
	v_mfma_f32_16x16x32_bf16 v[124:127], v[144:147], v[188:191], v[124:127]
	v_mfma_f32_16x16x32_bf16 v[120:123], v[152:155], v[188:191], v[120:123]
	v_mfma_f32_16x16x32_bf16 v[108:111], v[144:147], v[196:199], v[108:111]
	v_mfma_f32_16x16x32_bf16 v[104:107], v[152:155], v[196:199], v[104:107]
	v_mfma_f32_16x16x32_bf16 v[92:95], v[144:147], v[204:207], v[92:95]
	v_mfma_f32_16x16x32_bf16 v[88:91], v[152:155], v[204:207], v[88:91]
	v_mfma_f32_16x16x32_bf16 v[76:79], v[144:147], v[212:215], v[76:79]
	v_mfma_f32_16x16x32_bf16 v[72:75], v[152:155], v[212:215], v[72:75]
	v_mfma_f32_16x16x32_bf16 v[124:127], v[148:151], v[192:195], v[124:127]
	v_mfma_f32_16x16x32_bf16 v[120:123], v[156:159], v[192:195], v[120:123]
	v_mfma_f32_16x16x32_bf16 v[108:111], v[148:151], v[200:203], v[108:111]
	v_mfma_f32_16x16x32_bf16 v[104:107], v[156:159], v[200:203], v[104:107]
	v_mfma_f32_16x16x32_bf16 v[92:95], v[148:151], v[208:211], v[92:95]
	v_mfma_f32_16x16x32_bf16 v[88:91], v[156:159], v[208:211], v[88:91]
	v_mfma_f32_16x16x32_bf16 v[76:79], v[148:151], v[216:219], v[76:79]
	v_mfma_f32_16x16x32_bf16 v[72:75], v[156:159], v[216:219], v[72:75]
	v_mfma_f32_16x16x32_bf16 v[116:119], v[160:163], v[188:191], v[116:119]
	v_mfma_f32_16x16x32_bf16 v[112:115], v[180:183], v[188:191], v[112:115]
	v_mfma_f32_16x16x32_bf16 v[100:103], v[160:163], v[196:199], v[100:103]
	v_mfma_f32_16x16x32_bf16 v[96:99], v[180:183], v[196:199], v[96:99]
	v_mfma_f32_16x16x32_bf16 v[84:87], v[160:163], v[204:207], v[84:87]
	v_mfma_f32_16x16x32_bf16 v[80:83], v[180:183], v[204:207], v[80:83]
	v_mfma_f32_16x16x32_bf16 v[68:71], v[160:163], v[212:215], v[68:71]
	v_mfma_f32_16x16x32_bf16 v[64:67], v[180:183], v[212:215], v[64:67]
	v_mfma_f32_16x16x32_bf16 v[116:119], v[176:179], v[192:195], v[116:119]
	v_mfma_f32_16x16x32_bf16 v[112:115], v[184:187], v[192:195], v[112:115]
	v_mfma_f32_16x16x32_bf16 v[100:103], v[176:179], v[200:203], v[100:103]
	v_mfma_f32_16x16x32_bf16 v[96:99], v[184:187], v[200:203], v[96:99]
	v_mfma_f32_16x16x32_bf16 v[84:87], v[176:179], v[208:211], v[84:87]
	v_mfma_f32_16x16x32_bf16 v[80:83], v[184:187], v[208:211], v[80:83]
	v_mfma_f32_16x16x32_bf16 v[68:71], v[176:179], v[216:219], v[68:71]
	v_mfma_f32_16x16x32_bf16 v[64:67], v[184:187], v[216:219], v[64:67]
	s_barrier
	s_add_i32 s33, s46, s26
	v_lshl_add_u64 v[220:221], s[22:23], 0, v[130:131]
	s_mov_b32 m0, s33
	ds_read_b128 v[188:191], v169 offset:16384
	ds_read_b128 v[192:195], v169 offset:17408
	ds_read_b128 v[196:199], v169 offset:18432
	ds_read_b128 v[200:203], v169 offset:19456
	ds_read_b128 v[204:207], v169 offset:20480
	ds_read_b128 v[208:211], v169 offset:21504
	ds_read_b128 v[212:215], v169 offset:22528
	ds_read_b128 v[216:219], v169 offset:23552
	global_load_lds_dwordx4 v[220:221], off
	s_add_i32 m0, s33, 0x2000
	s_add_u32 s56, s22, 0x160000
	v_lshl_add_u64 v[222:223], s[22:23], 0, v[134:135]
	s_addc_u32 s57, s23, 0
	s_add_i32 s33, s47, s26
	global_load_lds_dwordx4 v[222:223], off
	v_lshl_add_u64 v[224:225], s[56:57], 0, v[130:131]
	s_mov_b32 m0, s33
	v_lshl_add_u64 v[226:227], s[24:25], 0, v[132:133]
	global_load_lds_dwordx4 v[224:225], off
	v_lshl_add_u64 v[224:225], s[56:57], 0, v[134:135]
	s_add_i32 m0, s33, 0x2000
	s_nop 0
	global_load_lds_dwordx4 v[224:225], off
	v_lshl_add_u64 v[224:225], s[24:25], 0, v[128:129]
	s_mov_b32 m0, s27
	s_nop 0
	global_load_lds_dwordx4 v[224:225], off
	s_mov_b32 m0, s28
	s_nop 0
	global_load_lds_dwordx4 v[226:227], off
	s_waitcnt vmcnt(8)
	s_waitcnt lgkmcnt(0)
	s_barrier
	s_waitcnt lgkmcnt(0)
	v_mfma_f32_16x16x32_bf16 v[60:63], v[144:147], v[188:191], v[60:63]
	v_mfma_f32_16x16x32_bf16 v[56:59], v[152:155], v[188:191], v[56:59]
	v_mfma_f32_16x16x32_bf16 v[44:47], v[144:147], v[196:199], v[44:47]
	v_mfma_f32_16x16x32_bf16 v[40:43], v[152:155], v[196:199], v[40:43]
	v_mfma_f32_16x16x32_bf16 v[28:31], v[144:147], v[204:207], v[28:31]
	v_mfma_f32_16x16x32_bf16 v[24:27], v[152:155], v[204:207], v[24:27]
	v_mfma_f32_16x16x32_bf16 v[12:15], v[144:147], v[212:215], v[12:15]
	v_mfma_f32_16x16x32_bf16 v[8:11], v[152:155], v[212:215], v[8:11]
	v_mfma_f32_16x16x32_bf16 v[60:63], v[148:151], v[192:195], v[60:63]
	v_mfma_f32_16x16x32_bf16 v[56:59], v[156:159], v[192:195], v[56:59]
	v_mfma_f32_16x16x32_bf16 v[44:47], v[148:151], v[200:203], v[44:47]
	v_mfma_f32_16x16x32_bf16 v[40:43], v[156:159], v[200:203], v[40:43]
	v_mfma_f32_16x16x32_bf16 v[28:31], v[148:151], v[208:211], v[28:31]
	v_mfma_f32_16x16x32_bf16 v[24:27], v[156:159], v[208:211], v[24:27]
	v_mfma_f32_16x16x32_bf16 v[12:15], v[148:151], v[216:219], v[12:15]
	v_mfma_f32_16x16x32_bf16 v[8:11], v[156:159], v[216:219], v[8:11]
	v_mfma_f32_16x16x32_bf16 v[52:55], v[160:163], v[188:191], v[52:55]
	v_mfma_f32_16x16x32_bf16 v[48:51], v[180:183], v[188:191], v[48:51]
	v_mfma_f32_16x16x32_bf16 v[36:39], v[160:163], v[196:199], v[36:39]
	v_mfma_f32_16x16x32_bf16 v[32:35], v[180:183], v[196:199], v[32:35]
	v_mfma_f32_16x16x32_bf16 v[20:23], v[160:163], v[204:207], v[20:23]
	v_mfma_f32_16x16x32_bf16 v[16:19], v[180:183], v[204:207], v[16:19]
	v_mfma_f32_16x16x32_bf16 v[4:7], v[160:163], v[212:215], v[4:7]
	v_mfma_f32_16x16x32_bf16 v[0:3], v[180:183], v[212:215], v[0:3]
	v_mfma_f32_16x16x32_bf16 v[52:55], v[176:179], v[192:195], v[52:55]
	v_mfma_f32_16x16x32_bf16 v[48:51], v[184:187], v[192:195], v[48:51]
	v_mfma_f32_16x16x32_bf16 v[36:39], v[176:179], v[200:203], v[36:39]
	v_mfma_f32_16x16x32_bf16 v[32:35], v[184:187], v[200:203], v[32:35]
	v_mfma_f32_16x16x32_bf16 v[20:23], v[176:179], v[208:211], v[20:23]
	v_mfma_f32_16x16x32_bf16 v[16:19], v[184:187], v[208:211], v[16:19]
	v_mfma_f32_16x16x32_bf16 v[4:7], v[176:179], v[216:219], v[4:7]
	v_mfma_f32_16x16x32_bf16 v[0:3], v[184:187], v[216:219], v[0:3]
	s_barrier
	s_add_i32 s33, 0, 0x18000
	s_add_i32 s34, 0, 0x1c000
	v_add_u32_e32 v156, s33, v166
	v_add_u32_e32 v171, s34, v166
	ds_read_b128 v[144:147], v156
	ds_read_b128 v[148:151], v156 offset:1024
	ds_read_b128 v[152:155], v156 offset:2048
	ds_read_b128 v[156:159], v156 offset:3072
	ds_read_b128 v[160:163], v171
	ds_read_b128 v[176:179], v171 offset:1024
	ds_read_b128 v[180:183], v171 offset:2048
	ds_read_b128 v[184:187], v171 offset:3072
	s_add_u32 s24, s24, 0x160000
	s_addc_u32 s25, s25, 0
	s_mov_b32 m0, s29
	v_lshl_add_u64 v[228:229], s[24:25], 0, v[128:129]
	ds_read_b128 v[188:191], v169 offset:32768
	ds_read_b128 v[192:195], v169 offset:33792
	ds_read_b128 v[196:199], v169 offset:34816
	ds_read_b128 v[200:203], v169 offset:35840
	ds_read_b128 v[204:207], v169 offset:36864
	ds_read_b128 v[208:211], v169 offset:37888
	ds_read_b128 v[212:215], v169 offset:38912
	ds_read_b128 v[216:219], v169 offset:39936
	global_load_lds_dwordx4 v[228:229], off
	v_lshl_add_u64 v[228:229], s[24:25], 0, v[132:133]
	s_mov_b32 m0, s30
	s_nop 0
	global_load_lds_dwordx4 v[228:229], off
	s_waitcnt vmcnt(8)
	s_waitcnt lgkmcnt(0)
	s_barrier
	s_waitcnt lgkmcnt(0)
	v_mfma_f32_16x16x32_bf16 v[124:127], v[144:147], v[188:191], v[124:127]
	v_mfma_f32_16x16x32_bf16 v[120:123], v[152:155], v[188:191], v[120:123]
	v_mfma_f32_16x16x32_bf16 v[108:111], v[144:147], v[196:199], v[108:111]
	v_mfma_f32_16x16x32_bf16 v[104:107], v[152:155], v[196:199], v[104:107]
	v_mfma_f32_16x16x32_bf16 v[92:95], v[144:147], v[204:207], v[92:95]
	v_mfma_f32_16x16x32_bf16 v[88:91], v[152:155], v[204:207], v[88:91]
	v_mfma_f32_16x16x32_bf16 v[76:79], v[144:147], v[212:215], v[76:79]
	v_mfma_f32_16x16x32_bf16 v[72:75], v[152:155], v[212:215], v[72:75]
	v_mfma_f32_16x16x32_bf16 v[124:127], v[148:151], v[192:195], v[124:127]
	v_mfma_f32_16x16x32_bf16 v[120:123], v[156:159], v[192:195], v[120:123]
	v_mfma_f32_16x16x32_bf16 v[108:111], v[148:151], v[200:203], v[108:111]
	v_mfma_f32_16x16x32_bf16 v[104:107], v[156:159], v[200:203], v[104:107]
	v_mfma_f32_16x16x32_bf16 v[92:95], v[148:151], v[208:211], v[92:95]
	v_mfma_f32_16x16x32_bf16 v[88:91], v[156:159], v[208:211], v[88:91]
	v_mfma_f32_16x16x32_bf16 v[76:79], v[148:151], v[216:219], v[76:79]
	v_mfma_f32_16x16x32_bf16 v[72:75], v[156:159], v[216:219], v[72:75]
	v_mfma_f32_16x16x32_bf16 v[116:119], v[160:163], v[188:191], v[116:119]
	v_mfma_f32_16x16x32_bf16 v[112:115], v[180:183], v[188:191], v[112:115]
	v_mfma_f32_16x16x32_bf16 v[100:103], v[160:163], v[196:199], v[100:103]
	v_mfma_f32_16x16x32_bf16 v[96:99], v[180:183], v[196:199], v[96:99]
	v_mfma_f32_16x16x32_bf16 v[84:87], v[160:163], v[204:207], v[84:87]
	v_mfma_f32_16x16x32_bf16 v[80:83], v[180:183], v[204:207], v[80:83]
	v_mfma_f32_16x16x32_bf16 v[68:71], v[160:163], v[212:215], v[68:71]
	v_mfma_f32_16x16x32_bf16 v[64:67], v[180:183], v[212:215], v[64:67]
	v_mfma_f32_16x16x32_bf16 v[116:119], v[176:179], v[192:195], v[116:119]
	v_mfma_f32_16x16x32_bf16 v[112:115], v[184:187], v[192:195], v[112:115]
	v_mfma_f32_16x16x32_bf16 v[100:103], v[176:179], v[200:203], v[100:103]
	v_mfma_f32_16x16x32_bf16 v[96:99], v[184:187], v[200:203], v[96:99]
	v_mfma_f32_16x16x32_bf16 v[84:87], v[176:179], v[208:211], v[84:87]
	v_mfma_f32_16x16x32_bf16 v[80:83], v[184:187], v[208:211], v[80:83]
	v_mfma_f32_16x16x32_bf16 v[68:71], v[176:179], v[216:219], v[68:71]
	v_mfma_f32_16x16x32_bf16 v[64:67], v[184:187], v[216:219], v[64:67]
	s_barrier
	s_add_i32 s24, s33, s26
	v_lshl_add_u64 v[220:221], v[220:221], 0, s[10:11]
	s_mov_b32 m0, s24
	ds_read_b128 v[188:191], v169 offset:49152
	ds_read_b128 v[192:195], v169 offset:50176
	ds_read_b128 v[196:199], v169 offset:51200
	ds_read_b128 v[200:203], v169 offset:52224
	ds_read_b128 v[204:207], v169 offset:53248
	ds_read_b128 v[208:211], v169 offset:54272
	ds_read_b128 v[212:215], v169 offset:55296
	ds_read_b128 v[216:219], v169 offset:56320
	global_load_lds_dwordx4 v[220:221], off
	s_add_i32 m0, s24, 0x2000
	s_add_u32 s22, s22, 0x160080
	v_lshl_add_u64 v[220:221], v[222:223], 0, s[10:11]
	s_addc_u32 s23, s23, 0
	s_add_i32 s24, s34, s26
	global_load_lds_dwordx4 v[220:221], off
	v_lshl_add_u64 v[220:221], s[22:23], 0, v[130:131]
	s_mov_b32 m0, s24
	s_nop 0
	global_load_lds_dwordx4 v[220:221], off
	v_lshl_add_u64 v[220:221], s[22:23], 0, v[134:135]
	s_add_i32 m0, s24, 0x2000
	s_nop 0
	global_load_lds_dwordx4 v[220:221], off
	v_lshl_add_u64 v[220:221], v[224:225], 0, s[10:11]
	s_mov_b32 m0, s38
	s_nop 0
	global_load_lds_dwordx4 v[220:221], off
	v_lshl_add_u64 v[220:221], v[226:227], 0, s[10:11]
	s_mov_b32 m0, s39
	s_nop 0
	global_load_lds_dwordx4 v[220:221], off
	s_waitcnt vmcnt(8)
	s_waitcnt lgkmcnt(0)
	s_barrier
	s_waitcnt lgkmcnt(0)
	v_mfma_f32_16x16x32_bf16 v[60:63], v[144:147], v[188:191], v[60:63]
	v_mfma_f32_16x16x32_bf16 v[56:59], v[152:155], v[188:191], v[56:59]
	v_mfma_f32_16x16x32_bf16 v[44:47], v[144:147], v[196:199], v[44:47]
	v_mfma_f32_16x16x32_bf16 v[40:43], v[152:155], v[196:199], v[40:43]
	v_mfma_f32_16x16x32_bf16 v[28:31], v[144:147], v[204:207], v[28:31]
	v_mfma_f32_16x16x32_bf16 v[24:27], v[152:155], v[204:207], v[24:27]
	v_mfma_f32_16x16x32_bf16 v[12:15], v[144:147], v[212:215], v[12:15]
	v_mfma_f32_16x16x32_bf16 v[8:11], v[152:155], v[212:215], v[8:11]
	v_mfma_f32_16x16x32_bf16 v[60:63], v[148:151], v[192:195], v[60:63]
	v_mfma_f32_16x16x32_bf16 v[56:59], v[156:159], v[192:195], v[56:59]
	v_mfma_f32_16x16x32_bf16 v[44:47], v[148:151], v[200:203], v[44:47]
	v_mfma_f32_16x16x32_bf16 v[40:43], v[156:159], v[200:203], v[40:43]
	v_mfma_f32_16x16x32_bf16 v[28:31], v[148:151], v[208:211], v[28:31]
	v_mfma_f32_16x16x32_bf16 v[24:27], v[156:159], v[208:211], v[24:27]
	v_mfma_f32_16x16x32_bf16 v[12:15], v[148:151], v[216:219], v[12:15]
	v_mfma_f32_16x16x32_bf16 v[8:11], v[156:159], v[216:219], v[8:11]
	v_mfma_f32_16x16x32_bf16 v[52:55], v[160:163], v[188:191], v[52:55]
	v_mfma_f32_16x16x32_bf16 v[48:51], v[180:183], v[188:191], v[48:51]
	v_mfma_f32_16x16x32_bf16 v[36:39], v[160:163], v[196:199], v[36:39]
	v_mfma_f32_16x16x32_bf16 v[32:35], v[180:183], v[196:199], v[32:35]
	v_mfma_f32_16x16x32_bf16 v[20:23], v[160:163], v[204:207], v[20:23]
	v_mfma_f32_16x16x32_bf16 v[16:19], v[180:183], v[204:207], v[16:19]
	v_mfma_f32_16x16x32_bf16 v[4:7], v[160:163], v[212:215], v[4:7]
	v_mfma_f32_16x16x32_bf16 v[0:3], v[180:183], v[212:215], v[0:3]
	v_mfma_f32_16x16x32_bf16 v[52:55], v[176:179], v[192:195], v[52:55]
	v_mfma_f32_16x16x32_bf16 v[48:51], v[184:187], v[192:195], v[48:51]
	v_mfma_f32_16x16x32_bf16 v[36:39], v[176:179], v[200:203], v[36:39]
	v_mfma_f32_16x16x32_bf16 v[32:35], v[184:187], v[200:203], v[32:35]
	v_mfma_f32_16x16x32_bf16 v[20:23], v[176:179], v[208:211], v[20:23]
	v_mfma_f32_16x16x32_bf16 v[16:19], v[184:187], v[208:211], v[16:19]
	v_mfma_f32_16x16x32_bf16 v[4:7], v[176:179], v[216:219], v[4:7]
	v_mfma_f32_16x16x32_bf16 v[0:3], v[184:187], v[216:219], v[0:3]
	s_barrier
	s_add_i32 s54, s54, 2
	s_add_u32 s20, s20, 0x100
	s_addc_u32 s21, s21, 0
	s_add_u32 s52, s52, 0x100
	s_addc_u32 s53, s53, 0
	s_cmpk_gt_u32 s54, 0x55
	s_cbranch_scc0 .LBB0_2240
	s_and_b64 vcc, exec, s[12:13]
	s_cbranch_vccz .LBB0_2243
	s_barrier
